# lever 4: per-segment s_setprio flips in the 12 GEMM loops removed, one static s_setprio 1 for waves 4-7 at kernel start
# baseline (speedup 1.0000x reference)
.LBB0_29:
	s_lshr_b32 s94, s93, 6
	s_cmp_lt_u32 s94, 4
	s_cbranch_scc1 .Lprio_skip
	s_setprio 1
.Lprio_skip:
	s_lshl_b32 s0, s24, 3
	s_add_i32 s8, s0, s94
	s_lshl_b32 s3, s56, 3
	s_lshl_b32 s66, s56, 9
	s_add_u32 s6, s54, 0x500000
	s_addc_u32 s7, s55, 0
	s_add_u32 s64, s54, 0x900000
	s_addc_u32 s65, s55, 0
	s_add_u32 s60, s54, 0xb00000
	s_addc_u32 s61, s55, 0
	s_add_u32 s50, s54, 0x1300000
	s_addc_u32 s51, s55, 0
	s_cmp_lt_i32 s40, 1
	v_writelane_b32 v246, s24, 6
	s_cselect_b64 s[4:5], -1, 0
	s_cmp_gt_i32 s40, 0
	v_writelane_b32 v246, s0, 7
	s_cselect_b64 s[0:1], -1, 0
	s_cmp_lt_i32 s41, 1
	s_cselect_b64 s[10:11], -1, 0
	s_or_b64 s[0:1], s[10:11], s[0:1]
	s_and_b64 vcc, exec, s[0:1]
	s_cbranch_vccnz .LBB0_71
	v_mov_b32_e32 v1, 0
	v_mbcnt_lo_u32_b32 v163, -1, 0
	v_mbcnt_hi_u32_b32 v163, -1, v163
	s_cmpk_gt_i32 s8, 0x14ff
	s_waitcnt vmcnt(3)
	v_readlane_b32 s13, v247, 29
	v_readlane_b32 s12, v247, 28
	s_waitcnt vmcnt(2)
	v_readlane_b32 s11, v247, 37
	v_readlane_b32 s10, v247, 36
	s_waitcnt vmcnt(1)
	v_readlane_b32 s15, v247, 25
	v_readlane_b32 s14, v247, 24
	s_waitcnt vmcnt(0)
	v_readlane_b32 s17, v247, 27
	v_readlane_b32 s16, v247, 26
	v_lshrrev_b32_e32 v3, 3, v163
	v_and_b32_e32 v2, 7, v163
	v_lshlrev_b32_e32 v4, 4, v2
	s_lshl_b32 s18, s94, 14
	v_mul_u32_u24_e32 v5, 33, v3
	v_lshl_add_u32 v5, v2, 2, v5
	v_lshl_add_u32 v5, v5, 2, s18
	v_mul_u32_u24_e32 v6, 0x108, v2
	v_add_u32_e32 v6, v6, v3
	v_lshl_add_u32 v6, v6, 2, s18
	s_lshr_b32 s18, s8, 3
	s_cmp_lg_u32 s56, 0x100
	s_cbranch_scc1 .Ltr_generic
	s_cmp_lt_u32 s18, 0xc0
	s_cbranch_scc0 .Ltr_free
	s_mul_i32 s0, s18, 13
	s_add_i32 s9, s0, 13
	s_branch .Ltr_dealt

.LBB0_193:
	ds_read_b128 v[152:155], v149
	ds_read_b128 v[156:159], v149 offset:1024
	ds_read_b128 v[160:163], v149 offset:2048
	ds_read_b128 v[164:167], v149 offset:3072
	ds_read_b128 v[168:171], v150
	ds_read_b128 v[172:175], v150 offset:1024
	ds_read_b128 v[176:179], v150 offset:2048
	ds_read_b128 v[180:183], v150 offset:3072
	s_add_u32 s38, s36, 0xfffc0080
	s_addc_u32 s39, s37, -1
	s_cmp_eq_u32 s82, 12
	s_cselect_b32 s49, s27, s39
	s_cselect_b32 s48, s78, s38
	s_cselect_b32 s39, s23, s81
	s_cselect_b32 s38, s79, s80
	v_lshl_add_u64 v[144:145], s[36:37], 0, v[136:137]
	s_add_i32 m0, s25, 0xc000
	ds_read_b128 v[184:187], v151
	ds_read_b128 v[188:191], v151 offset:1024
	ds_read_b128 v[192:195], v151 offset:2048
	ds_read_b128 v[196:199], v151 offset:3072
	ds_read_b128 v[200:203], v151 offset:4096
	ds_read_b128 v[204:207], v151 offset:5120
	ds_read_b128 v[208:211], v151 offset:6144
	ds_read_b128 v[212:215], v151 offset:7168
	global_load_lds_dwordx4 v[144:145], off
	v_lshl_add_u64 v[144:145], s[36:37], 0, v[138:139]
	s_add_i32 m0, s25, 0xe000
	s_nop 0
	global_load_lds_dwordx4 v[144:145], off
	s_waitcnt vmcnt(8)
	s_waitcnt lgkmcnt(0)
	s_barrier
	s_nop 0
	s_waitcnt lgkmcnt(0)
	v_mfma_f32_16x16x32_bf16 v[124:127], v[152:155], v[184:187], v[124:127]
	v_mfma_f32_16x16x32_bf16 v[120:123], v[160:163], v[184:187], v[120:123]
	v_mfma_f32_16x16x32_bf16 v[116:119], v[152:155], v[192:195], v[116:119]
	v_mfma_f32_16x16x32_bf16 v[108:111], v[160:163], v[192:195], v[108:111]
	v_mfma_f32_16x16x32_bf16 v[100:103], v[152:155], v[200:203], v[100:103]
	v_mfma_f32_16x16x32_bf16 v[92:95], v[160:163], v[200:203], v[92:95]
	v_mfma_f32_16x16x32_bf16 v[84:87], v[152:155], v[208:211], v[84:87]
	v_mfma_f32_16x16x32_bf16 v[76:79], v[160:163], v[208:211], v[76:79]
	v_mfma_f32_16x16x32_bf16 v[124:127], v[156:159], v[188:191], v[124:127]
	v_mfma_f32_16x16x32_bf16 v[120:123], v[164:167], v[188:191], v[120:123]
	v_mfma_f32_16x16x32_bf16 v[116:119], v[156:159], v[196:199], v[116:119]
	v_mfma_f32_16x16x32_bf16 v[108:111], v[164:167], v[196:199], v[108:111]
	v_mfma_f32_16x16x32_bf16 v[100:103], v[156:159], v[204:207], v[100:103]
	v_mfma_f32_16x16x32_bf16 v[92:95], v[164:167], v[204:207], v[92:95]
	v_mfma_f32_16x16x32_bf16 v[84:87], v[156:159], v[212:215], v[84:87]
	v_mfma_f32_16x16x32_bf16 v[76:79], v[164:167], v[212:215], v[76:79]
	s_nop 0
	s_nop 0
	v_mfma_f32_16x16x32_bf16 v[112:115], v[168:171], v[184:187], v[112:115]
	v_mfma_f32_16x16x32_bf16 v[104:107], v[176:179], v[184:187], v[104:107]
	v_mfma_f32_16x16x32_bf16 v[96:99], v[168:171], v[192:195], v[96:99]
	v_mfma_f32_16x16x32_bf16 v[88:91], v[176:179], v[192:195], v[88:91]
	v_mfma_f32_16x16x32_bf16 v[80:83], v[168:171], v[200:203], v[80:83]
	v_mfma_f32_16x16x32_bf16 v[72:75], v[176:179], v[200:203], v[72:75]
	v_mfma_f32_16x16x32_bf16 v[68:71], v[168:171], v[208:211], v[68:71]
	v_mfma_f32_16x16x32_bf16 v[64:67], v[176:179], v[208:211], v[64:67]
	v_mfma_f32_16x16x32_bf16 v[112:115], v[172:175], v[188:191], v[112:115]
	v_mfma_f32_16x16x32_bf16 v[104:107], v[180:183], v[188:191], v[104:107]
	v_mfma_f32_16x16x32_bf16 v[96:99], v[172:175], v[196:199], v[96:99]
	v_mfma_f32_16x16x32_bf16 v[88:91], v[180:183], v[196:199], v[88:91]
	v_mfma_f32_16x16x32_bf16 v[80:83], v[172:175], v[204:207], v[80:83]
	v_mfma_f32_16x16x32_bf16 v[72:75], v[180:183], v[204:207], v[72:75]
	v_mfma_f32_16x16x32_bf16 v[68:71], v[172:175], v[212:215], v[68:71]
	v_mfma_f32_16x16x32_bf16 v[64:67], v[180:183], v[212:215], v[64:67]
	s_nop 0
	s_barrier
	s_add_i32 s58, s71, s3
	v_lshl_add_u64 v[144:145], s[38:39], 0, v[132:133]
	s_mov_b32 m0, s58
	ds_read_b128 v[184:187], v151 offset:16384
	ds_read_b128 v[188:191], v151 offset:17408
	ds_read_b128 v[192:195], v151 offset:18432
	ds_read_b128 v[196:199], v151 offset:19456
	ds_read_b128 v[200:203], v151 offset:20480
	ds_read_b128 v[204:207], v151 offset:21504
	ds_read_b128 v[208:211], v151 offset:22528
	ds_read_b128 v[212:215], v151 offset:23552
	global_load_lds_dwordx4 v[144:145], off
	s_add_i32 m0, s58, 0x2000
	s_add_u32 s84, s38, 0x40000
	v_lshl_add_u64 v[216:217], s[38:39], 0, v[128:129]
	s_addc_u32 s85, s39, 0
	s_add_i32 s58, s72, s3
	global_load_lds_dwordx4 v[216:217], off
	v_lshl_add_u64 v[218:219], s[84:85], 0, v[132:133]
	s_mov_b32 m0, s58
	v_lshl_add_u64 v[220:221], s[48:49], 0, v[130:131]
	global_load_lds_dwordx4 v[218:219], off
	v_lshl_add_u64 v[218:219], s[84:85], 0, v[128:129]
	s_add_i32 m0, s58, 0x2000
	s_nop 0
	global_load_lds_dwordx4 v[218:219], off
	v_lshl_add_u64 v[218:219], s[48:49], 0, v[134:135]
	s_mov_b32 m0, s25
	s_nop 0
	global_load_lds_dwordx4 v[218:219], off
	s_mov_b32 m0, s31
	s_nop 0
	global_load_lds_dwordx4 v[220:221], off
	s_waitcnt vmcnt(8)
	s_waitcnt lgkmcnt(0)
	s_barrier
	s_nop 0
	s_waitcnt lgkmcnt(0)
	v_mfma_f32_16x16x32_bf16 v[60:63], v[152:155], v[184:187], v[60:63]
	v_mfma_f32_16x16x32_bf16 v[56:59], v[160:163], v[184:187], v[56:59]
	v_mfma_f32_16x16x32_bf16 v[52:55], v[152:155], v[192:195], v[52:55]
	v_mfma_f32_16x16x32_bf16 v[44:47], v[160:163], v[192:195], v[44:47]
	v_mfma_f32_16x16x32_bf16 v[36:39], v[152:155], v[200:203], v[36:39]
	v_mfma_f32_16x16x32_bf16 v[28:31], v[160:163], v[200:203], v[28:31]
	v_mfma_f32_16x16x32_bf16 v[20:23], v[152:155], v[208:211], v[20:23]
	v_mfma_f32_16x16x32_bf16 v[12:15], v[160:163], v[208:211], v[12:15]
	v_mfma_f32_16x16x32_bf16 v[60:63], v[156:159], v[188:191], v[60:63]
	v_mfma_f32_16x16x32_bf16 v[56:59], v[164:167], v[188:191], v[56:59]
	v_mfma_f32_16x16x32_bf16 v[52:55], v[156:159], v[196:199], v[52:55]
	v_mfma_f32_16x16x32_bf16 v[44:47], v[164:167], v[196:199], v[44:47]
	v_mfma_f32_16x16x32_bf16 v[36:39], v[156:159], v[204:207], v[36:39]
	v_mfma_f32_16x16x32_bf16 v[28:31], v[164:167], v[204:207], v[28:31]
	v_mfma_f32_16x16x32_bf16 v[20:23], v[156:159], v[212:215], v[20:23]
	v_mfma_f32_16x16x32_bf16 v[12:15], v[164:167], v[212:215], v[12:15]
	s_nop 0
	s_nop 0
	v_mfma_f32_16x16x32_bf16 v[48:51], v[168:171], v[184:187], v[48:51]
	v_mfma_f32_16x16x32_bf16 v[40:43], v[176:179], v[184:187], v[40:43]
	v_mfma_f32_16x16x32_bf16 v[32:35], v[168:171], v[192:195], v[32:35]
	v_mfma_f32_16x16x32_bf16 v[24:27], v[176:179], v[192:195], v[24:27]
	v_mfma_f32_16x16x32_bf16 v[16:19], v[168:171], v[200:203], v[16:19]
	v_mfma_f32_16x16x32_bf16 v[8:11], v[176:179], v[200:203], v[8:11]
	v_mfma_f32_16x16x32_bf16 v[4:7], v[168:171], v[208:211], v[4:7]
	v_mfma_f32_16x16x32_bf16 v[0:3], v[176:179], v[208:211], v[0:3]
	v_mfma_f32_16x16x32_bf16 v[48:51], v[172:175], v[188:191], v[48:51]
	v_mfma_f32_16x16x32_bf16 v[40:43], v[180:183], v[188:191], v[40:43]
	v_mfma_f32_16x16x32_bf16 v[32:35], v[172:175], v[196:199], v[32:35]
	v_mfma_f32_16x16x32_bf16 v[24:27], v[180:183], v[196:199], v[24:27]
	v_mfma_f32_16x16x32_bf16 v[16:19], v[172:175], v[204:207], v[16:19]
	v_mfma_f32_16x16x32_bf16 v[8:11], v[180:183], v[204:207], v[8:11]
	v_mfma_f32_16x16x32_bf16 v[4:7], v[172:175], v[212:215], v[4:7]
	v_mfma_f32_16x16x32_bf16 v[0:3], v[180:183], v[212:215], v[0:3]
	s_nop 0
	s_barrier
	s_add_i32 s58, 0, 0x18000
	s_add_i32 s59, 0, 0x1c000
	v_add_u32_e32 v164, s58, v147
	v_add_u32_e32 v180, s59, v147
	ds_read_b128 v[152:155], v164
	ds_read_b128 v[156:159], v164 offset:1024
	ds_read_b128 v[160:163], v164 offset:2048
	ds_read_b128 v[164:167], v164 offset:3072
	ds_read_b128 v[168:171], v180
	ds_read_b128 v[172:175], v180 offset:1024
	ds_read_b128 v[176:179], v180 offset:2048
	ds_read_b128 v[180:183], v180 offset:3072
	s_add_u32 s48, s48, 0x40000
	s_addc_u32 s49, s49, 0
	s_mov_b32 m0, s33
	v_lshl_add_u64 v[222:223], s[48:49], 0, v[134:135]
	ds_read_b128 v[184:187], v151 offset:32768
	ds_read_b128 v[188:191], v151 offset:33792
	ds_read_b128 v[192:195], v151 offset:34816
	ds_read_b128 v[196:199], v151 offset:35840
	ds_read_b128 v[200:203], v151 offset:36864
	ds_read_b128 v[204:207], v151 offset:37888
	ds_read_b128 v[208:211], v151 offset:38912
	ds_read_b128 v[212:215], v151 offset:39936
	global_load_lds_dwordx4 v[222:223], off
	v_lshl_add_u64 v[222:223], s[48:49], 0, v[130:131]
	s_mov_b32 m0, s42
	s_nop 0
	global_load_lds_dwordx4 v[222:223], off
	s_waitcnt vmcnt(8)
	s_waitcnt lgkmcnt(0)
	s_barrier
	s_nop 0
	s_waitcnt lgkmcnt(0)
	v_mfma_f32_16x16x32_bf16 v[124:127], v[152:155], v[184:187], v[124:127]
	v_mfma_f32_16x16x32_bf16 v[120:123], v[160:163], v[184:187], v[120:123]
	v_mfma_f32_16x16x32_bf16 v[116:119], v[152:155], v[192:195], v[116:119]
	v_mfma_f32_16x16x32_bf16 v[108:111], v[160:163], v[192:195], v[108:111]
	v_mfma_f32_16x16x32_bf16 v[100:103], v[152:155], v[200:203], v[100:103]
	v_mfma_f32_16x16x32_bf16 v[92:95], v[160:163], v[200:203], v[92:95]
	v_mfma_f32_16x16x32_bf16 v[84:87], v[152:155], v[208:211], v[84:87]
	v_mfma_f32_16x16x32_bf16 v[76:79], v[160:163], v[208:211], v[76:79]
	v_mfma_f32_16x16x32_bf16 v[124:127], v[156:159], v[188:191], v[124:127]
	v_mfma_f32_16x16x32_bf16 v[120:123], v[164:167], v[188:191], v[120:123]
	v_mfma_f32_16x16x32_bf16 v[116:119], v[156:159], v[196:199], v[116:119]
	v_mfma_f32_16x16x32_bf16 v[108:111], v[164:167], v[196:199], v[108:111]
	v_mfma_f32_16x16x32_bf16 v[100:103], v[156:159], v[204:207], v[100:103]
	v_mfma_f32_16x16x32_bf16 v[92:95], v[164:167], v[204:207], v[92:95]
	v_mfma_f32_16x16x32_bf16 v[84:87], v[156:159], v[212:215], v[84:87]
	v_mfma_f32_16x16x32_bf16 v[76:79], v[164:167], v[212:215], v[76:79]
	s_nop 0
	s_nop 0
	v_mfma_f32_16x16x32_bf16 v[112:115], v[168:171], v[184:187], v[112:115]
	v_mfma_f32_16x16x32_bf16 v[104:107], v[176:179], v[184:187], v[104:107]
	v_mfma_f32_16x16x32_bf16 v[96:99], v[168:171], v[192:195], v[96:99]
	v_mfma_f32_16x16x32_bf16 v[88:91], v[176:179], v[192:195], v[88:91]
	v_mfma_f32_16x16x32_bf16 v[80:83], v[168:171], v[200:203], v[80:83]
	v_mfma_f32_16x16x32_bf16 v[72:75], v[176:179], v[200:203], v[72:75]
	v_mfma_f32_16x16x32_bf16 v[68:71], v[168:171], v[208:211], v[68:71]
	v_mfma_f32_16x16x32_bf16 v[64:67], v[176:179], v[208:211], v[64:67]
	v_mfma_f32_16x16x32_bf16 v[112:115], v[172:175], v[188:191], v[112:115]
	v_mfma_f32_16x16x32_bf16 v[104:107], v[180:183], v[188:191], v[104:107]
	v_mfma_f32_16x16x32_bf16 v[96:99], v[172:175], v[196:199], v[96:99]
	v_mfma_f32_16x16x32_bf16 v[88:91], v[180:183], v[196:199], v[88:91]
	v_mfma_f32_16x16x32_bf16 v[80:83], v[172:175], v[204:207], v[80:83]
	v_mfma_f32_16x16x32_bf16 v[72:75], v[180:183], v[204:207], v[72:75]
	v_mfma_f32_16x16x32_bf16 v[68:71], v[172:175], v[212:215], v[68:71]
	v_mfma_f32_16x16x32_bf16 v[64:67], v[180:183], v[212:215], v[64:67]
	s_nop 0
	s_barrier
	s_add_i32 s48, s58, s3
	v_lshl_add_u64 v[144:145], v[144:145], 0, s[12:13]
	s_mov_b32 m0, s48
	ds_read_b128 v[184:187], v151 offset:49152
	ds_read_b128 v[188:191], v151 offset:50176
	ds_read_b128 v[192:195], v151 offset:51200
	ds_read_b128 v[196:199], v151 offset:52224
	ds_read_b128 v[200:203], v151 offset:53248
	ds_read_b128 v[204:207], v151 offset:54272
	ds_read_b128 v[208:211], v151 offset:55296
	ds_read_b128 v[212:215], v151 offset:56320
	global_load_lds_dwordx4 v[144:145], off
	s_add_i32 m0, s48, 0x2000
	s_add_u32 s38, s38, 0x40080
	v_lshl_add_u64 v[144:145], v[216:217], 0, s[12:13]
	s_addc_u32 s39, s39, 0
	s_add_i32 s48, s59, s3
	global_load_lds_dwordx4 v[144:145], off
	v_lshl_add_u64 v[144:145], s[38:39], 0, v[132:133]
	s_mov_b32 m0, s48
	s_nop 0
	global_load_lds_dwordx4 v[144:145], off
	v_lshl_add_u64 v[144:145], s[38:39], 0, v[128:129]
	s_add_i32 m0, s48, 0x2000
	s_nop 0
	global_load_lds_dwordx4 v[144:145], off
	v_lshl_add_u64 v[144:145], v[218:219], 0, s[12:13]
	s_mov_b32 m0, s68
	s_nop 0
	global_load_lds_dwordx4 v[144:145], off
	v_lshl_add_u64 v[144:145], v[220:221], 0, s[12:13]
	s_mov_b32 m0, s69
	s_nop 0
	global_load_lds_dwordx4 v[144:145], off
	s_waitcnt vmcnt(8)
	s_waitcnt lgkmcnt(0)
	s_barrier
	s_nop 0
	s_waitcnt lgkmcnt(0)
	v_mfma_f32_16x16x32_bf16 v[60:63], v[152:155], v[184:187], v[60:63]
	v_mfma_f32_16x16x32_bf16 v[56:59], v[160:163], v[184:187], v[56:59]
	v_mfma_f32_16x16x32_bf16 v[52:55], v[152:155], v[192:195], v[52:55]
	v_mfma_f32_16x16x32_bf16 v[44:47], v[160:163], v[192:195], v[44:47]
	v_mfma_f32_16x16x32_bf16 v[36:39], v[152:155], v[200:203], v[36:39]
	v_mfma_f32_16x16x32_bf16 v[28:31], v[160:163], v[200:203], v[28:31]
	v_mfma_f32_16x16x32_bf16 v[20:23], v[152:155], v[208:211], v[20:23]
	v_mfma_f32_16x16x32_bf16 v[12:15], v[160:163], v[208:211], v[12:15]
	v_mfma_f32_16x16x32_bf16 v[60:63], v[156:159], v[188:191], v[60:63]
	v_mfma_f32_16x16x32_bf16 v[56:59], v[164:167], v[188:191], v[56:59]
	v_mfma_f32_16x16x32_bf16 v[52:55], v[156:159], v[196:199], v[52:55]
	v_mfma_f32_16x16x32_bf16 v[44:47], v[164:167], v[196:199], v[44:47]
	v_mfma_f32_16x16x32_bf16 v[36:39], v[156:159], v[204:207], v[36:39]
	v_mfma_f32_16x16x32_bf16 v[28:31], v[164:167], v[204:207], v[28:31]
	v_mfma_f32_16x16x32_bf16 v[20:23], v[156:159], v[212:215], v[20:23]
	v_mfma_f32_16x16x32_bf16 v[12:15], v[164:167], v[212:215], v[12:15]
	s_nop 0
	s_nop 0
	v_mfma_f32_16x16x32_bf16 v[48:51], v[168:171], v[184:187], v[48:51]
	v_mfma_f32_16x16x32_bf16 v[40:43], v[176:179], v[184:187], v[40:43]
	v_mfma_f32_16x16x32_bf16 v[32:35], v[168:171], v[192:195], v[32:35]
	v_mfma_f32_16x16x32_bf16 v[24:27], v[176:179], v[192:195], v[24:27]
	v_mfma_f32_16x16x32_bf16 v[16:19], v[168:171], v[200:203], v[16:19]
	v_mfma_f32_16x16x32_bf16 v[8:11], v[176:179], v[200:203], v[8:11]
	v_mfma_f32_16x16x32_bf16 v[4:7], v[168:171], v[208:211], v[4:7]
	v_mfma_f32_16x16x32_bf16 v[0:3], v[176:179], v[208:211], v[0:3]
	v_mfma_f32_16x16x32_bf16 v[48:51], v[172:175], v[188:191], v[48:51]
	v_mfma_f32_16x16x32_bf16 v[40:43], v[180:183], v[188:191], v[40:43]
	v_mfma_f32_16x16x32_bf16 v[32:35], v[172:175], v[196:199], v[32:35]
	v_mfma_f32_16x16x32_bf16 v[24:27], v[180:183], v[196:199], v[24:27]
	v_mfma_f32_16x16x32_bf16 v[16:19], v[172:175], v[204:207], v[16:19]
	v_mfma_f32_16x16x32_bf16 v[8:11], v[180:183], v[204:207], v[8:11]
	v_mfma_f32_16x16x32_bf16 v[4:7], v[172:175], v[212:215], v[4:7]
	v_mfma_f32_16x16x32_bf16 v[0:3], v[180:183], v[212:215], v[0:3]
	s_nop 0
	s_barrier
	s_add_i32 s82, s82, 2
	s_add_u32 s36, s36, 0x100
	s_addc_u32 s37, s37, 0
	s_add_u32 s80, s80, 0x100
	s_addc_u32 s81, s81, 0
	s_cmp_gt_u32 s82, 13
	s_cbranch_scc0 .LBB0_193
	s_and_b64 vcc, exec, s[10:11]
	s_cbranch_vccz .LBB0_196
	s_barrier

.LBB0_342:
	ds_read_b128 v[112:115], v214
	ds_read_b128 v[120:123], v214 offset:1024
	ds_read_b128 v[128:131], v214 offset:2048
	ds_read_b128 v[132:135], v214 offset:3072
	ds_read_b128 v[144:147], v215
	ds_read_b128 v[148:151], v215 offset:1024
	ds_read_b128 v[168:171], v215 offset:2048
	ds_read_b128 v[172:175], v215 offset:3072
	s_add_u32 s58, s70, 0xfffc0080
	s_addc_u32 s59, s71, -1
	s_cmp_eq_u32 s88, 12
	s_cselect_b32 s75, s1, s59
	s_cselect_b32 s74, s18, s58
	s_cselect_b32 s73, s35, s87
	s_cselect_b32 s72, s37, s69
	v_lshl_add_u64 v[192:193], s[70:71], 0, v[160:161]
	s_add_i32 m0, s24, 0xc000
	ds_read_b128 v[176:179], v216
	ds_read_b128 v[180:183], v216 offset:1024
	ds_read_b128 v[184:187], v216 offset:2048
	ds_read_b128 v[188:191], v216 offset:3072
	ds_read_b128 v[222:225], v216 offset:4096
	ds_read_b128 v[226:229], v216 offset:5120
	ds_read_b128 v[230:233], v216 offset:6144
	ds_read_b128 v[234:237], v216 offset:7168
	global_load_lds_dwordx4 v[192:193], off
	v_lshl_add_u64 v[192:193], s[70:71], 0, v[162:163]
	s_add_i32 m0, s24, 0xe000
	s_nop 0
	global_load_lds_dwordx4 v[192:193], off
	s_waitcnt vmcnt(8)
	s_waitcnt lgkmcnt(0)
	s_barrier
	s_nop 0
	s_waitcnt lgkmcnt(0)
	v_mfma_f32_16x16x32_bf16 v[140:143], v[112:115], v[176:179], v[140:143]
	v_mfma_f32_16x16x32_bf16 v[136:139], v[128:131], v[176:179], v[136:139]
	v_mfma_f32_16x16x32_bf16 v[108:111], v[112:115], v[184:187], v[108:111]
	v_mfma_f32_16x16x32_bf16 v[104:107], v[128:131], v[184:187], v[104:107]
	v_mfma_f32_16x16x32_bf16 v[92:95], v[112:115], v[222:225], v[92:95]
	v_mfma_f32_16x16x32_bf16 v[88:91], v[128:131], v[222:225], v[88:91]
	v_mfma_f32_16x16x32_bf16 v[76:79], v[112:115], v[230:233], v[76:79]
	v_mfma_f32_16x16x32_bf16 v[72:75], v[128:131], v[230:233], v[72:75]
	v_mfma_f32_16x16x32_bf16 v[140:143], v[120:123], v[180:183], v[140:143]
	v_mfma_f32_16x16x32_bf16 v[136:139], v[132:135], v[180:183], v[136:139]
	v_mfma_f32_16x16x32_bf16 v[108:111], v[120:123], v[188:191], v[108:111]
	v_mfma_f32_16x16x32_bf16 v[104:107], v[132:135], v[188:191], v[104:107]
	v_mfma_f32_16x16x32_bf16 v[92:95], v[120:123], v[226:229], v[92:95]
	v_mfma_f32_16x16x32_bf16 v[88:91], v[132:135], v[226:229], v[88:91]
	v_mfma_f32_16x16x32_bf16 v[76:79], v[120:123], v[234:237], v[76:79]
	v_mfma_f32_16x16x32_bf16 v[72:75], v[132:135], v[234:237], v[72:75]
	s_nop 0
	s_nop 0
	v_mfma_f32_16x16x32_bf16 v[124:127], v[144:147], v[176:179], v[124:127]
	v_mfma_f32_16x16x32_bf16 v[116:119], v[168:171], v[176:179], v[116:119]
	v_mfma_f32_16x16x32_bf16 v[100:103], v[144:147], v[184:187], v[100:103]
	v_mfma_f32_16x16x32_bf16 v[96:99], v[168:171], v[184:187], v[96:99]
	v_mfma_f32_16x16x32_bf16 v[84:87], v[144:147], v[222:225], v[84:87]
	v_mfma_f32_16x16x32_bf16 v[80:83], v[168:171], v[222:225], v[80:83]
	v_mfma_f32_16x16x32_bf16 v[68:71], v[144:147], v[230:233], v[68:71]
	v_mfma_f32_16x16x32_bf16 v[64:67], v[168:171], v[230:233], v[64:67]
	v_mfma_f32_16x16x32_bf16 v[124:127], v[148:151], v[180:183], v[124:127]
	v_mfma_f32_16x16x32_bf16 v[116:119], v[172:175], v[180:183], v[116:119]
	v_mfma_f32_16x16x32_bf16 v[100:103], v[148:151], v[188:191], v[100:103]
	v_mfma_f32_16x16x32_bf16 v[96:99], v[172:175], v[188:191], v[96:99]
	v_mfma_f32_16x16x32_bf16 v[84:87], v[148:151], v[226:229], v[84:87]
	v_mfma_f32_16x16x32_bf16 v[80:83], v[172:175], v[226:229], v[80:83]
	v_mfma_f32_16x16x32_bf16 v[68:71], v[148:151], v[234:237], v[68:71]
	v_mfma_f32_16x16x32_bf16 v[64:67], v[172:175], v[234:237], v[64:67]
	s_nop 0
	s_barrier
	s_add_i32 s58, s84, s3
	v_lshl_add_u64 v[192:193], s[72:73], 0, v[152:153]
	s_mov_b32 m0, s58
	ds_read_b128 v[176:179], v216 offset:16384
	ds_read_b128 v[180:183], v216 offset:17408
	ds_read_b128 v[184:187], v216 offset:18432
	ds_read_b128 v[188:191], v216 offset:19456
	ds_read_b128 v[222:225], v216 offset:20480
	ds_read_b128 v[226:229], v216 offset:21504
	ds_read_b128 v[230:233], v216 offset:22528
	ds_read_b128 v[234:237], v216 offset:23552
	global_load_lds_dwordx4 v[192:193], off
	s_add_i32 m0, s58, 0x2000
	s_add_u32 s90, s72, 0x40000
	v_lshl_add_u64 v[238:239], s[72:73], 0, v[154:155]
	s_addc_u32 s91, s73, 0
	s_add_i32 s58, s85, s3
	global_load_lds_dwordx4 v[238:239], off
	v_lshl_add_u64 v[240:241], s[90:91], 0, v[152:153]
	s_mov_b32 m0, s58
	v_lshl_add_u64 v[242:243], s[74:75], 0, v[156:157]
	global_load_lds_dwordx4 v[240:241], off
	v_lshl_add_u64 v[240:241], s[90:91], 0, v[154:155]
	s_add_i32 m0, s58, 0x2000
	s_nop 0
	global_load_lds_dwordx4 v[240:241], off
	v_lshl_add_u64 v[240:241], s[74:75], 0, v[158:159]
	s_mov_b32 m0, s24
	s_nop 0
	global_load_lds_dwordx4 v[240:241], off
	s_mov_b32 m0, s25
	s_nop 0
	global_load_lds_dwordx4 v[242:243], off
	s_waitcnt vmcnt(8)
	s_waitcnt lgkmcnt(0)
	s_barrier
	s_nop 0
	s_waitcnt lgkmcnt(0)
	v_mfma_f32_16x16x32_bf16 v[60:63], v[112:115], v[176:179], v[60:63]
	v_mfma_f32_16x16x32_bf16 v[56:59], v[128:131], v[176:179], v[56:59]
	v_mfma_f32_16x16x32_bf16 v[44:47], v[112:115], v[184:187], v[44:47]
	v_mfma_f32_16x16x32_bf16 v[40:43], v[128:131], v[184:187], v[40:43]
	v_mfma_f32_16x16x32_bf16 v[28:31], v[112:115], v[222:225], v[28:31]
	v_mfma_f32_16x16x32_bf16 v[24:27], v[128:131], v[222:225], v[24:27]
	v_mfma_f32_16x16x32_bf16 v[12:15], v[112:115], v[230:233], v[12:15]
	v_mfma_f32_16x16x32_bf16 v[8:11], v[128:131], v[230:233], v[8:11]
	v_mfma_f32_16x16x32_bf16 v[60:63], v[120:123], v[180:183], v[60:63]
	v_mfma_f32_16x16x32_bf16 v[56:59], v[132:135], v[180:183], v[56:59]
	v_mfma_f32_16x16x32_bf16 v[44:47], v[120:123], v[188:191], v[44:47]
	v_mfma_f32_16x16x32_bf16 v[40:43], v[132:135], v[188:191], v[40:43]
	v_mfma_f32_16x16x32_bf16 v[28:31], v[120:123], v[226:229], v[28:31]
	v_mfma_f32_16x16x32_bf16 v[24:27], v[132:135], v[226:229], v[24:27]
	v_mfma_f32_16x16x32_bf16 v[12:15], v[120:123], v[234:237], v[12:15]
	v_mfma_f32_16x16x32_bf16 v[8:11], v[132:135], v[234:237], v[8:11]
	s_nop 0
	s_nop 0
	v_mfma_f32_16x16x32_bf16 v[52:55], v[144:147], v[176:179], v[52:55]
	v_mfma_f32_16x16x32_bf16 v[48:51], v[168:171], v[176:179], v[48:51]
	v_mfma_f32_16x16x32_bf16 v[36:39], v[144:147], v[184:187], v[36:39]
	v_mfma_f32_16x16x32_bf16 v[32:35], v[168:171], v[184:187], v[32:35]
	v_mfma_f32_16x16x32_bf16 v[20:23], v[144:147], v[222:225], v[20:23]
	v_mfma_f32_16x16x32_bf16 v[16:19], v[168:171], v[222:225], v[16:19]
	v_mfma_f32_16x16x32_bf16 v[4:7], v[144:147], v[230:233], v[4:7]
	v_mfma_f32_16x16x32_bf16 v[0:3], v[168:171], v[230:233], v[0:3]
	v_mfma_f32_16x16x32_bf16 v[52:55], v[148:151], v[180:183], v[52:55]
	v_mfma_f32_16x16x32_bf16 v[48:51], v[172:175], v[180:183], v[48:51]
	v_mfma_f32_16x16x32_bf16 v[36:39], v[148:151], v[188:191], v[36:39]
	v_mfma_f32_16x16x32_bf16 v[32:35], v[172:175], v[188:191], v[32:35]
	v_mfma_f32_16x16x32_bf16 v[20:23], v[148:151], v[226:229], v[20:23]
	v_mfma_f32_16x16x32_bf16 v[16:19], v[172:175], v[226:229], v[16:19]
	v_mfma_f32_16x16x32_bf16 v[4:7], v[148:151], v[234:237], v[4:7]
	v_mfma_f32_16x16x32_bf16 v[0:3], v[172:175], v[234:237], v[0:3]
	s_nop 0
	s_barrier
	s_add_i32 s58, 0, 0x18000
	s_add_i32 s59, 0, 0x1c000
	v_add_u32_e32 v132, s58, v195
	v_add_u32_e32 v172, s59, v195
	ds_read_b128 v[112:115], v132
	ds_read_b128 v[120:123], v132 offset:1024
	ds_read_b128 v[128:131], v132 offset:2048
	ds_read_b128 v[132:135], v132 offset:3072
	ds_read_b128 v[144:147], v172
	ds_read_b128 v[148:151], v172 offset:1024
	ds_read_b128 v[168:171], v172 offset:2048
	ds_read_b128 v[172:175], v172 offset:3072
	s_add_u32 s74, s74, 0x40000
	s_addc_u32 s75, s75, 0
	s_mov_b32 m0, s42
	v_lshl_add_u64 v[244:245], s[74:75], 0, v[158:159]
	ds_read_b128 v[176:179], v216 offset:32768
	ds_read_b128 v[180:183], v216 offset:33792
	ds_read_b128 v[184:187], v216 offset:34816
	ds_read_b128 v[188:191], v216 offset:35840
	ds_read_b128 v[222:225], v216 offset:36864
	ds_read_b128 v[226:229], v216 offset:37888
	ds_read_b128 v[230:233], v216 offset:38912
	ds_read_b128 v[234:237], v216 offset:39936
	global_load_lds_dwordx4 v[244:245], off
	v_lshl_add_u64 v[244:245], s[74:75], 0, v[156:157]
	s_mov_b32 m0, s43
	s_nop 0
	global_load_lds_dwordx4 v[244:245], off
	s_waitcnt vmcnt(8)
	s_waitcnt lgkmcnt(0)
	s_barrier
	s_nop 0
	s_waitcnt lgkmcnt(0)
	v_mfma_f32_16x16x32_bf16 v[140:143], v[112:115], v[176:179], v[140:143]
	v_mfma_f32_16x16x32_bf16 v[136:139], v[128:131], v[176:179], v[136:139]
	v_mfma_f32_16x16x32_bf16 v[108:111], v[112:115], v[184:187], v[108:111]
	v_mfma_f32_16x16x32_bf16 v[104:107], v[128:131], v[184:187], v[104:107]
	v_mfma_f32_16x16x32_bf16 v[92:95], v[112:115], v[222:225], v[92:95]
	v_mfma_f32_16x16x32_bf16 v[88:91], v[128:131], v[222:225], v[88:91]
	v_mfma_f32_16x16x32_bf16 v[76:79], v[112:115], v[230:233], v[76:79]
	v_mfma_f32_16x16x32_bf16 v[72:75], v[128:131], v[230:233], v[72:75]
	v_mfma_f32_16x16x32_bf16 v[140:143], v[120:123], v[180:183], v[140:143]
	v_mfma_f32_16x16x32_bf16 v[136:139], v[132:135], v[180:183], v[136:139]
	v_mfma_f32_16x16x32_bf16 v[108:111], v[120:123], v[188:191], v[108:111]
	v_mfma_f32_16x16x32_bf16 v[104:107], v[132:135], v[188:191], v[104:107]
	v_mfma_f32_16x16x32_bf16 v[92:95], v[120:123], v[226:229], v[92:95]
	v_mfma_f32_16x16x32_bf16 v[88:91], v[132:135], v[226:229], v[88:91]
	v_mfma_f32_16x16x32_bf16 v[76:79], v[120:123], v[234:237], v[76:79]
	v_mfma_f32_16x16x32_bf16 v[72:75], v[132:135], v[234:237], v[72:75]
	s_nop 0
	s_nop 0
	v_mfma_f32_16x16x32_bf16 v[124:127], v[144:147], v[176:179], v[124:127]
	v_mfma_f32_16x16x32_bf16 v[116:119], v[168:171], v[176:179], v[116:119]
	v_mfma_f32_16x16x32_bf16 v[100:103], v[144:147], v[184:187], v[100:103]
	v_mfma_f32_16x16x32_bf16 v[96:99], v[168:171], v[184:187], v[96:99]
	v_mfma_f32_16x16x32_bf16 v[84:87], v[144:147], v[222:225], v[84:87]
	v_mfma_f32_16x16x32_bf16 v[80:83], v[168:171], v[222:225], v[80:83]
	v_mfma_f32_16x16x32_bf16 v[68:71], v[144:147], v[230:233], v[68:71]
	v_mfma_f32_16x16x32_bf16 v[64:67], v[168:171], v[230:233], v[64:67]
	v_mfma_f32_16x16x32_bf16 v[124:127], v[148:151], v[180:183], v[124:127]
	v_mfma_f32_16x16x32_bf16 v[116:119], v[172:175], v[180:183], v[116:119]
	v_mfma_f32_16x16x32_bf16 v[100:103], v[148:151], v[188:191], v[100:103]
	v_mfma_f32_16x16x32_bf16 v[96:99], v[172:175], v[188:191], v[96:99]
	v_mfma_f32_16x16x32_bf16 v[84:87], v[148:151], v[226:229], v[84:87]
	v_mfma_f32_16x16x32_bf16 v[80:83], v[172:175], v[226:229], v[80:83]
	v_mfma_f32_16x16x32_bf16 v[68:71], v[148:151], v[234:237], v[68:71]
	v_mfma_f32_16x16x32_bf16 v[64:67], v[172:175], v[234:237], v[64:67]
	s_nop 0
	s_barrier
	s_add_i32 s58, s58, s3
	v_lshl_add_u64 v[192:193], v[192:193], 0, s[30:31]
	s_mov_b32 m0, s58
	ds_read_b128 v[176:179], v216 offset:49152
	ds_read_b128 v[180:183], v216 offset:50176
	ds_read_b128 v[184:187], v216 offset:51200
	ds_read_b128 v[188:191], v216 offset:52224
	ds_read_b128 v[222:225], v216 offset:53248
	ds_read_b128 v[226:229], v216 offset:54272
	ds_read_b128 v[230:233], v216 offset:55296
	ds_read_b128 v[234:237], v216 offset:56320
	global_load_lds_dwordx4 v[192:193], off
	s_add_i32 m0, s58, 0x2000
	s_add_u32 s72, s72, 0x40080
	v_lshl_add_u64 v[192:193], v[238:239], 0, s[30:31]
	s_addc_u32 s73, s73, 0
	s_add_i32 s58, s59, s3
	global_load_lds_dwordx4 v[192:193], off
	v_lshl_add_u64 v[192:193], s[72:73], 0, v[152:153]
	s_mov_b32 m0, s58
	s_nop 0
	global_load_lds_dwordx4 v[192:193], off
	v_lshl_add_u64 v[192:193], s[72:73], 0, v[154:155]
	s_add_i32 m0, s58, 0x2000
	s_nop 0
	global_load_lds_dwordx4 v[192:193], off
	v_lshl_add_u64 v[192:193], v[240:241], 0, s[30:31]
	s_mov_b32 m0, s81
	s_nop 0
	global_load_lds_dwordx4 v[192:193], off
	v_lshl_add_u64 v[192:193], v[242:243], 0, s[30:31]
	s_mov_b32 m0, s82
	s_nop 0
	global_load_lds_dwordx4 v[192:193], off
	s_waitcnt vmcnt(8)
	s_waitcnt lgkmcnt(0)
	s_barrier
	s_nop 0
	s_waitcnt lgkmcnt(0)
	v_mfma_f32_16x16x32_bf16 v[60:63], v[112:115], v[176:179], v[60:63]
	v_mfma_f32_16x16x32_bf16 v[56:59], v[128:131], v[176:179], v[56:59]
	v_mfma_f32_16x16x32_bf16 v[44:47], v[112:115], v[184:187], v[44:47]
	v_mfma_f32_16x16x32_bf16 v[40:43], v[128:131], v[184:187], v[40:43]
	v_mfma_f32_16x16x32_bf16 v[28:31], v[112:115], v[222:225], v[28:31]
	v_mfma_f32_16x16x32_bf16 v[24:27], v[128:131], v[222:225], v[24:27]
	v_mfma_f32_16x16x32_bf16 v[12:15], v[112:115], v[230:233], v[12:15]
	v_mfma_f32_16x16x32_bf16 v[8:11], v[128:131], v[230:233], v[8:11]
	v_mfma_f32_16x16x32_bf16 v[60:63], v[120:123], v[180:183], v[60:63]
	v_mfma_f32_16x16x32_bf16 v[56:59], v[132:135], v[180:183], v[56:59]
	v_mfma_f32_16x16x32_bf16 v[44:47], v[120:123], v[188:191], v[44:47]
	v_mfma_f32_16x16x32_bf16 v[40:43], v[132:135], v[188:191], v[40:43]
	v_mfma_f32_16x16x32_bf16 v[28:31], v[120:123], v[226:229], v[28:31]
	v_mfma_f32_16x16x32_bf16 v[24:27], v[132:135], v[226:229], v[24:27]
	v_mfma_f32_16x16x32_bf16 v[12:15], v[120:123], v[234:237], v[12:15]
	v_mfma_f32_16x16x32_bf16 v[8:11], v[132:135], v[234:237], v[8:11]
	s_nop 0
	s_nop 0
	v_mfma_f32_16x16x32_bf16 v[52:55], v[144:147], v[176:179], v[52:55]
	v_mfma_f32_16x16x32_bf16 v[48:51], v[168:171], v[176:179], v[48:51]
	v_mfma_f32_16x16x32_bf16 v[36:39], v[144:147], v[184:187], v[36:39]
	v_mfma_f32_16x16x32_bf16 v[32:35], v[168:171], v[184:187], v[32:35]
	v_mfma_f32_16x16x32_bf16 v[20:23], v[144:147], v[222:225], v[20:23]
	v_mfma_f32_16x16x32_bf16 v[16:19], v[168:171], v[222:225], v[16:19]
	v_mfma_f32_16x16x32_bf16 v[4:7], v[144:147], v[230:233], v[4:7]
	v_mfma_f32_16x16x32_bf16 v[0:3], v[168:171], v[230:233], v[0:3]
	v_mfma_f32_16x16x32_bf16 v[52:55], v[148:151], v[180:183], v[52:55]
	v_mfma_f32_16x16x32_bf16 v[48:51], v[172:175], v[180:183], v[48:51]
	v_mfma_f32_16x16x32_bf16 v[36:39], v[148:151], v[188:191], v[36:39]
	v_mfma_f32_16x16x32_bf16 v[32:35], v[172:175], v[188:191], v[32:35]
	v_mfma_f32_16x16x32_bf16 v[20:23], v[148:151], v[226:229], v[20:23]
	v_mfma_f32_16x16x32_bf16 v[16:19], v[172:175], v[226:229], v[16:19]
	v_mfma_f32_16x16x32_bf16 v[4:7], v[148:151], v[234:237], v[4:7]
	v_mfma_f32_16x16x32_bf16 v[0:3], v[172:175], v[234:237], v[0:3]
	s_nop 0
	s_barrier
	s_add_i32 s88, s88, 2
	s_add_u32 s70, s70, 0x100
	s_addc_u32 s71, s71, 0
	s_add_u32 s69, s69, 0x100
	s_addc_u32 s87, s87, 0
	s_cmp_gt_u32 s88, 13
	s_cbranch_scc0 .LBB0_342
	s_and_b64 vcc, exec, s[22:23]
	s_cbranch_vccz .LBB0_345
	s_barrier

.LBB0_438:
	ds_read_b128 v[152:155], v149
	ds_read_b128 v[156:159], v149 offset:1024
	ds_read_b128 v[160:163], v149 offset:2048
	ds_read_b128 v[164:167], v149 offset:3072
	ds_read_b128 v[168:171], v150
	ds_read_b128 v[172:175], v150 offset:1024
	ds_read_b128 v[176:179], v150 offset:2048
	ds_read_b128 v[180:183], v150 offset:3072
	s_add_u32 s36, s34, 0xfffc0080
	s_addc_u32 s37, s35, -1
	s_cmp_eq_u32 s80, 12
	s_cselect_b32 s39, s23, s37
	s_cselect_b32 s38, s76, s36
	s_cselect_b32 s37, s21, s79
	s_cselect_b32 s36, s77, s78
	v_lshl_add_u64 v[144:145], s[34:35], 0, v[136:137]
	s_add_i32 m0, s31, 0xc000
	ds_read_b128 v[184:187], v151
	ds_read_b128 v[188:191], v151 offset:1024
	ds_read_b128 v[192:195], v151 offset:2048
	ds_read_b128 v[196:199], v151 offset:3072
	ds_read_b128 v[200:203], v151 offset:4096
	ds_read_b128 v[204:207], v151 offset:5120
	ds_read_b128 v[208:211], v151 offset:6144
	ds_read_b128 v[212:215], v151 offset:7168
	global_load_lds_dwordx4 v[144:145], off
	v_lshl_add_u64 v[144:145], s[34:35], 0, v[138:139]
	s_add_i32 m0, s31, 0xe000
	s_nop 0
	global_load_lds_dwordx4 v[144:145], off
	s_waitcnt vmcnt(8)
	s_waitcnt lgkmcnt(0)
	s_barrier
	s_nop 0
	s_waitcnt lgkmcnt(0)
	v_mfma_f32_16x16x32_bf16 v[124:127], v[152:155], v[184:187], v[124:127]
	v_mfma_f32_16x16x32_bf16 v[120:123], v[160:163], v[184:187], v[120:123]
	v_mfma_f32_16x16x32_bf16 v[108:111], v[152:155], v[192:195], v[108:111]
	v_mfma_f32_16x16x32_bf16 v[104:107], v[160:163], v[192:195], v[104:107]
	v_mfma_f32_16x16x32_bf16 v[92:95], v[152:155], v[200:203], v[92:95]
	v_mfma_f32_16x16x32_bf16 v[88:91], v[160:163], v[200:203], v[88:91]
	v_mfma_f32_16x16x32_bf16 v[76:79], v[152:155], v[208:211], v[76:79]
	v_mfma_f32_16x16x32_bf16 v[72:75], v[160:163], v[208:211], v[72:75]
	v_mfma_f32_16x16x32_bf16 v[124:127], v[156:159], v[188:191], v[124:127]
	v_mfma_f32_16x16x32_bf16 v[120:123], v[164:167], v[188:191], v[120:123]
	v_mfma_f32_16x16x32_bf16 v[108:111], v[156:159], v[196:199], v[108:111]
	v_mfma_f32_16x16x32_bf16 v[104:107], v[164:167], v[196:199], v[104:107]
	v_mfma_f32_16x16x32_bf16 v[92:95], v[156:159], v[204:207], v[92:95]
	v_mfma_f32_16x16x32_bf16 v[88:91], v[164:167], v[204:207], v[88:91]
	v_mfma_f32_16x16x32_bf16 v[76:79], v[156:159], v[212:215], v[76:79]
	v_mfma_f32_16x16x32_bf16 v[72:75], v[164:167], v[212:215], v[72:75]
	s_nop 0
	s_nop 0
	v_mfma_f32_16x16x32_bf16 v[116:119], v[168:171], v[184:187], v[116:119]
	v_mfma_f32_16x16x32_bf16 v[112:115], v[176:179], v[184:187], v[112:115]
	v_mfma_f32_16x16x32_bf16 v[100:103], v[168:171], v[192:195], v[100:103]
	v_mfma_f32_16x16x32_bf16 v[96:99], v[176:179], v[192:195], v[96:99]
	v_mfma_f32_16x16x32_bf16 v[84:87], v[168:171], v[200:203], v[84:87]
	v_mfma_f32_16x16x32_bf16 v[80:83], v[176:179], v[200:203], v[80:83]
	v_mfma_f32_16x16x32_bf16 v[68:71], v[168:171], v[208:211], v[68:71]
	v_mfma_f32_16x16x32_bf16 v[64:67], v[176:179], v[208:211], v[64:67]
	v_mfma_f32_16x16x32_bf16 v[116:119], v[172:175], v[188:191], v[116:119]
	v_mfma_f32_16x16x32_bf16 v[112:115], v[180:183], v[188:191], v[112:115]
	v_mfma_f32_16x16x32_bf16 v[100:103], v[172:175], v[196:199], v[100:103]
	v_mfma_f32_16x16x32_bf16 v[96:99], v[180:183], v[196:199], v[96:99]
	v_mfma_f32_16x16x32_bf16 v[84:87], v[172:175], v[204:207], v[84:87]
	v_mfma_f32_16x16x32_bf16 v[80:83], v[180:183], v[204:207], v[80:83]
	v_mfma_f32_16x16x32_bf16 v[68:71], v[172:175], v[212:215], v[68:71]
	v_mfma_f32_16x16x32_bf16 v[64:67], v[180:183], v[212:215], v[64:67]
	s_nop 0
	s_barrier
	s_add_i32 s58, s69, s3
	v_lshl_add_u64 v[144:145], s[36:37], 0, v[132:133]
	s_mov_b32 m0, s58
	ds_read_b128 v[184:187], v151 offset:16384
	ds_read_b128 v[188:191], v151 offset:17408
	ds_read_b128 v[192:195], v151 offset:18432
	ds_read_b128 v[196:199], v151 offset:19456
	ds_read_b128 v[200:203], v151 offset:20480
	ds_read_b128 v[204:207], v151 offset:21504
	ds_read_b128 v[208:211], v151 offset:22528
	ds_read_b128 v[212:215], v151 offset:23552
	global_load_lds_dwordx4 v[144:145], off
	s_add_i32 m0, s58, 0x2000
	s_add_u32 s82, s36, 0x40000
	v_lshl_add_u64 v[216:217], s[36:37], 0, v[128:129]
	s_addc_u32 s83, s37, 0
	s_add_i32 s58, s70, s3
	global_load_lds_dwordx4 v[216:217], off
	v_lshl_add_u64 v[218:219], s[82:83], 0, v[132:133]
	s_mov_b32 m0, s58
	v_lshl_add_u64 v[220:221], s[38:39], 0, v[130:131]
	global_load_lds_dwordx4 v[218:219], off
	v_lshl_add_u64 v[218:219], s[82:83], 0, v[128:129]
	s_add_i32 m0, s58, 0x2000
	s_nop 0
	global_load_lds_dwordx4 v[218:219], off
	v_lshl_add_u64 v[218:219], s[38:39], 0, v[134:135]
	s_mov_b32 m0, s31
	s_nop 0
	global_load_lds_dwordx4 v[218:219], off
	s_mov_b32 m0, s33
	s_nop 0
	global_load_lds_dwordx4 v[220:221], off
	s_waitcnt vmcnt(8)
	s_waitcnt lgkmcnt(0)
	s_barrier
	s_nop 0
	s_waitcnt lgkmcnt(0)
	v_mfma_f32_16x16x32_bf16 v[60:63], v[152:155], v[184:187], v[60:63]
	v_mfma_f32_16x16x32_bf16 v[56:59], v[160:163], v[184:187], v[56:59]
	v_mfma_f32_16x16x32_bf16 v[44:47], v[152:155], v[192:195], v[44:47]
	v_mfma_f32_16x16x32_bf16 v[40:43], v[160:163], v[192:195], v[40:43]
	v_mfma_f32_16x16x32_bf16 v[28:31], v[152:155], v[200:203], v[28:31]
	v_mfma_f32_16x16x32_bf16 v[24:27], v[160:163], v[200:203], v[24:27]
	v_mfma_f32_16x16x32_bf16 v[12:15], v[152:155], v[208:211], v[12:15]
	v_mfma_f32_16x16x32_bf16 v[8:11], v[160:163], v[208:211], v[8:11]
	v_mfma_f32_16x16x32_bf16 v[60:63], v[156:159], v[188:191], v[60:63]
	v_mfma_f32_16x16x32_bf16 v[56:59], v[164:167], v[188:191], v[56:59]
	v_mfma_f32_16x16x32_bf16 v[44:47], v[156:159], v[196:199], v[44:47]
	v_mfma_f32_16x16x32_bf16 v[40:43], v[164:167], v[196:199], v[40:43]
	v_mfma_f32_16x16x32_bf16 v[28:31], v[156:159], v[204:207], v[28:31]
	v_mfma_f32_16x16x32_bf16 v[24:27], v[164:167], v[204:207], v[24:27]
	v_mfma_f32_16x16x32_bf16 v[12:15], v[156:159], v[212:215], v[12:15]
	v_mfma_f32_16x16x32_bf16 v[8:11], v[164:167], v[212:215], v[8:11]
	s_nop 0
	s_nop 0
	v_mfma_f32_16x16x32_bf16 v[52:55], v[168:171], v[184:187], v[52:55]
	v_mfma_f32_16x16x32_bf16 v[48:51], v[176:179], v[184:187], v[48:51]
	v_mfma_f32_16x16x32_bf16 v[36:39], v[168:171], v[192:195], v[36:39]
	v_mfma_f32_16x16x32_bf16 v[32:35], v[176:179], v[192:195], v[32:35]
	v_mfma_f32_16x16x32_bf16 v[20:23], v[168:171], v[200:203], v[20:23]
	v_mfma_f32_16x16x32_bf16 v[16:19], v[176:179], v[200:203], v[16:19]
	v_mfma_f32_16x16x32_bf16 v[4:7], v[168:171], v[208:211], v[4:7]
	v_mfma_f32_16x16x32_bf16 v[0:3], v[176:179], v[208:211], v[0:3]
	v_mfma_f32_16x16x32_bf16 v[52:55], v[172:175], v[188:191], v[52:55]
	v_mfma_f32_16x16x32_bf16 v[48:51], v[180:183], v[188:191], v[48:51]
	v_mfma_f32_16x16x32_bf16 v[36:39], v[172:175], v[196:199], v[36:39]
	v_mfma_f32_16x16x32_bf16 v[32:35], v[180:183], v[196:199], v[32:35]
	v_mfma_f32_16x16x32_bf16 v[20:23], v[172:175], v[204:207], v[20:23]
	v_mfma_f32_16x16x32_bf16 v[16:19], v[180:183], v[204:207], v[16:19]
	v_mfma_f32_16x16x32_bf16 v[4:7], v[172:175], v[212:215], v[4:7]
	v_mfma_f32_16x16x32_bf16 v[0:3], v[180:183], v[212:215], v[0:3]
	s_nop 0
	s_barrier
	s_add_i32 s58, 0, 0x18000
	s_add_i32 s59, 0, 0x1c000
	v_add_u32_e32 v164, s58, v147
	v_add_u32_e32 v180, s59, v147
	ds_read_b128 v[152:155], v164
	ds_read_b128 v[156:159], v164 offset:1024
	ds_read_b128 v[160:163], v164 offset:2048
	ds_read_b128 v[164:167], v164 offset:3072
	ds_read_b128 v[168:171], v180
	ds_read_b128 v[172:175], v180 offset:1024
	ds_read_b128 v[176:179], v180 offset:2048
	ds_read_b128 v[180:183], v180 offset:3072
	s_add_u32 s38, s38, 0x40000
	s_addc_u32 s39, s39, 0
	s_mov_b32 m0, s42
	v_lshl_add_u64 v[222:223], s[38:39], 0, v[134:135]
	ds_read_b128 v[184:187], v151 offset:32768
	ds_read_b128 v[188:191], v151 offset:33792
	ds_read_b128 v[192:195], v151 offset:34816
	ds_read_b128 v[196:199], v151 offset:35840
	ds_read_b128 v[200:203], v151 offset:36864
	ds_read_b128 v[204:207], v151 offset:37888
	ds_read_b128 v[208:211], v151 offset:38912
	ds_read_b128 v[212:215], v151 offset:39936
	global_load_lds_dwordx4 v[222:223], off
	v_lshl_add_u64 v[222:223], s[38:39], 0, v[130:131]
	s_mov_b32 m0, s43
	s_nop 0
	global_load_lds_dwordx4 v[222:223], off
	s_waitcnt vmcnt(8)
	s_waitcnt lgkmcnt(0)
	s_barrier
	s_nop 0
	s_waitcnt lgkmcnt(0)
	v_mfma_f32_16x16x32_bf16 v[124:127], v[152:155], v[184:187], v[124:127]
	v_mfma_f32_16x16x32_bf16 v[120:123], v[160:163], v[184:187], v[120:123]
	v_mfma_f32_16x16x32_bf16 v[108:111], v[152:155], v[192:195], v[108:111]
	v_mfma_f32_16x16x32_bf16 v[104:107], v[160:163], v[192:195], v[104:107]
	v_mfma_f32_16x16x32_bf16 v[92:95], v[152:155], v[200:203], v[92:95]
	v_mfma_f32_16x16x32_bf16 v[88:91], v[160:163], v[200:203], v[88:91]
	v_mfma_f32_16x16x32_bf16 v[76:79], v[152:155], v[208:211], v[76:79]
	v_mfma_f32_16x16x32_bf16 v[72:75], v[160:163], v[208:211], v[72:75]
	v_mfma_f32_16x16x32_bf16 v[124:127], v[156:159], v[188:191], v[124:127]
	v_mfma_f32_16x16x32_bf16 v[120:123], v[164:167], v[188:191], v[120:123]
	v_mfma_f32_16x16x32_bf16 v[108:111], v[156:159], v[196:199], v[108:111]
	v_mfma_f32_16x16x32_bf16 v[104:107], v[164:167], v[196:199], v[104:107]
	v_mfma_f32_16x16x32_bf16 v[92:95], v[156:159], v[204:207], v[92:95]
	v_mfma_f32_16x16x32_bf16 v[88:91], v[164:167], v[204:207], v[88:91]
	v_mfma_f32_16x16x32_bf16 v[76:79], v[156:159], v[212:215], v[76:79]
	v_mfma_f32_16x16x32_bf16 v[72:75], v[164:167], v[212:215], v[72:75]
	s_nop 0
	s_nop 0
	v_mfma_f32_16x16x32_bf16 v[116:119], v[168:171], v[184:187], v[116:119]
	v_mfma_f32_16x16x32_bf16 v[112:115], v[176:179], v[184:187], v[112:115]
	v_mfma_f32_16x16x32_bf16 v[100:103], v[168:171], v[192:195], v[100:103]
	v_mfma_f32_16x16x32_bf16 v[96:99], v[176:179], v[192:195], v[96:99]
	v_mfma_f32_16x16x32_bf16 v[84:87], v[168:171], v[200:203], v[84:87]
	v_mfma_f32_16x16x32_bf16 v[80:83], v[176:179], v[200:203], v[80:83]
	v_mfma_f32_16x16x32_bf16 v[68:71], v[168:171], v[208:211], v[68:71]
	v_mfma_f32_16x16x32_bf16 v[64:67], v[176:179], v[208:211], v[64:67]
	v_mfma_f32_16x16x32_bf16 v[116:119], v[172:175], v[188:191], v[116:119]
	v_mfma_f32_16x16x32_bf16 v[112:115], v[180:183], v[188:191], v[112:115]
	v_mfma_f32_16x16x32_bf16 v[100:103], v[172:175], v[196:199], v[100:103]
	v_mfma_f32_16x16x32_bf16 v[96:99], v[180:183], v[196:199], v[96:99]
	v_mfma_f32_16x16x32_bf16 v[84:87], v[172:175], v[204:207], v[84:87]
	v_mfma_f32_16x16x32_bf16 v[80:83], v[180:183], v[204:207], v[80:83]
	v_mfma_f32_16x16x32_bf16 v[68:71], v[172:175], v[212:215], v[68:71]
	v_mfma_f32_16x16x32_bf16 v[64:67], v[180:183], v[212:215], v[64:67]
	s_nop 0
	s_barrier
	s_add_i32 s38, s58, s3
	v_lshl_add_u64 v[144:145], v[144:145], 0, s[10:11]
	s_mov_b32 m0, s38
	ds_read_b128 v[184:187], v151 offset:49152
	ds_read_b128 v[188:191], v151 offset:50176
	ds_read_b128 v[192:195], v151 offset:51200
	ds_read_b128 v[196:199], v151 offset:52224
	ds_read_b128 v[200:203], v151 offset:53248
	ds_read_b128 v[204:207], v151 offset:54272
	ds_read_b128 v[208:211], v151 offset:55296
	ds_read_b128 v[212:215], v151 offset:56320
	global_load_lds_dwordx4 v[144:145], off
	s_add_i32 m0, s38, 0x2000
	s_add_u32 s36, s36, 0x40080
	v_lshl_add_u64 v[144:145], v[216:217], 0, s[10:11]
	s_addc_u32 s37, s37, 0
	s_add_i32 s38, s59, s3
	global_load_lds_dwordx4 v[144:145], off
	v_lshl_add_u64 v[144:145], s[36:37], 0, v[132:133]
	s_mov_b32 m0, s38
	s_nop 0
	global_load_lds_dwordx4 v[144:145], off
	v_lshl_add_u64 v[144:145], s[36:37], 0, v[128:129]
	s_add_i32 m0, s38, 0x2000
	s_nop 0
	global_load_lds_dwordx4 v[144:145], off
	v_lshl_add_u64 v[144:145], v[218:219], 0, s[10:11]
	s_mov_b32 m0, s66
	s_nop 0
	global_load_lds_dwordx4 v[144:145], off
	v_lshl_add_u64 v[144:145], v[220:221], 0, s[10:11]
	s_mov_b32 m0, s67
	s_nop 0
	global_load_lds_dwordx4 v[144:145], off
	s_waitcnt vmcnt(8)
	s_waitcnt lgkmcnt(0)
	s_barrier
	s_nop 0
	s_waitcnt lgkmcnt(0)
	v_mfma_f32_16x16x32_bf16 v[60:63], v[152:155], v[184:187], v[60:63]
	v_mfma_f32_16x16x32_bf16 v[56:59], v[160:163], v[184:187], v[56:59]
	v_mfma_f32_16x16x32_bf16 v[44:47], v[152:155], v[192:195], v[44:47]
	v_mfma_f32_16x16x32_bf16 v[40:43], v[160:163], v[192:195], v[40:43]
	v_mfma_f32_16x16x32_bf16 v[28:31], v[152:155], v[200:203], v[28:31]
	v_mfma_f32_16x16x32_bf16 v[24:27], v[160:163], v[200:203], v[24:27]
	v_mfma_f32_16x16x32_bf16 v[12:15], v[152:155], v[208:211], v[12:15]
	v_mfma_f32_16x16x32_bf16 v[8:11], v[160:163], v[208:211], v[8:11]
	v_mfma_f32_16x16x32_bf16 v[60:63], v[156:159], v[188:191], v[60:63]
	v_mfma_f32_16x16x32_bf16 v[56:59], v[164:167], v[188:191], v[56:59]
	v_mfma_f32_16x16x32_bf16 v[44:47], v[156:159], v[196:199], v[44:47]
	v_mfma_f32_16x16x32_bf16 v[40:43], v[164:167], v[196:199], v[40:43]
	v_mfma_f32_16x16x32_bf16 v[28:31], v[156:159], v[204:207], v[28:31]
	v_mfma_f32_16x16x32_bf16 v[24:27], v[164:167], v[204:207], v[24:27]
	v_mfma_f32_16x16x32_bf16 v[12:15], v[156:159], v[212:215], v[12:15]
	v_mfma_f32_16x16x32_bf16 v[8:11], v[164:167], v[212:215], v[8:11]
	s_nop 0
	s_nop 0
	v_mfma_f32_16x16x32_bf16 v[52:55], v[168:171], v[184:187], v[52:55]
	v_mfma_f32_16x16x32_bf16 v[48:51], v[176:179], v[184:187], v[48:51]
	v_mfma_f32_16x16x32_bf16 v[36:39], v[168:171], v[192:195], v[36:39]
	v_mfma_f32_16x16x32_bf16 v[32:35], v[176:179], v[192:195], v[32:35]
	v_mfma_f32_16x16x32_bf16 v[20:23], v[168:171], v[200:203], v[20:23]
	v_mfma_f32_16x16x32_bf16 v[16:19], v[176:179], v[200:203], v[16:19]
	v_mfma_f32_16x16x32_bf16 v[4:7], v[168:171], v[208:211], v[4:7]
	v_mfma_f32_16x16x32_bf16 v[0:3], v[176:179], v[208:211], v[0:3]
	v_mfma_f32_16x16x32_bf16 v[52:55], v[172:175], v[188:191], v[52:55]
	v_mfma_f32_16x16x32_bf16 v[48:51], v[180:183], v[188:191], v[48:51]
	v_mfma_f32_16x16x32_bf16 v[36:39], v[172:175], v[196:199], v[36:39]
	v_mfma_f32_16x16x32_bf16 v[32:35], v[180:183], v[196:199], v[32:35]
	v_mfma_f32_16x16x32_bf16 v[20:23], v[172:175], v[204:207], v[20:23]
	v_mfma_f32_16x16x32_bf16 v[16:19], v[180:183], v[204:207], v[16:19]
	v_mfma_f32_16x16x32_bf16 v[4:7], v[172:175], v[212:215], v[4:7]
	v_mfma_f32_16x16x32_bf16 v[0:3], v[180:183], v[212:215], v[0:3]
	s_nop 0
	s_barrier
	s_add_i32 s80, s80, 2
	s_add_u32 s34, s34, 0x100
	s_addc_u32 s35, s35, 0
	s_add_u32 s78, s78, 0x100
	s_addc_u32 s79, s79, 0
	s_cmp_gt_u32 s80, 13
	s_cbranch_scc0 .LBB0_438
	s_and_b64 vcc, exec, s[8:9]
	s_cbranch_vccz .LBB0_441
	s_barrier

.LBB0_505:
	ds_read_b128 v[112:115], v214
	ds_read_b128 v[120:123], v214 offset:1024
	ds_read_b128 v[128:131], v214 offset:2048
	ds_read_b128 v[132:135], v214 offset:3072
	ds_read_b128 v[144:147], v215
	ds_read_b128 v[148:151], v215 offset:1024
	ds_read_b128 v[168:171], v215 offset:2048
	ds_read_b128 v[172:175], v215 offset:3072
	s_add_u32 s58, s80, 0xfff00080
	s_addc_u32 s59, s81, -1
	s_cmp_eq_u32 vcc_hi, 60
	s_cselect_b32 s85, s1, s59
	s_cselect_b32 s84, s28, s58
	s_cselect_b32 s83, s71, vcc_lo
	s_cselect_b32 s82, s73, s79
	v_lshl_add_u64 v[192:193], s[80:81], 0, v[160:161]
	s_add_i32 m0, s86, 0xc000
	ds_read_b128 v[176:179], v216
	ds_read_b128 v[180:183], v216 offset:1024
	ds_read_b128 v[184:187], v216 offset:2048
	ds_read_b128 v[188:191], v216 offset:3072
	ds_read_b128 v[222:225], v216 offset:4096
	ds_read_b128 v[226:229], v216 offset:5120
	ds_read_b128 v[230:233], v216 offset:6144
	ds_read_b128 v[234:237], v216 offset:7168
	global_load_lds_dwordx4 v[192:193], off
	v_lshl_add_u64 v[192:193], s[80:81], 0, v[162:163]
	s_add_i32 m0, s86, 0xe000
	s_nop 0
	global_load_lds_dwordx4 v[192:193], off
	s_waitcnt vmcnt(8)
	s_waitcnt lgkmcnt(0)
	s_barrier
	s_nop 0
	s_waitcnt lgkmcnt(0)
	v_mfma_f32_16x16x32_bf16 v[140:143], v[112:115], v[176:179], v[140:143]
	v_mfma_f32_16x16x32_bf16 v[136:139], v[128:131], v[176:179], v[136:139]
	v_mfma_f32_16x16x32_bf16 v[108:111], v[112:115], v[184:187], v[108:111]
	v_mfma_f32_16x16x32_bf16 v[104:107], v[128:131], v[184:187], v[104:107]
	v_mfma_f32_16x16x32_bf16 v[92:95], v[112:115], v[222:225], v[92:95]
	v_mfma_f32_16x16x32_bf16 v[88:91], v[128:131], v[222:225], v[88:91]
	v_mfma_f32_16x16x32_bf16 v[76:79], v[112:115], v[230:233], v[76:79]
	v_mfma_f32_16x16x32_bf16 v[72:75], v[128:131], v[230:233], v[72:75]
	v_mfma_f32_16x16x32_bf16 v[140:143], v[120:123], v[180:183], v[140:143]
	v_mfma_f32_16x16x32_bf16 v[136:139], v[132:135], v[180:183], v[136:139]
	v_mfma_f32_16x16x32_bf16 v[108:111], v[120:123], v[188:191], v[108:111]
	v_mfma_f32_16x16x32_bf16 v[104:107], v[132:135], v[188:191], v[104:107]
	v_mfma_f32_16x16x32_bf16 v[92:95], v[120:123], v[226:229], v[92:95]
	v_mfma_f32_16x16x32_bf16 v[88:91], v[132:135], v[226:229], v[88:91]
	v_mfma_f32_16x16x32_bf16 v[76:79], v[120:123], v[234:237], v[76:79]
	v_mfma_f32_16x16x32_bf16 v[72:75], v[132:135], v[234:237], v[72:75]
	s_nop 0
	s_nop 0
	v_mfma_f32_16x16x32_bf16 v[124:127], v[144:147], v[176:179], v[124:127]
	v_mfma_f32_16x16x32_bf16 v[116:119], v[168:171], v[176:179], v[116:119]
	v_mfma_f32_16x16x32_bf16 v[100:103], v[144:147], v[184:187], v[100:103]
	v_mfma_f32_16x16x32_bf16 v[96:99], v[168:171], v[184:187], v[96:99]
	v_mfma_f32_16x16x32_bf16 v[84:87], v[144:147], v[222:225], v[84:87]
	v_mfma_f32_16x16x32_bf16 v[80:83], v[168:171], v[222:225], v[80:83]
	v_mfma_f32_16x16x32_bf16 v[68:71], v[144:147], v[230:233], v[68:71]
	v_mfma_f32_16x16x32_bf16 v[64:67], v[168:171], v[230:233], v[64:67]
	v_mfma_f32_16x16x32_bf16 v[124:127], v[148:151], v[180:183], v[124:127]
	v_mfma_f32_16x16x32_bf16 v[116:119], v[172:175], v[180:183], v[116:119]
	v_mfma_f32_16x16x32_bf16 v[100:103], v[148:151], v[188:191], v[100:103]
	v_mfma_f32_16x16x32_bf16 v[96:99], v[172:175], v[188:191], v[96:99]
	v_mfma_f32_16x16x32_bf16 v[84:87], v[148:151], v[226:229], v[84:87]
	v_mfma_f32_16x16x32_bf16 v[80:83], v[172:175], v[226:229], v[80:83]
	v_mfma_f32_16x16x32_bf16 v[68:71], v[148:151], v[234:237], v[68:71]
	v_mfma_f32_16x16x32_bf16 v[64:67], v[172:175], v[234:237], v[64:67]
	s_nop 0
	s_barrier
	s_add_i32 s58, s33, s3
	v_lshl_add_u64 v[192:193], s[82:83], 0, v[152:153]
	s_mov_b32 m0, s58
	ds_read_b128 v[176:179], v216 offset:16384
	ds_read_b128 v[180:183], v216 offset:17408
	ds_read_b128 v[184:187], v216 offset:18432
	ds_read_b128 v[188:191], v216 offset:19456
	ds_read_b128 v[222:225], v216 offset:20480
	ds_read_b128 v[226:229], v216 offset:21504
	ds_read_b128 v[230:233], v216 offset:22528
	ds_read_b128 v[234:237], v216 offset:23552
	global_load_lds_dwordx4 v[192:193], off
	s_add_i32 m0, s58, 0x2000
	s_add_u32 s62, s82, 0x100000
	v_lshl_add_u64 v[238:239], s[82:83], 0, v[154:155]
	s_addc_u32 s63, s83, 0
	s_add_i32 s58, s90, s3
	global_load_lds_dwordx4 v[238:239], off
	v_lshl_add_u64 v[240:241], s[62:63], 0, v[152:153]
	s_mov_b32 m0, s58
	v_lshl_add_u64 v[242:243], s[84:85], 0, v[156:157]
	global_load_lds_dwordx4 v[240:241], off
	v_lshl_add_u64 v[240:241], s[62:63], 0, v[154:155]
	s_add_i32 m0, s58, 0x2000
	s_nop 0
	global_load_lds_dwordx4 v[240:241], off
	v_lshl_add_u64 v[240:241], s[84:85], 0, v[158:159]
	s_mov_b32 m0, s86
	s_nop 0
	global_load_lds_dwordx4 v[240:241], off
	s_mov_b32 m0, s87
	s_nop 0
	global_load_lds_dwordx4 v[242:243], off
	s_waitcnt vmcnt(8)
	s_waitcnt lgkmcnt(0)
	s_barrier
	s_nop 0
	s_waitcnt lgkmcnt(0)
	v_mfma_f32_16x16x32_bf16 v[60:63], v[112:115], v[176:179], v[60:63]
	v_mfma_f32_16x16x32_bf16 v[56:59], v[128:131], v[176:179], v[56:59]
	v_mfma_f32_16x16x32_bf16 v[44:47], v[112:115], v[184:187], v[44:47]
	v_mfma_f32_16x16x32_bf16 v[40:43], v[128:131], v[184:187], v[40:43]
	v_mfma_f32_16x16x32_bf16 v[28:31], v[112:115], v[222:225], v[28:31]
	v_mfma_f32_16x16x32_bf16 v[24:27], v[128:131], v[222:225], v[24:27]
	v_mfma_f32_16x16x32_bf16 v[12:15], v[112:115], v[230:233], v[12:15]
	v_mfma_f32_16x16x32_bf16 v[8:11], v[128:131], v[230:233], v[8:11]
	v_mfma_f32_16x16x32_bf16 v[60:63], v[120:123], v[180:183], v[60:63]
	v_mfma_f32_16x16x32_bf16 v[56:59], v[132:135], v[180:183], v[56:59]
	v_mfma_f32_16x16x32_bf16 v[44:47], v[120:123], v[188:191], v[44:47]
	v_mfma_f32_16x16x32_bf16 v[40:43], v[132:135], v[188:191], v[40:43]
	v_mfma_f32_16x16x32_bf16 v[28:31], v[120:123], v[226:229], v[28:31]
	v_mfma_f32_16x16x32_bf16 v[24:27], v[132:135], v[226:229], v[24:27]
	v_mfma_f32_16x16x32_bf16 v[12:15], v[120:123], v[234:237], v[12:15]
	v_mfma_f32_16x16x32_bf16 v[8:11], v[132:135], v[234:237], v[8:11]
	s_nop 0
	s_nop 0
	v_mfma_f32_16x16x32_bf16 v[52:55], v[144:147], v[176:179], v[52:55]
	v_mfma_f32_16x16x32_bf16 v[48:51], v[168:171], v[176:179], v[48:51]
	v_mfma_f32_16x16x32_bf16 v[36:39], v[144:147], v[184:187], v[36:39]
	v_mfma_f32_16x16x32_bf16 v[32:35], v[168:171], v[184:187], v[32:35]
	v_mfma_f32_16x16x32_bf16 v[20:23], v[144:147], v[222:225], v[20:23]
	v_mfma_f32_16x16x32_bf16 v[16:19], v[168:171], v[222:225], v[16:19]
	v_mfma_f32_16x16x32_bf16 v[4:7], v[144:147], v[230:233], v[4:7]
	v_mfma_f32_16x16x32_bf16 v[0:3], v[168:171], v[230:233], v[0:3]
	v_mfma_f32_16x16x32_bf16 v[52:55], v[148:151], v[180:183], v[52:55]
	v_mfma_f32_16x16x32_bf16 v[48:51], v[172:175], v[180:183], v[48:51]
	v_mfma_f32_16x16x32_bf16 v[36:39], v[148:151], v[188:191], v[36:39]
	v_mfma_f32_16x16x32_bf16 v[32:35], v[172:175], v[188:191], v[32:35]
	v_mfma_f32_16x16x32_bf16 v[20:23], v[148:151], v[226:229], v[20:23]
	v_mfma_f32_16x16x32_bf16 v[16:19], v[172:175], v[226:229], v[16:19]
	v_mfma_f32_16x16x32_bf16 v[4:7], v[148:151], v[234:237], v[4:7]
	v_mfma_f32_16x16x32_bf16 v[0:3], v[172:175], v[234:237], v[0:3]
	s_nop 0
	s_barrier
	s_add_i32 s58, 0, 0x18000
	s_add_i32 s59, 0, 0x1c000
	v_add_u32_e32 v132, s58, v195
	v_add_u32_e32 v172, s59, v195
	ds_read_b128 v[112:115], v132
	ds_read_b128 v[120:123], v132 offset:1024
	ds_read_b128 v[128:131], v132 offset:2048
	ds_read_b128 v[132:135], v132 offset:3072
	ds_read_b128 v[144:147], v172
	ds_read_b128 v[148:151], v172 offset:1024
	ds_read_b128 v[168:171], v172 offset:2048
	ds_read_b128 v[172:175], v172 offset:3072
	s_add_u32 s62, s84, 0x100000
	s_addc_u32 s63, s85, 0
	s_mov_b32 m0, s88
	v_lshl_add_u64 v[244:245], s[62:63], 0, v[158:159]
	ds_read_b128 v[176:179], v216 offset:32768
	ds_read_b128 v[180:183], v216 offset:33792
	ds_read_b128 v[184:187], v216 offset:34816
	ds_read_b128 v[188:191], v216 offset:35840
	ds_read_b128 v[222:225], v216 offset:36864
	ds_read_b128 v[226:229], v216 offset:37888
	ds_read_b128 v[230:233], v216 offset:38912
	ds_read_b128 v[234:237], v216 offset:39936
	global_load_lds_dwordx4 v[244:245], off
	v_lshl_add_u64 v[244:245], s[62:63], 0, v[156:157]
	s_mov_b32 m0, s89
	s_nop 0
	global_load_lds_dwordx4 v[244:245], off
	s_waitcnt vmcnt(8)
	s_waitcnt lgkmcnt(0)
	s_barrier
	s_nop 0
	s_waitcnt lgkmcnt(0)
	v_mfma_f32_16x16x32_bf16 v[140:143], v[112:115], v[176:179], v[140:143]
	v_mfma_f32_16x16x32_bf16 v[136:139], v[128:131], v[176:179], v[136:139]
	v_mfma_f32_16x16x32_bf16 v[108:111], v[112:115], v[184:187], v[108:111]
	v_mfma_f32_16x16x32_bf16 v[104:107], v[128:131], v[184:187], v[104:107]
	v_mfma_f32_16x16x32_bf16 v[92:95], v[112:115], v[222:225], v[92:95]
	v_mfma_f32_16x16x32_bf16 v[88:91], v[128:131], v[222:225], v[88:91]
	v_mfma_f32_16x16x32_bf16 v[76:79], v[112:115], v[230:233], v[76:79]
	v_mfma_f32_16x16x32_bf16 v[72:75], v[128:131], v[230:233], v[72:75]
	v_mfma_f32_16x16x32_bf16 v[140:143], v[120:123], v[180:183], v[140:143]
	v_mfma_f32_16x16x32_bf16 v[136:139], v[132:135], v[180:183], v[136:139]
	v_mfma_f32_16x16x32_bf16 v[108:111], v[120:123], v[188:191], v[108:111]
	v_mfma_f32_16x16x32_bf16 v[104:107], v[132:135], v[188:191], v[104:107]
	v_mfma_f32_16x16x32_bf16 v[92:95], v[120:123], v[226:229], v[92:95]
	v_mfma_f32_16x16x32_bf16 v[88:91], v[132:135], v[226:229], v[88:91]
	v_mfma_f32_16x16x32_bf16 v[76:79], v[120:123], v[234:237], v[76:79]
	v_mfma_f32_16x16x32_bf16 v[72:75], v[132:135], v[234:237], v[72:75]
	s_nop 0
	s_nop 0
	v_mfma_f32_16x16x32_bf16 v[124:127], v[144:147], v[176:179], v[124:127]
	v_mfma_f32_16x16x32_bf16 v[116:119], v[168:171], v[176:179], v[116:119]
	v_mfma_f32_16x16x32_bf16 v[100:103], v[144:147], v[184:187], v[100:103]
	v_mfma_f32_16x16x32_bf16 v[96:99], v[168:171], v[184:187], v[96:99]
	v_mfma_f32_16x16x32_bf16 v[84:87], v[144:147], v[222:225], v[84:87]
	v_mfma_f32_16x16x32_bf16 v[80:83], v[168:171], v[222:225], v[80:83]
	v_mfma_f32_16x16x32_bf16 v[68:71], v[144:147], v[230:233], v[68:71]
	v_mfma_f32_16x16x32_bf16 v[64:67], v[168:171], v[230:233], v[64:67]
	v_mfma_f32_16x16x32_bf16 v[124:127], v[148:151], v[180:183], v[124:127]
	v_mfma_f32_16x16x32_bf16 v[116:119], v[172:175], v[180:183], v[116:119]
	v_mfma_f32_16x16x32_bf16 v[100:103], v[148:151], v[188:191], v[100:103]
	v_mfma_f32_16x16x32_bf16 v[96:99], v[172:175], v[188:191], v[96:99]
	v_mfma_f32_16x16x32_bf16 v[84:87], v[148:151], v[226:229], v[84:87]
	v_mfma_f32_16x16x32_bf16 v[80:83], v[172:175], v[226:229], v[80:83]
	v_mfma_f32_16x16x32_bf16 v[68:71], v[148:151], v[234:237], v[68:71]
	v_mfma_f32_16x16x32_bf16 v[64:67], v[172:175], v[234:237], v[64:67]
	s_nop 0
	s_barrier
	s_add_i32 s58, s58, s3
	v_lshl_add_u64 v[192:193], v[192:193], 0, s[68:69]
	s_mov_b32 m0, s58
	ds_read_b128 v[176:179], v216 offset:49152
	ds_read_b128 v[180:183], v216 offset:50176
	ds_read_b128 v[184:187], v216 offset:51200
	ds_read_b128 v[188:191], v216 offset:52224
	ds_read_b128 v[222:225], v216 offset:53248
	ds_read_b128 v[226:229], v216 offset:54272
	ds_read_b128 v[230:233], v216 offset:55296
	ds_read_b128 v[234:237], v216 offset:56320
	global_load_lds_dwordx4 v[192:193], off
	s_add_i32 m0, s58, 0x2000
	s_add_u32 s62, s82, 0x100080
	v_lshl_add_u64 v[192:193], v[238:239], 0, s[68:69]
	s_addc_u32 s63, s83, 0
	s_add_i32 s58, s59, s3
	global_load_lds_dwordx4 v[192:193], off
	v_lshl_add_u64 v[192:193], s[62:63], 0, v[152:153]
	s_mov_b32 m0, s58
	s_nop 0
	global_load_lds_dwordx4 v[192:193], off
	v_lshl_add_u64 v[192:193], s[62:63], 0, v[154:155]
	s_add_i32 m0, s58, 0x2000
	s_nop 0
	global_load_lds_dwordx4 v[192:193], off
	v_lshl_add_u64 v[192:193], v[240:241], 0, s[68:69]
	s_mov_b32 m0, s43
	s_nop 0
	global_load_lds_dwordx4 v[192:193], off
	v_lshl_add_u64 v[192:193], v[242:243], 0, s[68:69]
	s_mov_b32 m0, s34
	s_nop 0
	global_load_lds_dwordx4 v[192:193], off
	s_waitcnt vmcnt(8)
	s_waitcnt lgkmcnt(0)
	s_barrier
	s_nop 0
	s_waitcnt lgkmcnt(0)
	v_mfma_f32_16x16x32_bf16 v[60:63], v[112:115], v[176:179], v[60:63]
	v_mfma_f32_16x16x32_bf16 v[56:59], v[128:131], v[176:179], v[56:59]
	v_mfma_f32_16x16x32_bf16 v[44:47], v[112:115], v[184:187], v[44:47]
	v_mfma_f32_16x16x32_bf16 v[40:43], v[128:131], v[184:187], v[40:43]
	v_mfma_f32_16x16x32_bf16 v[28:31], v[112:115], v[222:225], v[28:31]
	v_mfma_f32_16x16x32_bf16 v[24:27], v[128:131], v[222:225], v[24:27]
	v_mfma_f32_16x16x32_bf16 v[12:15], v[112:115], v[230:233], v[12:15]
	v_mfma_f32_16x16x32_bf16 v[8:11], v[128:131], v[230:233], v[8:11]
	v_mfma_f32_16x16x32_bf16 v[60:63], v[120:123], v[180:183], v[60:63]
	v_mfma_f32_16x16x32_bf16 v[56:59], v[132:135], v[180:183], v[56:59]
	v_mfma_f32_16x16x32_bf16 v[44:47], v[120:123], v[188:191], v[44:47]
	v_mfma_f32_16x16x32_bf16 v[40:43], v[132:135], v[188:191], v[40:43]
	v_mfma_f32_16x16x32_bf16 v[28:31], v[120:123], v[226:229], v[28:31]
	v_mfma_f32_16x16x32_bf16 v[24:27], v[132:135], v[226:229], v[24:27]
	v_mfma_f32_16x16x32_bf16 v[12:15], v[120:123], v[234:237], v[12:15]
	v_mfma_f32_16x16x32_bf16 v[8:11], v[132:135], v[234:237], v[8:11]
	s_nop 0
	s_nop 0
	v_mfma_f32_16x16x32_bf16 v[52:55], v[144:147], v[176:179], v[52:55]
	v_mfma_f32_16x16x32_bf16 v[48:51], v[168:171], v[176:179], v[48:51]
	v_mfma_f32_16x16x32_bf16 v[36:39], v[144:147], v[184:187], v[36:39]
	v_mfma_f32_16x16x32_bf16 v[32:35], v[168:171], v[184:187], v[32:35]
	v_mfma_f32_16x16x32_bf16 v[20:23], v[144:147], v[222:225], v[20:23]
	v_mfma_f32_16x16x32_bf16 v[16:19], v[168:171], v[222:225], v[16:19]
	v_mfma_f32_16x16x32_bf16 v[4:7], v[144:147], v[230:233], v[4:7]
	v_mfma_f32_16x16x32_bf16 v[0:3], v[168:171], v[230:233], v[0:3]
	v_mfma_f32_16x16x32_bf16 v[52:55], v[148:151], v[180:183], v[52:55]
	v_mfma_f32_16x16x32_bf16 v[48:51], v[172:175], v[180:183], v[48:51]
	v_mfma_f32_16x16x32_bf16 v[36:39], v[148:151], v[188:191], v[36:39]
	v_mfma_f32_16x16x32_bf16 v[32:35], v[172:175], v[188:191], v[32:35]
	v_mfma_f32_16x16x32_bf16 v[20:23], v[148:151], v[226:229], v[20:23]
	v_mfma_f32_16x16x32_bf16 v[16:19], v[172:175], v[226:229], v[16:19]
	v_mfma_f32_16x16x32_bf16 v[4:7], v[148:151], v[234:237], v[4:7]
	v_mfma_f32_16x16x32_bf16 v[0:3], v[172:175], v[234:237], v[0:3]
	s_nop 0
	s_barrier
	s_add_i32 vcc_hi, vcc_hi, 2
	s_add_u32 s80, s80, 0x100
	s_addc_u32 s81, s81, 0
	s_add_u32 s79, s79, 0x100
	s_addc_u32 vcc_lo, vcc_lo, 0
	s_cmp_gt_u32 vcc_hi, 61
	s_cbranch_scc0 .LBB0_505
	s_and_b64 vcc, exec, s[60:61]
	s_cbranch_vccz .LBB0_508
	s_barrier

.LBB0_634:
	ds_read_b128 v[128:131], v159
	ds_read_b128 v[152:155], v159 offset:1024
	ds_read_b128 v[162:165], v159 offset:2048
	ds_read_b128 v[166:169], v159 offset:3072
	ds_read_b128 v[170:173], v160
	ds_read_b128 v[174:177], v160 offset:1024
	ds_read_b128 v[178:181], v160 offset:2048
	ds_read_b128 v[182:185], v160 offset:3072
	s_add_u32 s58, s70, 0xfffc0080
	s_addc_u32 s59, s71, -1
	s_cmp_eq_u32 s89, 12
	s_cselect_b32 s75, s1, s59
	s_cselect_b32 s74, s9, s58
	s_cselect_b32 s73, s63, s88
	s_cselect_b32 s72, s65, s87
	v_lshl_add_u64 v[218:219], s[70:71], 0, v[144:145]
	s_add_i32 m0, s34, 0xc000
	ds_read_b128 v[186:189], v161
	ds_read_b128 v[190:193], v161 offset:1024
	ds_read_b128 v[194:197], v161 offset:2048
	ds_read_b128 v[198:201], v161 offset:3072
	ds_read_b128 v[202:205], v161 offset:4096
	ds_read_b128 v[206:209], v161 offset:5120
	ds_read_b128 v[210:213], v161 offset:6144
	ds_read_b128 v[214:217], v161 offset:7168
	global_load_lds_dwordx4 v[218:219], off
	v_lshl_add_u64 v[218:219], s[70:71], 0, v[146:147]
	s_add_i32 m0, s34, 0xe000
	s_nop 0
	global_load_lds_dwordx4 v[218:219], off
	s_waitcnt vmcnt(8)
	s_waitcnt lgkmcnt(0)
	s_barrier
	s_nop 0
	s_waitcnt lgkmcnt(0)
	v_mfma_f32_16x16x32_bf16 v[124:127], v[128:131], v[186:189], v[124:127]
	v_mfma_f32_16x16x32_bf16 v[120:123], v[162:165], v[186:189], v[120:123]
	v_mfma_f32_16x16x32_bf16 v[108:111], v[128:131], v[194:197], v[108:111]
	v_mfma_f32_16x16x32_bf16 v[104:107], v[162:165], v[194:197], v[104:107]
	v_mfma_f32_16x16x32_bf16 v[92:95], v[128:131], v[202:205], v[92:95]
	v_mfma_f32_16x16x32_bf16 v[88:91], v[162:165], v[202:205], v[88:91]
	v_mfma_f32_16x16x32_bf16 v[76:79], v[128:131], v[210:213], v[76:79]
	v_mfma_f32_16x16x32_bf16 v[72:75], v[162:165], v[210:213], v[72:75]
	v_mfma_f32_16x16x32_bf16 v[124:127], v[152:155], v[190:193], v[124:127]
	v_mfma_f32_16x16x32_bf16 v[120:123], v[166:169], v[190:193], v[120:123]
	v_mfma_f32_16x16x32_bf16 v[108:111], v[152:155], v[198:201], v[108:111]
	v_mfma_f32_16x16x32_bf16 v[104:107], v[166:169], v[198:201], v[104:107]
	v_mfma_f32_16x16x32_bf16 v[92:95], v[152:155], v[206:209], v[92:95]
	v_mfma_f32_16x16x32_bf16 v[88:91], v[166:169], v[206:209], v[88:91]
	v_mfma_f32_16x16x32_bf16 v[76:79], v[152:155], v[214:217], v[76:79]
	v_mfma_f32_16x16x32_bf16 v[72:75], v[166:169], v[214:217], v[72:75]
	s_nop 0
	s_nop 0
	v_mfma_f32_16x16x32_bf16 v[116:119], v[170:173], v[186:189], v[116:119]
	v_mfma_f32_16x16x32_bf16 v[112:115], v[178:181], v[186:189], v[112:115]
	v_mfma_f32_16x16x32_bf16 v[100:103], v[170:173], v[194:197], v[100:103]
	v_mfma_f32_16x16x32_bf16 v[96:99], v[178:181], v[194:197], v[96:99]
	v_mfma_f32_16x16x32_bf16 v[84:87], v[170:173], v[202:205], v[84:87]
	v_mfma_f32_16x16x32_bf16 v[80:83], v[178:181], v[202:205], v[80:83]
	v_mfma_f32_16x16x32_bf16 v[68:71], v[170:173], v[210:213], v[68:71]
	v_mfma_f32_16x16x32_bf16 v[64:67], v[178:181], v[210:213], v[64:67]
	v_mfma_f32_16x16x32_bf16 v[116:119], v[174:177], v[190:193], v[116:119]
	v_mfma_f32_16x16x32_bf16 v[112:115], v[182:185], v[190:193], v[112:115]
	v_mfma_f32_16x16x32_bf16 v[100:103], v[174:177], v[198:201], v[100:103]
	v_mfma_f32_16x16x32_bf16 v[96:99], v[182:185], v[198:201], v[96:99]
	v_mfma_f32_16x16x32_bf16 v[84:87], v[174:177], v[206:209], v[84:87]
	v_mfma_f32_16x16x32_bf16 v[80:83], v[182:185], v[206:209], v[80:83]
	v_mfma_f32_16x16x32_bf16 v[68:71], v[174:177], v[214:217], v[68:71]
	v_mfma_f32_16x16x32_bf16 v[64:67], v[182:185], v[214:217], v[64:67]
	s_nop 0
	s_barrier
	s_add_i32 s58, s82, s3
	v_lshl_add_u64 v[218:219], s[72:73], 0, v[134:135]
	s_mov_b32 m0, s58
	ds_read_b128 v[186:189], v161 offset:16384
	ds_read_b128 v[190:193], v161 offset:17408
	ds_read_b128 v[194:197], v161 offset:18432
	ds_read_b128 v[198:201], v161 offset:19456
	ds_read_b128 v[202:205], v161 offset:20480
	ds_read_b128 v[206:209], v161 offset:21504
	ds_read_b128 v[210:213], v161 offset:22528
	ds_read_b128 v[214:217], v161 offset:23552
	global_load_lds_dwordx4 v[218:219], off
	s_add_i32 m0, s58, 0x2000
	s_add_u32 s90, s72, 0x40000
	v_lshl_add_u64 v[220:221], s[72:73], 0, v[138:139]
	s_addc_u32 s91, s73, 0
	s_add_i32 s58, s83, s3
	global_load_lds_dwordx4 v[220:221], off
	v_lshl_add_u64 v[222:223], s[90:91], 0, v[134:135]
	s_mov_b32 m0, s58
	v_lshl_add_u64 v[224:225], s[74:75], 0, v[136:137]
	global_load_lds_dwordx4 v[222:223], off
	v_lshl_add_u64 v[222:223], s[90:91], 0, v[138:139]
	s_add_i32 m0, s58, 0x2000
	s_nop 0
	global_load_lds_dwordx4 v[222:223], off
	v_lshl_add_u64 v[222:223], s[74:75], 0, v[132:133]
	s_mov_b32 m0, s34
	s_nop 0
	global_load_lds_dwordx4 v[222:223], off
	s_mov_b32 m0, s35
	s_nop 0
	global_load_lds_dwordx4 v[224:225], off
	s_waitcnt vmcnt(8)
	s_waitcnt lgkmcnt(0)
	s_barrier
	s_nop 0
	s_waitcnt lgkmcnt(0)
	v_mfma_f32_16x16x32_bf16 v[60:63], v[128:131], v[186:189], v[60:63]
	v_mfma_f32_16x16x32_bf16 v[56:59], v[162:165], v[186:189], v[56:59]
	v_mfma_f32_16x16x32_bf16 v[44:47], v[128:131], v[194:197], v[44:47]
	v_mfma_f32_16x16x32_bf16 v[40:43], v[162:165], v[194:197], v[40:43]
	v_mfma_f32_16x16x32_bf16 v[28:31], v[128:131], v[202:205], v[28:31]
	v_mfma_f32_16x16x32_bf16 v[24:27], v[162:165], v[202:205], v[24:27]
	v_mfma_f32_16x16x32_bf16 v[12:15], v[128:131], v[210:213], v[12:15]
	v_mfma_f32_16x16x32_bf16 v[8:11], v[162:165], v[210:213], v[8:11]
	v_mfma_f32_16x16x32_bf16 v[60:63], v[152:155], v[190:193], v[60:63]
	v_mfma_f32_16x16x32_bf16 v[56:59], v[166:169], v[190:193], v[56:59]
	v_mfma_f32_16x16x32_bf16 v[44:47], v[152:155], v[198:201], v[44:47]
	v_mfma_f32_16x16x32_bf16 v[40:43], v[166:169], v[198:201], v[40:43]
	v_mfma_f32_16x16x32_bf16 v[28:31], v[152:155], v[206:209], v[28:31]
	v_mfma_f32_16x16x32_bf16 v[24:27], v[166:169], v[206:209], v[24:27]
	v_mfma_f32_16x16x32_bf16 v[12:15], v[152:155], v[214:217], v[12:15]
	v_mfma_f32_16x16x32_bf16 v[8:11], v[166:169], v[214:217], v[8:11]
	s_nop 0
	s_nop 0
	v_mfma_f32_16x16x32_bf16 v[52:55], v[170:173], v[186:189], v[52:55]
	v_mfma_f32_16x16x32_bf16 v[48:51], v[178:181], v[186:189], v[48:51]
	v_mfma_f32_16x16x32_bf16 v[36:39], v[170:173], v[194:197], v[36:39]
	v_mfma_f32_16x16x32_bf16 v[32:35], v[178:181], v[194:197], v[32:35]
	v_mfma_f32_16x16x32_bf16 v[20:23], v[170:173], v[202:205], v[20:23]
	v_mfma_f32_16x16x32_bf16 v[16:19], v[178:181], v[202:205], v[16:19]
	v_mfma_f32_16x16x32_bf16 v[4:7], v[170:173], v[210:213], v[4:7]
	v_mfma_f32_16x16x32_bf16 v[0:3], v[178:181], v[210:213], v[0:3]
	v_mfma_f32_16x16x32_bf16 v[52:55], v[174:177], v[190:193], v[52:55]
	v_mfma_f32_16x16x32_bf16 v[48:51], v[182:185], v[190:193], v[48:51]
	v_mfma_f32_16x16x32_bf16 v[36:39], v[174:177], v[198:201], v[36:39]
	v_mfma_f32_16x16x32_bf16 v[32:35], v[182:185], v[198:201], v[32:35]
	v_mfma_f32_16x16x32_bf16 v[20:23], v[174:177], v[206:209], v[20:23]
	v_mfma_f32_16x16x32_bf16 v[16:19], v[182:185], v[206:209], v[16:19]
	v_mfma_f32_16x16x32_bf16 v[4:7], v[174:177], v[214:217], v[4:7]
	v_mfma_f32_16x16x32_bf16 v[0:3], v[182:185], v[214:217], v[0:3]
	s_nop 0
	s_barrier
	s_add_i32 s58, 0, 0x18000
	s_add_i32 s59, 0, 0x1c000
	v_add_u32_e32 v166, s58, v157
	v_add_u32_e32 v182, s59, v157
	ds_read_b128 v[128:131], v166
	ds_read_b128 v[152:155], v166 offset:1024
	ds_read_b128 v[162:165], v166 offset:2048
	ds_read_b128 v[166:169], v166 offset:3072
	ds_read_b128 v[170:173], v182
	ds_read_b128 v[174:177], v182 offset:1024
	ds_read_b128 v[178:181], v182 offset:2048
	ds_read_b128 v[182:185], v182 offset:3072
	s_add_u32 s74, s74, 0x40000
	s_addc_u32 s75, s75, 0
	s_mov_b32 m0, s42
	v_lshl_add_u64 v[226:227], s[74:75], 0, v[132:133]
	ds_read_b128 v[186:189], v161 offset:32768
	ds_read_b128 v[190:193], v161 offset:33792
	ds_read_b128 v[194:197], v161 offset:34816
	ds_read_b128 v[198:201], v161 offset:35840
	ds_read_b128 v[202:205], v161 offset:36864
	ds_read_b128 v[206:209], v161 offset:37888
	ds_read_b128 v[210:213], v161 offset:38912
	ds_read_b128 v[214:217], v161 offset:39936
	global_load_lds_dwordx4 v[226:227], off
	v_lshl_add_u64 v[226:227], s[74:75], 0, v[136:137]
	s_mov_b32 m0, s43
	s_nop 0
	global_load_lds_dwordx4 v[226:227], off
	s_waitcnt vmcnt(8)
	s_waitcnt lgkmcnt(0)
	s_barrier
	s_nop 0
	s_waitcnt lgkmcnt(0)
	v_mfma_f32_16x16x32_bf16 v[124:127], v[128:131], v[186:189], v[124:127]
	v_mfma_f32_16x16x32_bf16 v[120:123], v[162:165], v[186:189], v[120:123]
	v_mfma_f32_16x16x32_bf16 v[108:111], v[128:131], v[194:197], v[108:111]
	v_mfma_f32_16x16x32_bf16 v[104:107], v[162:165], v[194:197], v[104:107]
	v_mfma_f32_16x16x32_bf16 v[92:95], v[128:131], v[202:205], v[92:95]
	v_mfma_f32_16x16x32_bf16 v[88:91], v[162:165], v[202:205], v[88:91]
	v_mfma_f32_16x16x32_bf16 v[76:79], v[128:131], v[210:213], v[76:79]
	v_mfma_f32_16x16x32_bf16 v[72:75], v[162:165], v[210:213], v[72:75]
	v_mfma_f32_16x16x32_bf16 v[124:127], v[152:155], v[190:193], v[124:127]
	v_mfma_f32_16x16x32_bf16 v[120:123], v[166:169], v[190:193], v[120:123]
	v_mfma_f32_16x16x32_bf16 v[108:111], v[152:155], v[198:201], v[108:111]
	v_mfma_f32_16x16x32_bf16 v[104:107], v[166:169], v[198:201], v[104:107]
	v_mfma_f32_16x16x32_bf16 v[92:95], v[152:155], v[206:209], v[92:95]
	v_mfma_f32_16x16x32_bf16 v[88:91], v[166:169], v[206:209], v[88:91]
	v_mfma_f32_16x16x32_bf16 v[76:79], v[152:155], v[214:217], v[76:79]
	v_mfma_f32_16x16x32_bf16 v[72:75], v[166:169], v[214:217], v[72:75]
	s_nop 0
	s_nop 0
	v_mfma_f32_16x16x32_bf16 v[116:119], v[170:173], v[186:189], v[116:119]
	v_mfma_f32_16x16x32_bf16 v[112:115], v[178:181], v[186:189], v[112:115]
	v_mfma_f32_16x16x32_bf16 v[100:103], v[170:173], v[194:197], v[100:103]
	v_mfma_f32_16x16x32_bf16 v[96:99], v[178:181], v[194:197], v[96:99]
	v_mfma_f32_16x16x32_bf16 v[84:87], v[170:173], v[202:205], v[84:87]
	v_mfma_f32_16x16x32_bf16 v[80:83], v[178:181], v[202:205], v[80:83]
	v_mfma_f32_16x16x32_bf16 v[68:71], v[170:173], v[210:213], v[68:71]
	v_mfma_f32_16x16x32_bf16 v[64:67], v[178:181], v[210:213], v[64:67]
	v_mfma_f32_16x16x32_bf16 v[116:119], v[174:177], v[190:193], v[116:119]
	v_mfma_f32_16x16x32_bf16 v[112:115], v[182:185], v[190:193], v[112:115]
	v_mfma_f32_16x16x32_bf16 v[100:103], v[174:177], v[198:201], v[100:103]
	v_mfma_f32_16x16x32_bf16 v[96:99], v[182:185], v[198:201], v[96:99]
	v_mfma_f32_16x16x32_bf16 v[84:87], v[174:177], v[206:209], v[84:87]
	v_mfma_f32_16x16x32_bf16 v[80:83], v[182:185], v[206:209], v[80:83]
	v_mfma_f32_16x16x32_bf16 v[68:71], v[174:177], v[214:217], v[68:71]
	v_mfma_f32_16x16x32_bf16 v[64:67], v[182:185], v[214:217], v[64:67]
	s_nop 0
	s_barrier
	s_add_i32 s58, s58, s3
	v_lshl_add_u64 v[218:219], v[218:219], 0, s[60:61]
	s_mov_b32 m0, s58
	ds_read_b128 v[186:189], v161 offset:49152
	ds_read_b128 v[190:193], v161 offset:50176
	ds_read_b128 v[194:197], v161 offset:51200
	ds_read_b128 v[198:201], v161 offset:52224
	ds_read_b128 v[202:205], v161 offset:53248
	ds_read_b128 v[206:209], v161 offset:54272
	ds_read_b128 v[210:213], v161 offset:55296
	ds_read_b128 v[214:217], v161 offset:56320
	global_load_lds_dwordx4 v[218:219], off
	s_add_i32 m0, s58, 0x2000
	s_add_u32 s72, s72, 0x40080
	v_lshl_add_u64 v[218:219], v[220:221], 0, s[60:61]
	s_addc_u32 s73, s73, 0
	s_add_i32 s58, s59, s3
	global_load_lds_dwordx4 v[218:219], off
	v_lshl_add_u64 v[218:219], s[72:73], 0, v[134:135]
	s_mov_b32 m0, s58
	s_nop 0
	global_load_lds_dwordx4 v[218:219], off
	v_lshl_add_u64 v[218:219], s[72:73], 0, v[138:139]
	s_add_i32 m0, s58, 0x2000
	s_nop 0
	global_load_lds_dwordx4 v[218:219], off
	v_lshl_add_u64 v[218:219], v[222:223], 0, s[60:61]
	s_mov_b32 m0, s80
	s_nop 0
	global_load_lds_dwordx4 v[218:219], off
	v_lshl_add_u64 v[218:219], v[224:225], 0, s[60:61]
	s_mov_b32 m0, s81
	s_nop 0
	global_load_lds_dwordx4 v[218:219], off
	s_waitcnt vmcnt(8)
	s_waitcnt lgkmcnt(0)
	s_barrier
	s_nop 0
	s_waitcnt lgkmcnt(0)
	v_mfma_f32_16x16x32_bf16 v[60:63], v[128:131], v[186:189], v[60:63]
	v_mfma_f32_16x16x32_bf16 v[56:59], v[162:165], v[186:189], v[56:59]
	v_mfma_f32_16x16x32_bf16 v[44:47], v[128:131], v[194:197], v[44:47]
	v_mfma_f32_16x16x32_bf16 v[40:43], v[162:165], v[194:197], v[40:43]
	v_mfma_f32_16x16x32_bf16 v[28:31], v[128:131], v[202:205], v[28:31]
	v_mfma_f32_16x16x32_bf16 v[24:27], v[162:165], v[202:205], v[24:27]
	v_mfma_f32_16x16x32_bf16 v[12:15], v[128:131], v[210:213], v[12:15]
	v_mfma_f32_16x16x32_bf16 v[8:11], v[162:165], v[210:213], v[8:11]
	v_mfma_f32_16x16x32_bf16 v[60:63], v[152:155], v[190:193], v[60:63]
	v_mfma_f32_16x16x32_bf16 v[56:59], v[166:169], v[190:193], v[56:59]
	v_mfma_f32_16x16x32_bf16 v[44:47], v[152:155], v[198:201], v[44:47]
	v_mfma_f32_16x16x32_bf16 v[40:43], v[166:169], v[198:201], v[40:43]
	v_mfma_f32_16x16x32_bf16 v[28:31], v[152:155], v[206:209], v[28:31]
	v_mfma_f32_16x16x32_bf16 v[24:27], v[166:169], v[206:209], v[24:27]
	v_mfma_f32_16x16x32_bf16 v[12:15], v[152:155], v[214:217], v[12:15]
	v_mfma_f32_16x16x32_bf16 v[8:11], v[166:169], v[214:217], v[8:11]
	s_nop 0
	s_nop 0
	v_mfma_f32_16x16x32_bf16 v[52:55], v[170:173], v[186:189], v[52:55]
	v_mfma_f32_16x16x32_bf16 v[48:51], v[178:181], v[186:189], v[48:51]
	v_mfma_f32_16x16x32_bf16 v[36:39], v[170:173], v[194:197], v[36:39]
	v_mfma_f32_16x16x32_bf16 v[32:35], v[178:181], v[194:197], v[32:35]
	v_mfma_f32_16x16x32_bf16 v[20:23], v[170:173], v[202:205], v[20:23]
	v_mfma_f32_16x16x32_bf16 v[16:19], v[178:181], v[202:205], v[16:19]
	v_mfma_f32_16x16x32_bf16 v[4:7], v[170:173], v[210:213], v[4:7]
	v_mfma_f32_16x16x32_bf16 v[0:3], v[178:181], v[210:213], v[0:3]
	v_mfma_f32_16x16x32_bf16 v[52:55], v[174:177], v[190:193], v[52:55]
	v_mfma_f32_16x16x32_bf16 v[48:51], v[182:185], v[190:193], v[48:51]
	v_mfma_f32_16x16x32_bf16 v[36:39], v[174:177], v[198:201], v[36:39]
	v_mfma_f32_16x16x32_bf16 v[32:35], v[182:185], v[198:201], v[32:35]
	v_mfma_f32_16x16x32_bf16 v[20:23], v[174:177], v[206:209], v[20:23]
	v_mfma_f32_16x16x32_bf16 v[16:19], v[182:185], v[206:209], v[16:19]
	v_mfma_f32_16x16x32_bf16 v[4:7], v[174:177], v[214:217], v[4:7]
	v_mfma_f32_16x16x32_bf16 v[0:3], v[182:185], v[214:217], v[0:3]
	s_nop 0
	s_barrier
	s_add_i32 s89, s89, 2
	s_add_u32 s70, s70, 0x100
	s_addc_u32 s71, s71, 0
	s_add_u32 s87, s87, 0x100
	s_addc_u32 s88, s88, 0
	s_cmp_gt_u32 s89, 13
	s_cbranch_scc0 .LBB0_634
	s_and_b64 vcc, exec, s[22:23]
	s_cbranch_vccz .LBB0_637
	s_barrier

.LBB0_749:
	ds_read_b128 v[128:131], v167
	ds_read_b128 v[170:173], v167 offset:1024
	ds_read_b128 v[174:177], v167 offset:2048
	ds_read_b128 v[178:181], v167 offset:3072
	ds_read_b128 v[182:185], v168
	ds_read_b128 v[186:189], v168 offset:1024
	ds_read_b128 v[190:193], v168 offset:2048
	ds_read_b128 v[194:197], v168 offset:3072
	s_add_u32 s58, s68, 0xfffc0080
	s_addc_u32 s59, s69, -1
	s_cmp_eq_u32 s86, 12
	s_cselect_b32 s73, s9, s59
	s_cselect_b32 s72, s61, s58
	s_cselect_b32 s71, s21, s85
	s_cselect_b32 s70, s67, s84
	v_lshl_add_u64 v[230:231], s[68:69], 0, v[152:153]
	s_add_i32 m0, s43, 0xc000
	ds_read_b128 v[198:201], v169
	ds_read_b128 v[202:205], v169 offset:1024
	ds_read_b128 v[206:209], v169 offset:2048
	ds_read_b128 v[210:213], v169 offset:3072
	ds_read_b128 v[214:217], v169 offset:4096
	ds_read_b128 v[218:221], v169 offset:5120
	ds_read_b128 v[222:225], v169 offset:6144
	ds_read_b128 v[226:229], v169 offset:7168
	global_load_lds_dwordx4 v[230:231], off
	v_lshl_add_u64 v[230:231], s[68:69], 0, v[154:155]
	s_add_i32 m0, s43, 0xe000
	s_nop 0
	global_load_lds_dwordx4 v[230:231], off
	s_waitcnt vmcnt(8)
	s_waitcnt lgkmcnt(0)
	s_barrier
	s_nop 0
	s_waitcnt lgkmcnt(0)
	v_mfma_f32_16x16x32_bf16 v[124:127], v[128:131], v[198:201], v[124:127]
	v_mfma_f32_16x16x32_bf16 v[120:123], v[174:177], v[198:201], v[120:123]
	v_mfma_f32_16x16x32_bf16 v[108:111], v[128:131], v[206:209], v[108:111]
	v_mfma_f32_16x16x32_bf16 v[104:107], v[174:177], v[206:209], v[104:107]
	v_mfma_f32_16x16x32_bf16 v[92:95], v[128:131], v[214:217], v[92:95]
	v_mfma_f32_16x16x32_bf16 v[88:91], v[174:177], v[214:217], v[88:91]
	v_mfma_f32_16x16x32_bf16 v[76:79], v[128:131], v[222:225], v[76:79]
	v_mfma_f32_16x16x32_bf16 v[72:75], v[174:177], v[222:225], v[72:75]
	v_mfma_f32_16x16x32_bf16 v[124:127], v[170:173], v[202:205], v[124:127]
	v_mfma_f32_16x16x32_bf16 v[120:123], v[178:181], v[202:205], v[120:123]
	v_mfma_f32_16x16x32_bf16 v[108:111], v[170:173], v[210:213], v[108:111]
	v_mfma_f32_16x16x32_bf16 v[104:107], v[178:181], v[210:213], v[104:107]
	v_mfma_f32_16x16x32_bf16 v[92:95], v[170:173], v[218:221], v[92:95]
	v_mfma_f32_16x16x32_bf16 v[88:91], v[178:181], v[218:221], v[88:91]
	v_mfma_f32_16x16x32_bf16 v[76:79], v[170:173], v[226:229], v[76:79]
	v_mfma_f32_16x16x32_bf16 v[72:75], v[178:181], v[226:229], v[72:75]
	s_nop 0
	s_nop 0
	v_mfma_f32_16x16x32_bf16 v[116:119], v[182:185], v[198:201], v[116:119]
	v_mfma_f32_16x16x32_bf16 v[112:115], v[190:193], v[198:201], v[112:115]
	v_mfma_f32_16x16x32_bf16 v[100:103], v[182:185], v[206:209], v[100:103]
	v_mfma_f32_16x16x32_bf16 v[96:99], v[190:193], v[206:209], v[96:99]
	v_mfma_f32_16x16x32_bf16 v[84:87], v[182:185], v[214:217], v[84:87]
	v_mfma_f32_16x16x32_bf16 v[80:83], v[190:193], v[214:217], v[80:83]
	v_mfma_f32_16x16x32_bf16 v[68:71], v[182:185], v[222:225], v[68:71]
	v_mfma_f32_16x16x32_bf16 v[64:67], v[190:193], v[222:225], v[64:67]
	v_mfma_f32_16x16x32_bf16 v[116:119], v[186:189], v[202:205], v[116:119]
	v_mfma_f32_16x16x32_bf16 v[112:115], v[194:197], v[202:205], v[112:115]
	v_mfma_f32_16x16x32_bf16 v[100:103], v[186:189], v[210:213], v[100:103]
	v_mfma_f32_16x16x32_bf16 v[96:99], v[194:197], v[210:213], v[96:99]
	v_mfma_f32_16x16x32_bf16 v[84:87], v[186:189], v[218:221], v[84:87]
	v_mfma_f32_16x16x32_bf16 v[80:83], v[194:197], v[218:221], v[80:83]
	v_mfma_f32_16x16x32_bf16 v[68:71], v[186:189], v[226:229], v[68:71]
	v_mfma_f32_16x16x32_bf16 v[64:67], v[194:197], v[226:229], v[64:67]
	s_nop 0
	s_barrier
	s_add_i32 s58, s25, s3
	v_lshl_add_u64 v[230:231], s[70:71], 0, v[134:135]
	s_mov_b32 m0, s58
	ds_read_b128 v[198:201], v169 offset:16384
	ds_read_b128 v[202:205], v169 offset:17408
	ds_read_b128 v[206:209], v169 offset:18432
	ds_read_b128 v[210:213], v169 offset:19456
	ds_read_b128 v[214:217], v169 offset:20480
	ds_read_b128 v[218:221], v169 offset:21504
	ds_read_b128 v[222:225], v169 offset:22528
	ds_read_b128 v[226:229], v169 offset:23552
	global_load_lds_dwordx4 v[230:231], off
	s_add_i32 m0, s58, 0x2000
	s_add_u32 s88, s70, 0x40000
	v_lshl_add_u64 v[232:233], s[70:71], 0, v[138:139]
	s_addc_u32 s89, s71, 0
	s_add_i32 s58, s33, s3
	global_load_lds_dwordx4 v[232:233], off
	v_lshl_add_u64 v[234:235], s[88:89], 0, v[134:135]
	s_mov_b32 m0, s58
	v_lshl_add_u64 v[236:237], s[72:73], 0, v[136:137]
	global_load_lds_dwordx4 v[234:235], off
	v_lshl_add_u64 v[234:235], s[88:89], 0, v[138:139]
	s_add_i32 m0, s58, 0x2000
	s_nop 0
	global_load_lds_dwordx4 v[234:235], off
	v_lshl_add_u64 v[234:235], s[72:73], 0, v[132:133]
	s_mov_b32 m0, s43
	s_nop 0
	global_load_lds_dwordx4 v[234:235], off
	s_mov_b32 m0, s74
	s_nop 0
	global_load_lds_dwordx4 v[236:237], off
	s_waitcnt vmcnt(8)
	s_waitcnt lgkmcnt(0)
	s_barrier
	s_nop 0
	s_waitcnt lgkmcnt(0)
	v_mfma_f32_16x16x32_bf16 v[60:63], v[128:131], v[198:201], v[60:63]
	v_mfma_f32_16x16x32_bf16 v[56:59], v[174:177], v[198:201], v[56:59]
	v_mfma_f32_16x16x32_bf16 v[44:47], v[128:131], v[206:209], v[44:47]
	v_mfma_f32_16x16x32_bf16 v[40:43], v[174:177], v[206:209], v[40:43]
	v_mfma_f32_16x16x32_bf16 v[28:31], v[128:131], v[214:217], v[28:31]
	v_mfma_f32_16x16x32_bf16 v[24:27], v[174:177], v[214:217], v[24:27]
	v_mfma_f32_16x16x32_bf16 v[12:15], v[128:131], v[222:225], v[12:15]
	v_mfma_f32_16x16x32_bf16 v[8:11], v[174:177], v[222:225], v[8:11]
	v_mfma_f32_16x16x32_bf16 v[60:63], v[170:173], v[202:205], v[60:63]
	v_mfma_f32_16x16x32_bf16 v[56:59], v[178:181], v[202:205], v[56:59]
	v_mfma_f32_16x16x32_bf16 v[44:47], v[170:173], v[210:213], v[44:47]
	v_mfma_f32_16x16x32_bf16 v[40:43], v[178:181], v[210:213], v[40:43]
	v_mfma_f32_16x16x32_bf16 v[28:31], v[170:173], v[218:221], v[28:31]
	v_mfma_f32_16x16x32_bf16 v[24:27], v[178:181], v[218:221], v[24:27]
	v_mfma_f32_16x16x32_bf16 v[12:15], v[170:173], v[226:229], v[12:15]
	v_mfma_f32_16x16x32_bf16 v[8:11], v[178:181], v[226:229], v[8:11]
	s_nop 0
	s_nop 0
	v_mfma_f32_16x16x32_bf16 v[52:55], v[182:185], v[198:201], v[52:55]
	v_mfma_f32_16x16x32_bf16 v[48:51], v[190:193], v[198:201], v[48:51]
	v_mfma_f32_16x16x32_bf16 v[36:39], v[182:185], v[206:209], v[36:39]
	v_mfma_f32_16x16x32_bf16 v[32:35], v[190:193], v[206:209], v[32:35]
	v_mfma_f32_16x16x32_bf16 v[20:23], v[182:185], v[214:217], v[20:23]
	v_mfma_f32_16x16x32_bf16 v[16:19], v[190:193], v[214:217], v[16:19]
	v_mfma_f32_16x16x32_bf16 v[4:7], v[182:185], v[222:225], v[4:7]
	v_mfma_f32_16x16x32_bf16 v[0:3], v[190:193], v[222:225], v[0:3]
	v_mfma_f32_16x16x32_bf16 v[52:55], v[186:189], v[202:205], v[52:55]
	v_mfma_f32_16x16x32_bf16 v[48:51], v[194:197], v[202:205], v[48:51]
	v_mfma_f32_16x16x32_bf16 v[36:39], v[186:189], v[210:213], v[36:39]
	v_mfma_f32_16x16x32_bf16 v[32:35], v[194:197], v[210:213], v[32:35]
	v_mfma_f32_16x16x32_bf16 v[20:23], v[186:189], v[218:221], v[20:23]
	v_mfma_f32_16x16x32_bf16 v[16:19], v[194:197], v[218:221], v[16:19]
	v_mfma_f32_16x16x32_bf16 v[4:7], v[186:189], v[226:229], v[4:7]
	v_mfma_f32_16x16x32_bf16 v[0:3], v[194:197], v[226:229], v[0:3]
	s_nop 0
	s_barrier
	s_add_i32 s58, 0, 0x18000
	v_add_u32_e32 v140, s58, v161
	s_add_i32 s59, 0, 0x1c000
	ds_read_b128 v[128:131], v140
	ds_read_b128 v[170:173], v140 offset:1024
	ds_read_b128 v[174:177], v140 offset:2048
	ds_read_b128 v[178:181], v140 offset:3072
	v_add_u32_e32 v140, s59, v161
	ds_read_b128 v[182:185], v140
	ds_read_b128 v[186:189], v140 offset:1024
	ds_read_b128 v[190:193], v140 offset:2048
	ds_read_b128 v[194:197], v140 offset:3072
	s_add_u32 s72, s72, 0x40000
	s_addc_u32 s73, s73, 0
	s_mov_b32 m0, s75
	v_lshl_add_u64 v[238:239], s[72:73], 0, v[132:133]
	ds_read_b128 v[198:201], v169 offset:32768
	ds_read_b128 v[202:205], v169 offset:33792
	ds_read_b128 v[206:209], v169 offset:34816
	ds_read_b128 v[210:213], v169 offset:35840
	ds_read_b128 v[214:217], v169 offset:36864
	ds_read_b128 v[218:221], v169 offset:37888
	ds_read_b128 v[222:225], v169 offset:38912
	ds_read_b128 v[226:229], v169 offset:39936
	global_load_lds_dwordx4 v[238:239], off
	v_lshl_add_u64 v[238:239], s[72:73], 0, v[136:137]
	s_mov_b32 m0, s78
	s_nop 0
	global_load_lds_dwordx4 v[238:239], off
	s_waitcnt vmcnt(8)
	s_waitcnt lgkmcnt(0)
	s_barrier
	s_nop 0
	s_waitcnt lgkmcnt(0)
	v_mfma_f32_16x16x32_bf16 v[124:127], v[128:131], v[198:201], v[124:127]
	v_mfma_f32_16x16x32_bf16 v[120:123], v[174:177], v[198:201], v[120:123]
	v_mfma_f32_16x16x32_bf16 v[108:111], v[128:131], v[206:209], v[108:111]
	v_mfma_f32_16x16x32_bf16 v[104:107], v[174:177], v[206:209], v[104:107]
	v_mfma_f32_16x16x32_bf16 v[92:95], v[128:131], v[214:217], v[92:95]
	v_mfma_f32_16x16x32_bf16 v[88:91], v[174:177], v[214:217], v[88:91]
	v_mfma_f32_16x16x32_bf16 v[76:79], v[128:131], v[222:225], v[76:79]
	v_mfma_f32_16x16x32_bf16 v[72:75], v[174:177], v[222:225], v[72:75]
	v_mfma_f32_16x16x32_bf16 v[124:127], v[170:173], v[202:205], v[124:127]
	v_mfma_f32_16x16x32_bf16 v[120:123], v[178:181], v[202:205], v[120:123]
	v_mfma_f32_16x16x32_bf16 v[108:111], v[170:173], v[210:213], v[108:111]
	v_mfma_f32_16x16x32_bf16 v[104:107], v[178:181], v[210:213], v[104:107]
	v_mfma_f32_16x16x32_bf16 v[92:95], v[170:173], v[218:221], v[92:95]
	v_mfma_f32_16x16x32_bf16 v[88:91], v[178:181], v[218:221], v[88:91]
	v_mfma_f32_16x16x32_bf16 v[76:79], v[170:173], v[226:229], v[76:79]
	v_mfma_f32_16x16x32_bf16 v[72:75], v[178:181], v[226:229], v[72:75]
	s_nop 0
	s_nop 0
	v_mfma_f32_16x16x32_bf16 v[116:119], v[182:185], v[198:201], v[116:119]
	v_mfma_f32_16x16x32_bf16 v[112:115], v[190:193], v[198:201], v[112:115]
	v_mfma_f32_16x16x32_bf16 v[100:103], v[182:185], v[206:209], v[100:103]
	v_mfma_f32_16x16x32_bf16 v[96:99], v[190:193], v[206:209], v[96:99]
	v_mfma_f32_16x16x32_bf16 v[84:87], v[182:185], v[214:217], v[84:87]
	v_mfma_f32_16x16x32_bf16 v[80:83], v[190:193], v[214:217], v[80:83]
	v_mfma_f32_16x16x32_bf16 v[68:71], v[182:185], v[222:225], v[68:71]
	v_mfma_f32_16x16x32_bf16 v[64:67], v[190:193], v[222:225], v[64:67]
	v_mfma_f32_16x16x32_bf16 v[116:119], v[186:189], v[202:205], v[116:119]
	v_mfma_f32_16x16x32_bf16 v[112:115], v[194:197], v[202:205], v[112:115]
	v_mfma_f32_16x16x32_bf16 v[100:103], v[186:189], v[210:213], v[100:103]
	v_mfma_f32_16x16x32_bf16 v[96:99], v[194:197], v[210:213], v[96:99]
	v_mfma_f32_16x16x32_bf16 v[84:87], v[186:189], v[218:221], v[84:87]
	v_mfma_f32_16x16x32_bf16 v[80:83], v[194:197], v[218:221], v[80:83]
	v_mfma_f32_16x16x32_bf16 v[68:71], v[186:189], v[226:229], v[68:71]
	v_mfma_f32_16x16x32_bf16 v[64:67], v[194:197], v[226:229], v[64:67]
	s_nop 0
	s_barrier
	s_add_i32 s58, s58, s3
	v_lshl_add_u64 v[230:231], v[230:231], 0, s[0:1]
	s_mov_b32 m0, s58
	ds_read_b128 v[198:201], v169 offset:49152
	ds_read_b128 v[202:205], v169 offset:50176
	ds_read_b128 v[206:209], v169 offset:51200
	ds_read_b128 v[210:213], v169 offset:52224
	ds_read_b128 v[214:217], v169 offset:53248
	ds_read_b128 v[218:221], v169 offset:54272
	ds_read_b128 v[222:225], v169 offset:55296
	ds_read_b128 v[226:229], v169 offset:56320
	global_load_lds_dwordx4 v[230:231], off
	s_add_i32 m0, s58, 0x2000
	s_add_u32 s70, s70, 0x40080
	v_lshl_add_u64 v[230:231], v[232:233], 0, s[0:1]
	s_addc_u32 s71, s71, 0
	s_add_i32 s58, s59, s3
	global_load_lds_dwordx4 v[230:231], off
	v_lshl_add_u64 v[230:231], s[70:71], 0, v[134:135]
	s_mov_b32 m0, s58
	s_nop 0
	global_load_lds_dwordx4 v[230:231], off
	v_lshl_add_u64 v[230:231], s[70:71], 0, v[138:139]
	s_add_i32 m0, s58, 0x2000
	s_nop 0
	global_load_lds_dwordx4 v[230:231], off
	v_lshl_add_u64 v[230:231], v[234:235], 0, s[0:1]
	s_mov_b32 m0, s80
	s_nop 0
	global_load_lds_dwordx4 v[230:231], off
	v_lshl_add_u64 v[230:231], v[236:237], 0, s[0:1]
	s_mov_b32 m0, s81
	s_nop 0
	global_load_lds_dwordx4 v[230:231], off
	s_waitcnt vmcnt(8)
	s_waitcnt lgkmcnt(0)
	s_barrier
	s_nop 0
	s_waitcnt lgkmcnt(0)
	v_mfma_f32_16x16x32_bf16 v[60:63], v[128:131], v[198:201], v[60:63]
	v_mfma_f32_16x16x32_bf16 v[56:59], v[174:177], v[198:201], v[56:59]
	v_mfma_f32_16x16x32_bf16 v[44:47], v[128:131], v[206:209], v[44:47]
	v_mfma_f32_16x16x32_bf16 v[40:43], v[174:177], v[206:209], v[40:43]
	v_mfma_f32_16x16x32_bf16 v[28:31], v[128:131], v[214:217], v[28:31]
	v_mfma_f32_16x16x32_bf16 v[24:27], v[174:177], v[214:217], v[24:27]
	v_mfma_f32_16x16x32_bf16 v[12:15], v[128:131], v[222:225], v[12:15]
	v_mfma_f32_16x16x32_bf16 v[8:11], v[174:177], v[222:225], v[8:11]
	v_mfma_f32_16x16x32_bf16 v[60:63], v[170:173], v[202:205], v[60:63]
	v_mfma_f32_16x16x32_bf16 v[56:59], v[178:181], v[202:205], v[56:59]
	v_mfma_f32_16x16x32_bf16 v[44:47], v[170:173], v[210:213], v[44:47]
	v_mfma_f32_16x16x32_bf16 v[40:43], v[178:181], v[210:213], v[40:43]
	v_mfma_f32_16x16x32_bf16 v[28:31], v[170:173], v[218:221], v[28:31]
	v_mfma_f32_16x16x32_bf16 v[24:27], v[178:181], v[218:221], v[24:27]
	v_mfma_f32_16x16x32_bf16 v[12:15], v[170:173], v[226:229], v[12:15]
	v_mfma_f32_16x16x32_bf16 v[8:11], v[178:181], v[226:229], v[8:11]
	s_nop 0
	s_nop 0
	v_mfma_f32_16x16x32_bf16 v[52:55], v[182:185], v[198:201], v[52:55]
	v_mfma_f32_16x16x32_bf16 v[48:51], v[190:193], v[198:201], v[48:51]
	v_mfma_f32_16x16x32_bf16 v[36:39], v[182:185], v[206:209], v[36:39]
	v_mfma_f32_16x16x32_bf16 v[32:35], v[190:193], v[206:209], v[32:35]
	v_mfma_f32_16x16x32_bf16 v[20:23], v[182:185], v[214:217], v[20:23]
	v_mfma_f32_16x16x32_bf16 v[16:19], v[190:193], v[214:217], v[16:19]
	v_mfma_f32_16x16x32_bf16 v[4:7], v[182:185], v[222:225], v[4:7]
	v_mfma_f32_16x16x32_bf16 v[0:3], v[190:193], v[222:225], v[0:3]
	v_mfma_f32_16x16x32_bf16 v[52:55], v[186:189], v[202:205], v[52:55]
	v_mfma_f32_16x16x32_bf16 v[48:51], v[194:197], v[202:205], v[48:51]
	v_mfma_f32_16x16x32_bf16 v[36:39], v[186:189], v[210:213], v[36:39]
	v_mfma_f32_16x16x32_bf16 v[32:35], v[194:197], v[210:213], v[32:35]
	v_mfma_f32_16x16x32_bf16 v[20:23], v[186:189], v[218:221], v[20:23]
	v_mfma_f32_16x16x32_bf16 v[16:19], v[194:197], v[218:221], v[16:19]
	v_mfma_f32_16x16x32_bf16 v[4:7], v[186:189], v[226:229], v[4:7]
	v_mfma_f32_16x16x32_bf16 v[0:3], v[194:197], v[226:229], v[0:3]
	s_nop 0
	s_barrier
	s_add_i32 s86, s86, 2
	s_add_u32 s68, s68, 0x100
	s_addc_u32 s69, s69, 0
	s_add_u32 s84, s84, 0x100
	s_addc_u32 s85, s85, 0
	s_cmp_gt_u32 s86, 13
	s_cbranch_scc0 .LBB0_749
	s_and_b64 vcc, exec, s[22:23]
	s_cbranch_vccz .LBB0_752
	s_barrier

.LBB0_886:
	ds_read_b128 v[150:153], v146
	ds_read_b128 v[154:157], v146 offset:1024
	ds_read_b128 v[158:161], v146 offset:2048
	ds_read_b128 v[162:165], v146 offset:3072
	ds_read_b128 v[166:169], v147
	ds_read_b128 v[170:173], v147 offset:1024
	ds_read_b128 v[174:177], v147 offset:2048
	ds_read_b128 v[178:181], v147 offset:3072
	s_add_i32 s25, s80, 2
	s_add_u32 s58, s78, 0xfffe0080
	s_addc_u32 s59, s79, -1
	s_cmp_eq_u32 s91, s80
	s_cselect_b32 s80, s62, s63
	s_cselect_b32 s83, s11, s59
	s_cselect_b32 s82, vcc_lo, s58
	s_cselect_b32 s81, vcc_hi, s85
	v_lshl_add_u64 v[214:215], s[78:79], 0, v[138:139]
	s_add_i32 m0, s35, 0xc000
	ds_read_b128 v[182:185], v148
	ds_read_b128 v[186:189], v148 offset:1024
	ds_read_b128 v[190:193], v148 offset:2048
	ds_read_b128 v[194:197], v148 offset:3072
	ds_read_b128 v[198:201], v148 offset:4096
	ds_read_b128 v[202:205], v148 offset:5120
	ds_read_b128 v[206:209], v148 offset:6144
	ds_read_b128 v[210:213], v148 offset:7168
	global_load_lds_dwordx4 v[214:215], off
	v_lshl_add_u64 v[214:215], s[78:79], 0, v[140:141]
	s_add_i32 m0, s35, 0xe000
	s_nop 0
	global_load_lds_dwordx4 v[214:215], off
	s_waitcnt vmcnt(8)
	s_waitcnt lgkmcnt(0)
	s_barrier
	s_nop 0
	s_waitcnt lgkmcnt(0)
	v_mfma_f32_16x16x32_bf16 v[124:127], v[150:153], v[182:185], v[124:127]
	v_mfma_f32_16x16x32_bf16 v[120:123], v[158:161], v[182:185], v[120:123]
	v_mfma_f32_16x16x32_bf16 v[108:111], v[150:153], v[190:193], v[108:111]
	v_mfma_f32_16x16x32_bf16 v[104:107], v[158:161], v[190:193], v[104:107]
	v_mfma_f32_16x16x32_bf16 v[92:95], v[150:153], v[198:201], v[92:95]
	v_mfma_f32_16x16x32_bf16 v[88:91], v[158:161], v[198:201], v[88:91]
	v_mfma_f32_16x16x32_bf16 v[76:79], v[150:153], v[206:209], v[76:79]
	v_mfma_f32_16x16x32_bf16 v[72:75], v[158:161], v[206:209], v[72:75]
	v_mfma_f32_16x16x32_bf16 v[124:127], v[154:157], v[186:189], v[124:127]
	v_mfma_f32_16x16x32_bf16 v[120:123], v[162:165], v[186:189], v[120:123]
	v_mfma_f32_16x16x32_bf16 v[108:111], v[154:157], v[194:197], v[108:111]
	v_mfma_f32_16x16x32_bf16 v[104:107], v[162:165], v[194:197], v[104:107]
	v_mfma_f32_16x16x32_bf16 v[92:95], v[154:157], v[202:205], v[92:95]
	v_mfma_f32_16x16x32_bf16 v[88:91], v[162:165], v[202:205], v[88:91]
	v_mfma_f32_16x16x32_bf16 v[76:79], v[154:157], v[210:213], v[76:79]
	v_mfma_f32_16x16x32_bf16 v[72:75], v[162:165], v[210:213], v[72:75]
	s_nop 0
	s_nop 0
	v_mfma_f32_16x16x32_bf16 v[116:119], v[166:169], v[182:185], v[116:119]
	v_mfma_f32_16x16x32_bf16 v[112:115], v[174:177], v[182:185], v[112:115]
	v_mfma_f32_16x16x32_bf16 v[100:103], v[166:169], v[190:193], v[100:103]
	v_mfma_f32_16x16x32_bf16 v[96:99], v[174:177], v[190:193], v[96:99]
	v_mfma_f32_16x16x32_bf16 v[84:87], v[166:169], v[198:201], v[84:87]
	v_mfma_f32_16x16x32_bf16 v[80:83], v[174:177], v[198:201], v[80:83]
	v_mfma_f32_16x16x32_bf16 v[68:71], v[166:169], v[206:209], v[68:71]
	v_mfma_f32_16x16x32_bf16 v[64:67], v[174:177], v[206:209], v[64:67]
	v_mfma_f32_16x16x32_bf16 v[116:119], v[170:173], v[186:189], v[116:119]
	v_mfma_f32_16x16x32_bf16 v[112:115], v[178:181], v[186:189], v[112:115]
	v_mfma_f32_16x16x32_bf16 v[100:103], v[170:173], v[194:197], v[100:103]
	v_mfma_f32_16x16x32_bf16 v[96:99], v[178:181], v[194:197], v[96:99]
	v_mfma_f32_16x16x32_bf16 v[84:87], v[170:173], v[202:205], v[84:87]
	v_mfma_f32_16x16x32_bf16 v[80:83], v[178:181], v[202:205], v[80:83]
	v_mfma_f32_16x16x32_bf16 v[68:71], v[170:173], v[210:213], v[68:71]
	v_mfma_f32_16x16x32_bf16 v[64:67], v[178:181], v[210:213], v[64:67]
	s_nop 0
	s_barrier
	s_add_i32 s58, s92, s84
	v_lshl_add_u64 v[214:215], s[80:81], 0, v[132:133]
	s_mov_b32 m0, s58
	ds_read_b128 v[182:185], v148 offset:16384
	ds_read_b128 v[186:189], v148 offset:17408
	ds_read_b128 v[190:193], v148 offset:18432
	ds_read_b128 v[194:197], v148 offset:19456
	ds_read_b128 v[198:201], v148 offset:20480
	ds_read_b128 v[202:205], v148 offset:21504
	ds_read_b128 v[206:209], v148 offset:22528
	ds_read_b128 v[210:213], v148 offset:23552
	global_load_lds_dwordx4 v[214:215], off
	s_add_i32 m0, s58, 0x2000
	s_add_u32 s58, s80, 0x20000
	v_lshl_add_u64 v[216:217], s[80:81], 0, v[128:129]
	s_addc_u32 s59, s81, 0
	s_add_i32 s33, s93, s84
	global_load_lds_dwordx4 v[216:217], off
	v_lshl_add_u64 v[218:219], s[58:59], 0, v[132:133]
	s_mov_b32 m0, s33
	v_lshl_add_u64 v[220:221], s[82:83], 0, v[130:131]
	global_load_lds_dwordx4 v[218:219], off
	v_lshl_add_u64 v[218:219], s[58:59], 0, v[128:129]
	s_add_i32 m0, s33, 0x2000
	s_nop 0
	global_load_lds_dwordx4 v[218:219], off
	v_lshl_add_u64 v[218:219], s[82:83], 0, v[134:135]
	s_mov_b32 m0, s35
	s_nop 0
	global_load_lds_dwordx4 v[218:219], off
	s_mov_b32 m0, s42
	s_nop 0
	global_load_lds_dwordx4 v[220:221], off
	s_waitcnt vmcnt(8)
	s_waitcnt lgkmcnt(0)
	s_barrier
	s_nop 0
	s_waitcnt lgkmcnt(0)
	v_mfma_f32_16x16x32_bf16 v[60:63], v[150:153], v[182:185], v[60:63]
	v_mfma_f32_16x16x32_bf16 v[56:59], v[158:161], v[182:185], v[56:59]
	v_mfma_f32_16x16x32_bf16 v[44:47], v[150:153], v[190:193], v[44:47]
	v_mfma_f32_16x16x32_bf16 v[40:43], v[158:161], v[190:193], v[40:43]
	v_mfma_f32_16x16x32_bf16 v[28:31], v[150:153], v[198:201], v[28:31]
	v_mfma_f32_16x16x32_bf16 v[24:27], v[158:161], v[198:201], v[24:27]
	v_mfma_f32_16x16x32_bf16 v[12:15], v[150:153], v[206:209], v[12:15]
	v_mfma_f32_16x16x32_bf16 v[8:11], v[158:161], v[206:209], v[8:11]
	v_mfma_f32_16x16x32_bf16 v[60:63], v[154:157], v[186:189], v[60:63]
	v_mfma_f32_16x16x32_bf16 v[56:59], v[162:165], v[186:189], v[56:59]
	v_mfma_f32_16x16x32_bf16 v[44:47], v[154:157], v[194:197], v[44:47]
	v_mfma_f32_16x16x32_bf16 v[40:43], v[162:165], v[194:197], v[40:43]
	v_mfma_f32_16x16x32_bf16 v[28:31], v[154:157], v[202:205], v[28:31]
	v_mfma_f32_16x16x32_bf16 v[24:27], v[162:165], v[202:205], v[24:27]
	v_mfma_f32_16x16x32_bf16 v[12:15], v[154:157], v[210:213], v[12:15]
	v_mfma_f32_16x16x32_bf16 v[8:11], v[162:165], v[210:213], v[8:11]
	s_nop 0
	s_nop 0
	v_mfma_f32_16x16x32_bf16 v[52:55], v[166:169], v[182:185], v[52:55]
	v_mfma_f32_16x16x32_bf16 v[48:51], v[174:177], v[182:185], v[48:51]
	v_mfma_f32_16x16x32_bf16 v[36:39], v[166:169], v[190:193], v[36:39]
	v_mfma_f32_16x16x32_bf16 v[32:35], v[174:177], v[190:193], v[32:35]
	v_mfma_f32_16x16x32_bf16 v[20:23], v[166:169], v[198:201], v[20:23]
	v_mfma_f32_16x16x32_bf16 v[16:19], v[174:177], v[198:201], v[16:19]
	v_mfma_f32_16x16x32_bf16 v[4:7], v[166:169], v[206:209], v[4:7]
	v_mfma_f32_16x16x32_bf16 v[0:3], v[174:177], v[206:209], v[0:3]
	v_mfma_f32_16x16x32_bf16 v[52:55], v[170:173], v[186:189], v[52:55]
	v_mfma_f32_16x16x32_bf16 v[48:51], v[178:181], v[186:189], v[48:51]
	v_mfma_f32_16x16x32_bf16 v[36:39], v[170:173], v[194:197], v[36:39]
	v_mfma_f32_16x16x32_bf16 v[32:35], v[178:181], v[194:197], v[32:35]
	v_mfma_f32_16x16x32_bf16 v[20:23], v[170:173], v[202:205], v[20:23]
	v_mfma_f32_16x16x32_bf16 v[16:19], v[178:181], v[202:205], v[16:19]
	v_mfma_f32_16x16x32_bf16 v[4:7], v[170:173], v[210:213], v[4:7]
	v_mfma_f32_16x16x32_bf16 v[0:3], v[178:181], v[210:213], v[0:3]
	s_nop 0
	s_barrier
	s_add_i32 s33, 0, 0x18000
	v_add_u32_e32 v149, s33, v145
	s_add_i32 s34, 0, 0x1c000
	ds_read_b128 v[150:153], v149
	ds_read_b128 v[154:157], v149 offset:1024
	ds_read_b128 v[158:161], v149 offset:2048
	ds_read_b128 v[162:165], v149 offset:3072
	v_add_u32_e32 v149, s34, v145
	ds_read_b128 v[166:169], v149
	ds_read_b128 v[170:173], v149 offset:1024
	ds_read_b128 v[174:177], v149 offset:2048
	ds_read_b128 v[178:181], v149 offset:3072
	s_add_u32 s58, s82, 0x20000
	s_addc_u32 s59, s83, 0
	s_mov_b32 m0, s43
	v_lshl_add_u64 v[222:223], s[58:59], 0, v[134:135]
	ds_read_b128 v[182:185], v148 offset:32768
	ds_read_b128 v[186:189], v148 offset:33792
	ds_read_b128 v[190:193], v148 offset:34816
	ds_read_b128 v[194:197], v148 offset:35840
	ds_read_b128 v[198:201], v148 offset:36864
	ds_read_b128 v[202:205], v148 offset:37888
	ds_read_b128 v[206:209], v148 offset:38912
	ds_read_b128 v[210:213], v148 offset:39936
	global_load_lds_dwordx4 v[222:223], off
	v_lshl_add_u64 v[222:223], s[58:59], 0, v[130:131]
	s_mov_b32 m0, s87
	s_nop 0
	global_load_lds_dwordx4 v[222:223], off
	s_waitcnt vmcnt(8)
	s_waitcnt lgkmcnt(0)
	s_barrier
	s_nop 0
	s_waitcnt lgkmcnt(0)
	v_mfma_f32_16x16x32_bf16 v[124:127], v[150:153], v[182:185], v[124:127]
	v_mfma_f32_16x16x32_bf16 v[120:123], v[158:161], v[182:185], v[120:123]
	v_mfma_f32_16x16x32_bf16 v[108:111], v[150:153], v[190:193], v[108:111]
	v_mfma_f32_16x16x32_bf16 v[104:107], v[158:161], v[190:193], v[104:107]
	v_mfma_f32_16x16x32_bf16 v[92:95], v[150:153], v[198:201], v[92:95]
	v_mfma_f32_16x16x32_bf16 v[88:91], v[158:161], v[198:201], v[88:91]
	v_mfma_f32_16x16x32_bf16 v[76:79], v[150:153], v[206:209], v[76:79]
	v_mfma_f32_16x16x32_bf16 v[72:75], v[158:161], v[206:209], v[72:75]
	v_mfma_f32_16x16x32_bf16 v[124:127], v[154:157], v[186:189], v[124:127]
	v_mfma_f32_16x16x32_bf16 v[120:123], v[162:165], v[186:189], v[120:123]
	v_mfma_f32_16x16x32_bf16 v[108:111], v[154:157], v[194:197], v[108:111]
	v_mfma_f32_16x16x32_bf16 v[104:107], v[162:165], v[194:197], v[104:107]
	v_mfma_f32_16x16x32_bf16 v[92:95], v[154:157], v[202:205], v[92:95]
	v_mfma_f32_16x16x32_bf16 v[88:91], v[162:165], v[202:205], v[88:91]
	v_mfma_f32_16x16x32_bf16 v[76:79], v[154:157], v[210:213], v[76:79]
	v_mfma_f32_16x16x32_bf16 v[72:75], v[162:165], v[210:213], v[72:75]
	s_nop 0
	s_nop 0
	v_mfma_f32_16x16x32_bf16 v[116:119], v[166:169], v[182:185], v[116:119]
	v_mfma_f32_16x16x32_bf16 v[112:115], v[174:177], v[182:185], v[112:115]
	v_mfma_f32_16x16x32_bf16 v[100:103], v[166:169], v[190:193], v[100:103]
	v_mfma_f32_16x16x32_bf16 v[96:99], v[174:177], v[190:193], v[96:99]
	v_mfma_f32_16x16x32_bf16 v[84:87], v[166:169], v[198:201], v[84:87]
	v_mfma_f32_16x16x32_bf16 v[80:83], v[174:177], v[198:201], v[80:83]
	v_mfma_f32_16x16x32_bf16 v[68:71], v[166:169], v[206:209], v[68:71]
	v_mfma_f32_16x16x32_bf16 v[64:67], v[174:177], v[206:209], v[64:67]
	v_mfma_f32_16x16x32_bf16 v[116:119], v[170:173], v[186:189], v[116:119]
	v_mfma_f32_16x16x32_bf16 v[112:115], v[178:181], v[186:189], v[112:115]
	v_mfma_f32_16x16x32_bf16 v[100:103], v[170:173], v[194:197], v[100:103]
	v_mfma_f32_16x16x32_bf16 v[96:99], v[178:181], v[194:197], v[96:99]
	v_mfma_f32_16x16x32_bf16 v[84:87], v[170:173], v[202:205], v[84:87]
	v_mfma_f32_16x16x32_bf16 v[80:83], v[178:181], v[202:205], v[80:83]
	v_mfma_f32_16x16x32_bf16 v[68:71], v[170:173], v[210:213], v[68:71]
	v_mfma_f32_16x16x32_bf16 v[64:67], v[178:181], v[210:213], v[64:67]
	s_nop 0
	s_barrier
	s_add_i32 s33, s33, s84
	v_lshl_add_u64 v[214:215], v[214:215], 0, s[70:71]
	s_mov_b32 m0, s33
	ds_read_b128 v[182:185], v148 offset:49152
	ds_read_b128 v[186:189], v148 offset:50176
	ds_read_b128 v[190:193], v148 offset:51200
	ds_read_b128 v[194:197], v148 offset:52224
	ds_read_b128 v[198:201], v148 offset:53248
	ds_read_b128 v[202:205], v148 offset:54272
	ds_read_b128 v[206:209], v148 offset:55296
	ds_read_b128 v[210:213], v148 offset:56320
	global_load_lds_dwordx4 v[214:215], off
	s_add_i32 m0, s33, 0x2000
	s_add_u32 s58, s80, 0x20080
	v_lshl_add_u64 v[214:215], v[216:217], 0, s[70:71]
	s_addc_u32 s59, s81, 0
	s_add_i32 s33, s34, s84
	global_load_lds_dwordx4 v[214:215], off
	v_lshl_add_u64 v[214:215], s[58:59], 0, v[132:133]
	s_mov_b32 m0, s33
	s_nop 0
	global_load_lds_dwordx4 v[214:215], off
	v_lshl_add_u64 v[214:215], s[58:59], 0, v[128:129]
	s_add_i32 m0, s33, 0x2000
	s_nop 0
	global_load_lds_dwordx4 v[214:215], off
	v_lshl_add_u64 v[214:215], v[218:219], 0, s[70:71]
	s_mov_b32 m0, s88
	s_nop 0
	global_load_lds_dwordx4 v[214:215], off
	v_lshl_add_u64 v[214:215], v[220:221], 0, s[70:71]
	s_mov_b32 m0, s89
	s_nop 0
	global_load_lds_dwordx4 v[214:215], off
	s_waitcnt vmcnt(8)
	s_waitcnt lgkmcnt(0)
	s_barrier
	s_nop 0
	s_waitcnt lgkmcnt(0)
	v_mfma_f32_16x16x32_bf16 v[60:63], v[150:153], v[182:185], v[60:63]
	v_mfma_f32_16x16x32_bf16 v[56:59], v[158:161], v[182:185], v[56:59]
	v_mfma_f32_16x16x32_bf16 v[44:47], v[150:153], v[190:193], v[44:47]
	v_mfma_f32_16x16x32_bf16 v[40:43], v[158:161], v[190:193], v[40:43]
	v_mfma_f32_16x16x32_bf16 v[28:31], v[150:153], v[198:201], v[28:31]
	v_mfma_f32_16x16x32_bf16 v[24:27], v[158:161], v[198:201], v[24:27]
	v_mfma_f32_16x16x32_bf16 v[12:15], v[150:153], v[206:209], v[12:15]
	v_mfma_f32_16x16x32_bf16 v[8:11], v[158:161], v[206:209], v[8:11]
	v_mfma_f32_16x16x32_bf16 v[60:63], v[154:157], v[186:189], v[60:63]
	v_mfma_f32_16x16x32_bf16 v[56:59], v[162:165], v[186:189], v[56:59]
	v_mfma_f32_16x16x32_bf16 v[44:47], v[154:157], v[194:197], v[44:47]
	v_mfma_f32_16x16x32_bf16 v[40:43], v[162:165], v[194:197], v[40:43]
	v_mfma_f32_16x16x32_bf16 v[28:31], v[154:157], v[202:205], v[28:31]
	v_mfma_f32_16x16x32_bf16 v[24:27], v[162:165], v[202:205], v[24:27]
	v_mfma_f32_16x16x32_bf16 v[12:15], v[154:157], v[210:213], v[12:15]
	v_mfma_f32_16x16x32_bf16 v[8:11], v[162:165], v[210:213], v[8:11]
	s_nop 0
	s_nop 0
	v_mfma_f32_16x16x32_bf16 v[52:55], v[166:169], v[182:185], v[52:55]
	v_mfma_f32_16x16x32_bf16 v[48:51], v[174:177], v[182:185], v[48:51]
	v_mfma_f32_16x16x32_bf16 v[36:39], v[166:169], v[190:193], v[36:39]
	v_mfma_f32_16x16x32_bf16 v[32:35], v[174:177], v[190:193], v[32:35]
	v_mfma_f32_16x16x32_bf16 v[20:23], v[166:169], v[198:201], v[20:23]
	v_mfma_f32_16x16x32_bf16 v[16:19], v[174:177], v[198:201], v[16:19]
	v_mfma_f32_16x16x32_bf16 v[4:7], v[166:169], v[206:209], v[4:7]
	v_mfma_f32_16x16x32_bf16 v[0:3], v[174:177], v[206:209], v[0:3]
	v_mfma_f32_16x16x32_bf16 v[52:55], v[170:173], v[186:189], v[52:55]
	v_mfma_f32_16x16x32_bf16 v[48:51], v[178:181], v[186:189], v[48:51]
	v_mfma_f32_16x16x32_bf16 v[36:39], v[170:173], v[194:197], v[36:39]
	v_mfma_f32_16x16x32_bf16 v[32:35], v[178:181], v[194:197], v[32:35]
	v_mfma_f32_16x16x32_bf16 v[20:23], v[170:173], v[202:205], v[20:23]
	v_mfma_f32_16x16x32_bf16 v[16:19], v[178:181], v[202:205], v[16:19]
	v_mfma_f32_16x16x32_bf16 v[4:7], v[170:173], v[210:213], v[4:7]
	v_mfma_f32_16x16x32_bf16 v[0:3], v[178:181], v[210:213], v[0:3]
	s_nop 0
	s_barrier
	s_add_u32 s78, s78, 0x100
	s_addc_u32 s79, s79, 0
	s_add_u32 s63, s63, 0x100
	s_addc_u32 s85, s85, 0
	s_cmp_ge_i32 s25, s90
	s_mov_b32 s80, s25
	s_cbranch_scc0 .LBB0_886

.LBB0_917:
	ds_read_b128 v[152:155], v148
	ds_read_b128 v[156:159], v148 offset:1024
	ds_read_b128 v[160:163], v148 offset:2048
	ds_read_b128 v[164:167], v148 offset:3072
	ds_read_b128 v[168:171], v149
	ds_read_b128 v[172:175], v149 offset:1024
	ds_read_b128 v[176:179], v149 offset:2048
	ds_read_b128 v[180:183], v149 offset:3072
	s_add_u32 s58, s18, 0xfffe0080
	s_addc_u32 s59, s19, -1
	s_cmp_eq_u32 s62, 4
	s_cselect_b32 s69, s9, s59
	s_cselect_b32 s68, s33, s58
	s_cselect_b32 s67, s34, s43
	s_cselect_b32 s66, s35, s42
	s_mov_b32 m0, s76
	v_lshl_add_u64 v[216:217], s[18:19], 0, v[138:139]
	ds_read_b128 v[184:187], v150
	ds_read_b128 v[188:191], v150 offset:1024
	ds_read_b128 v[192:195], v150 offset:2048
	ds_read_b128 v[196:199], v150 offset:3072
	ds_read_b128 v[200:203], v150 offset:4096
	ds_read_b128 v[204:207], v150 offset:5120
	ds_read_b128 v[208:211], v150 offset:6144
	ds_read_b128 v[212:215], v150 offset:7168
	global_load_lds_dwordx4 v[216:217], off
	v_lshl_add_u64 v[216:217], s[18:19], 0, v[140:141]
	s_mov_b32 m0, s77
	s_nop 0
	global_load_lds_dwordx4 v[216:217], off
	s_waitcnt vmcnt(8)
	s_waitcnt lgkmcnt(0)
	s_barrier
	s_nop 0
	s_waitcnt lgkmcnt(0)
	v_mfma_f32_16x16x32_bf16 v[124:127], v[152:155], v[184:187], v[124:127]
	v_mfma_f32_16x16x32_bf16 v[120:123], v[160:163], v[184:187], v[120:123]
	v_mfma_f32_16x16x32_bf16 v[108:111], v[152:155], v[192:195], v[108:111]
	v_mfma_f32_16x16x32_bf16 v[104:107], v[160:163], v[192:195], v[104:107]
	v_mfma_f32_16x16x32_bf16 v[92:95], v[152:155], v[200:203], v[92:95]
	v_mfma_f32_16x16x32_bf16 v[88:91], v[160:163], v[200:203], v[88:91]
	v_mfma_f32_16x16x32_bf16 v[76:79], v[152:155], v[208:211], v[76:79]
	v_mfma_f32_16x16x32_bf16 v[72:75], v[160:163], v[208:211], v[72:75]
	v_mfma_f32_16x16x32_bf16 v[124:127], v[156:159], v[188:191], v[124:127]
	v_mfma_f32_16x16x32_bf16 v[120:123], v[164:167], v[188:191], v[120:123]
	v_mfma_f32_16x16x32_bf16 v[108:111], v[156:159], v[196:199], v[108:111]
	v_mfma_f32_16x16x32_bf16 v[104:107], v[164:167], v[196:199], v[104:107]
	v_mfma_f32_16x16x32_bf16 v[92:95], v[156:159], v[204:207], v[92:95]
	v_mfma_f32_16x16x32_bf16 v[88:91], v[164:167], v[204:207], v[88:91]
	v_mfma_f32_16x16x32_bf16 v[76:79], v[156:159], v[212:215], v[76:79]
	v_mfma_f32_16x16x32_bf16 v[72:75], v[164:167], v[212:215], v[72:75]
	s_nop 0
	s_nop 0
	v_mfma_f32_16x16x32_bf16 v[116:119], v[168:171], v[184:187], v[116:119]
	v_mfma_f32_16x16x32_bf16 v[112:115], v[176:179], v[184:187], v[112:115]
	v_mfma_f32_16x16x32_bf16 v[100:103], v[168:171], v[192:195], v[100:103]
	v_mfma_f32_16x16x32_bf16 v[96:99], v[176:179], v[192:195], v[96:99]
	v_mfma_f32_16x16x32_bf16 v[84:87], v[168:171], v[200:203], v[84:87]
	v_mfma_f32_16x16x32_bf16 v[80:83], v[176:179], v[200:203], v[80:83]
	v_mfma_f32_16x16x32_bf16 v[68:71], v[168:171], v[208:211], v[68:71]
	v_mfma_f32_16x16x32_bf16 v[64:67], v[176:179], v[208:211], v[64:67]
	v_mfma_f32_16x16x32_bf16 v[116:119], v[172:175], v[188:191], v[116:119]
	v_mfma_f32_16x16x32_bf16 v[112:115], v[180:183], v[188:191], v[112:115]
	v_mfma_f32_16x16x32_bf16 v[100:103], v[172:175], v[196:199], v[100:103]
	v_mfma_f32_16x16x32_bf16 v[96:99], v[180:183], v[196:199], v[96:99]
	v_mfma_f32_16x16x32_bf16 v[84:87], v[172:175], v[204:207], v[84:87]
	v_mfma_f32_16x16x32_bf16 v[80:83], v[180:183], v[204:207], v[80:83]
	v_mfma_f32_16x16x32_bf16 v[68:71], v[172:175], v[212:215], v[68:71]
	v_mfma_f32_16x16x32_bf16 v[64:67], v[180:183], v[212:215], v[64:67]
	s_nop 0
	s_barrier
	s_mov_b32 m0, s78
	v_lshl_add_u64 v[216:217], s[66:67], 0, v[132:133]
	ds_read_b128 v[184:187], v150 offset:16384
	ds_read_b128 v[188:191], v150 offset:17408
	ds_read_b128 v[192:195], v150 offset:18432
	ds_read_b128 v[196:199], v150 offset:19456
	ds_read_b128 v[200:203], v150 offset:20480
	ds_read_b128 v[204:207], v150 offset:21504
	ds_read_b128 v[208:211], v150 offset:22528
	ds_read_b128 v[212:215], v150 offset:23552
	global_load_lds_dwordx4 v[216:217], off
	s_add_i32 m0, s78, 0x2000
	s_add_u32 s58, s66, 0x20000
	v_lshl_add_u64 v[218:219], s[66:67], 0, v[128:129]
	s_addc_u32 s59, s67, 0
	s_add_i32 s63, s75, s84
	global_load_lds_dwordx4 v[218:219], off
	v_lshl_add_u64 v[220:221], s[58:59], 0, v[132:133]
	s_mov_b32 m0, s63
	v_lshl_add_u64 v[222:223], s[68:69], 0, v[130:131]
	global_load_lds_dwordx4 v[220:221], off
	v_lshl_add_u64 v[220:221], s[58:59], 0, v[128:129]
	s_add_i32 m0, s63, 0x2000
	s_nop 0
	global_load_lds_dwordx4 v[220:221], off
	v_lshl_add_u64 v[220:221], s[68:69], 0, v[134:135]
	s_mov_b32 m0, s21
	s_nop 0
	global_load_lds_dwordx4 v[220:221], off
	s_mov_b32 m0, s70
	s_nop 0
	global_load_lds_dwordx4 v[222:223], off
	s_waitcnt vmcnt(8)
	s_waitcnt lgkmcnt(0)
	s_barrier
	s_nop 0
	s_waitcnt lgkmcnt(0)
	v_mfma_f32_16x16x32_bf16 v[60:63], v[152:155], v[184:187], v[60:63]
	v_mfma_f32_16x16x32_bf16 v[56:59], v[160:163], v[184:187], v[56:59]
	v_mfma_f32_16x16x32_bf16 v[44:47], v[152:155], v[192:195], v[44:47]
	v_mfma_f32_16x16x32_bf16 v[40:43], v[160:163], v[192:195], v[40:43]
	v_mfma_f32_16x16x32_bf16 v[28:31], v[152:155], v[200:203], v[28:31]
	v_mfma_f32_16x16x32_bf16 v[24:27], v[160:163], v[200:203], v[24:27]
	v_mfma_f32_16x16x32_bf16 v[12:15], v[152:155], v[208:211], v[12:15]
	v_mfma_f32_16x16x32_bf16 v[8:11], v[160:163], v[208:211], v[8:11]
	v_mfma_f32_16x16x32_bf16 v[60:63], v[156:159], v[188:191], v[60:63]
	v_mfma_f32_16x16x32_bf16 v[56:59], v[164:167], v[188:191], v[56:59]
	v_mfma_f32_16x16x32_bf16 v[44:47], v[156:159], v[196:199], v[44:47]
	v_mfma_f32_16x16x32_bf16 v[40:43], v[164:167], v[196:199], v[40:43]
	v_mfma_f32_16x16x32_bf16 v[28:31], v[156:159], v[204:207], v[28:31]
	v_mfma_f32_16x16x32_bf16 v[24:27], v[164:167], v[204:207], v[24:27]
	v_mfma_f32_16x16x32_bf16 v[12:15], v[156:159], v[212:215], v[12:15]
	v_mfma_f32_16x16x32_bf16 v[8:11], v[164:167], v[212:215], v[8:11]
	s_nop 0
	s_nop 0
	v_mfma_f32_16x16x32_bf16 v[52:55], v[168:171], v[184:187], v[52:55]
	v_mfma_f32_16x16x32_bf16 v[48:51], v[176:179], v[184:187], v[48:51]
	v_mfma_f32_16x16x32_bf16 v[36:39], v[168:171], v[192:195], v[36:39]
	v_mfma_f32_16x16x32_bf16 v[32:35], v[176:179], v[192:195], v[32:35]
	v_mfma_f32_16x16x32_bf16 v[20:23], v[168:171], v[200:203], v[20:23]
	v_mfma_f32_16x16x32_bf16 v[16:19], v[176:179], v[200:203], v[16:19]
	v_mfma_f32_16x16x32_bf16 v[4:7], v[168:171], v[208:211], v[4:7]
	v_mfma_f32_16x16x32_bf16 v[0:3], v[176:179], v[208:211], v[0:3]
	v_mfma_f32_16x16x32_bf16 v[52:55], v[172:175], v[188:191], v[52:55]
	v_mfma_f32_16x16x32_bf16 v[48:51], v[180:183], v[188:191], v[48:51]
	v_mfma_f32_16x16x32_bf16 v[36:39], v[172:175], v[196:199], v[36:39]
	v_mfma_f32_16x16x32_bf16 v[32:35], v[180:183], v[196:199], v[32:35]
	v_mfma_f32_16x16x32_bf16 v[20:23], v[172:175], v[204:207], v[20:23]
	v_mfma_f32_16x16x32_bf16 v[16:19], v[180:183], v[204:207], v[16:19]
	v_mfma_f32_16x16x32_bf16 v[4:7], v[172:175], v[212:215], v[4:7]
	v_mfma_f32_16x16x32_bf16 v[0:3], v[180:183], v[212:215], v[0:3]
	s_nop 0
	s_barrier
	s_add_i32 s63, 0, 0x18000
	v_add_u32_e32 v151, s63, v145
	s_add_i32 s80, 0, 0x1c000
	ds_read_b128 v[152:155], v151
	ds_read_b128 v[156:159], v151 offset:1024
	ds_read_b128 v[160:163], v151 offset:2048
	ds_read_b128 v[164:167], v151 offset:3072
	v_add_u32_e32 v151, s80, v145
	ds_read_b128 v[168:171], v151
	ds_read_b128 v[172:175], v151 offset:1024
	ds_read_b128 v[176:179], v151 offset:2048
	ds_read_b128 v[180:183], v151 offset:3072
	s_add_u32 s58, s68, 0x20000
	s_addc_u32 s59, s69, 0
	s_mov_b32 m0, s71
	v_lshl_add_u64 v[224:225], s[58:59], 0, v[134:135]
	ds_read_b128 v[184:187], v150 offset:32768
	ds_read_b128 v[188:191], v150 offset:33792
	ds_read_b128 v[192:195], v150 offset:34816
	ds_read_b128 v[196:199], v150 offset:35840
	ds_read_b128 v[200:203], v150 offset:36864
	ds_read_b128 v[204:207], v150 offset:37888
	ds_read_b128 v[208:211], v150 offset:38912
	ds_read_b128 v[212:215], v150 offset:39936
	global_load_lds_dwordx4 v[224:225], off
	v_lshl_add_u64 v[224:225], s[58:59], 0, v[130:131]
	s_mov_b32 m0, s72
	s_nop 0
	global_load_lds_dwordx4 v[224:225], off
	s_waitcnt vmcnt(8)
	s_waitcnt lgkmcnt(0)
	s_barrier
	s_nop 0
	s_waitcnt lgkmcnt(0)
	v_mfma_f32_16x16x32_bf16 v[124:127], v[152:155], v[184:187], v[124:127]
	v_mfma_f32_16x16x32_bf16 v[120:123], v[160:163], v[184:187], v[120:123]
	v_mfma_f32_16x16x32_bf16 v[108:111], v[152:155], v[192:195], v[108:111]
	v_mfma_f32_16x16x32_bf16 v[104:107], v[160:163], v[192:195], v[104:107]
	v_mfma_f32_16x16x32_bf16 v[92:95], v[152:155], v[200:203], v[92:95]
	v_mfma_f32_16x16x32_bf16 v[88:91], v[160:163], v[200:203], v[88:91]
	v_mfma_f32_16x16x32_bf16 v[76:79], v[152:155], v[208:211], v[76:79]
	v_mfma_f32_16x16x32_bf16 v[72:75], v[160:163], v[208:211], v[72:75]
	v_mfma_f32_16x16x32_bf16 v[124:127], v[156:159], v[188:191], v[124:127]
	v_mfma_f32_16x16x32_bf16 v[120:123], v[164:167], v[188:191], v[120:123]
	v_mfma_f32_16x16x32_bf16 v[108:111], v[156:159], v[196:199], v[108:111]
	v_mfma_f32_16x16x32_bf16 v[104:107], v[164:167], v[196:199], v[104:107]
	v_mfma_f32_16x16x32_bf16 v[92:95], v[156:159], v[204:207], v[92:95]
	v_mfma_f32_16x16x32_bf16 v[88:91], v[164:167], v[204:207], v[88:91]
	v_mfma_f32_16x16x32_bf16 v[76:79], v[156:159], v[212:215], v[76:79]
	v_mfma_f32_16x16x32_bf16 v[72:75], v[164:167], v[212:215], v[72:75]
	s_nop 0
	s_nop 0
	v_mfma_f32_16x16x32_bf16 v[116:119], v[168:171], v[184:187], v[116:119]
	v_mfma_f32_16x16x32_bf16 v[112:115], v[176:179], v[184:187], v[112:115]
	v_mfma_f32_16x16x32_bf16 v[100:103], v[168:171], v[192:195], v[100:103]
	v_mfma_f32_16x16x32_bf16 v[96:99], v[176:179], v[192:195], v[96:99]
	v_mfma_f32_16x16x32_bf16 v[84:87], v[168:171], v[200:203], v[84:87]
	v_mfma_f32_16x16x32_bf16 v[80:83], v[176:179], v[200:203], v[80:83]
	v_mfma_f32_16x16x32_bf16 v[68:71], v[168:171], v[208:211], v[68:71]
	v_mfma_f32_16x16x32_bf16 v[64:67], v[176:179], v[208:211], v[64:67]
	v_mfma_f32_16x16x32_bf16 v[116:119], v[172:175], v[188:191], v[116:119]
	v_mfma_f32_16x16x32_bf16 v[112:115], v[180:183], v[188:191], v[112:115]
	v_mfma_f32_16x16x32_bf16 v[100:103], v[172:175], v[196:199], v[100:103]
	v_mfma_f32_16x16x32_bf16 v[96:99], v[180:183], v[196:199], v[96:99]
	v_mfma_f32_16x16x32_bf16 v[84:87], v[172:175], v[204:207], v[84:87]
	v_mfma_f32_16x16x32_bf16 v[80:83], v[180:183], v[204:207], v[80:83]
	v_mfma_f32_16x16x32_bf16 v[68:71], v[172:175], v[212:215], v[68:71]
	v_mfma_f32_16x16x32_bf16 v[64:67], v[180:183], v[212:215], v[64:67]
	s_nop 0
	s_barrier
	s_add_i32 s58, s63, s84
	v_lshl_add_u64 v[216:217], v[216:217], 0, s[10:11]
	s_mov_b32 m0, s58
	ds_read_b128 v[184:187], v150 offset:49152
	ds_read_b128 v[188:191], v150 offset:50176
	ds_read_b128 v[192:195], v150 offset:51200
	ds_read_b128 v[196:199], v150 offset:52224
	ds_read_b128 v[200:203], v150 offset:53248
	ds_read_b128 v[204:207], v150 offset:54272
	ds_read_b128 v[208:211], v150 offset:55296
	ds_read_b128 v[212:215], v150 offset:56320
	global_load_lds_dwordx4 v[216:217], off
	s_add_i32 m0, s58, 0x2000
	s_add_u32 s58, s66, 0x20080
	v_lshl_add_u64 v[216:217], v[218:219], 0, s[10:11]
	s_addc_u32 s59, s67, 0
	s_add_i32 s63, s80, s84
	global_load_lds_dwordx4 v[216:217], off
	v_lshl_add_u64 v[216:217], s[58:59], 0, v[132:133]
	s_mov_b32 m0, s63
	s_nop 0
	global_load_lds_dwordx4 v[216:217], off
	v_lshl_add_u64 v[216:217], s[58:59], 0, v[128:129]
	s_add_i32 m0, s63, 0x2000
	s_nop 0
	global_load_lds_dwordx4 v[216:217], off
	v_lshl_add_u64 v[216:217], v[220:221], 0, s[10:11]
	s_mov_b32 m0, s73
	s_nop 0
	global_load_lds_dwordx4 v[216:217], off
	v_lshl_add_u64 v[216:217], v[222:223], 0, s[10:11]
	s_mov_b32 m0, s74
	s_nop 0
	global_load_lds_dwordx4 v[216:217], off
	s_waitcnt vmcnt(8)
	s_waitcnt lgkmcnt(0)
	s_barrier
	s_nop 0
	s_waitcnt lgkmcnt(0)
	v_mfma_f32_16x16x32_bf16 v[60:63], v[152:155], v[184:187], v[60:63]
	v_mfma_f32_16x16x32_bf16 v[56:59], v[160:163], v[184:187], v[56:59]
	v_mfma_f32_16x16x32_bf16 v[44:47], v[152:155], v[192:195], v[44:47]
	v_mfma_f32_16x16x32_bf16 v[40:43], v[160:163], v[192:195], v[40:43]
	v_mfma_f32_16x16x32_bf16 v[28:31], v[152:155], v[200:203], v[28:31]
	v_mfma_f32_16x16x32_bf16 v[24:27], v[160:163], v[200:203], v[24:27]
	v_mfma_f32_16x16x32_bf16 v[12:15], v[152:155], v[208:211], v[12:15]
	v_mfma_f32_16x16x32_bf16 v[8:11], v[160:163], v[208:211], v[8:11]
	v_mfma_f32_16x16x32_bf16 v[60:63], v[156:159], v[188:191], v[60:63]
	v_mfma_f32_16x16x32_bf16 v[56:59], v[164:167], v[188:191], v[56:59]
	v_mfma_f32_16x16x32_bf16 v[44:47], v[156:159], v[196:199], v[44:47]
	v_mfma_f32_16x16x32_bf16 v[40:43], v[164:167], v[196:199], v[40:43]
	v_mfma_f32_16x16x32_bf16 v[28:31], v[156:159], v[204:207], v[28:31]
	v_mfma_f32_16x16x32_bf16 v[24:27], v[164:167], v[204:207], v[24:27]
	v_mfma_f32_16x16x32_bf16 v[12:15], v[156:159], v[212:215], v[12:15]
	v_mfma_f32_16x16x32_bf16 v[8:11], v[164:167], v[212:215], v[8:11]
	s_nop 0
	s_nop 0
	v_mfma_f32_16x16x32_bf16 v[52:55], v[168:171], v[184:187], v[52:55]
	v_mfma_f32_16x16x32_bf16 v[48:51], v[176:179], v[184:187], v[48:51]
	v_mfma_f32_16x16x32_bf16 v[36:39], v[168:171], v[192:195], v[36:39]
	v_mfma_f32_16x16x32_bf16 v[32:35], v[176:179], v[192:195], v[32:35]
	v_mfma_f32_16x16x32_bf16 v[20:23], v[168:171], v[200:203], v[20:23]
	v_mfma_f32_16x16x32_bf16 v[16:19], v[176:179], v[200:203], v[16:19]
	v_mfma_f32_16x16x32_bf16 v[4:7], v[168:171], v[208:211], v[4:7]
	v_mfma_f32_16x16x32_bf16 v[0:3], v[176:179], v[208:211], v[0:3]
	v_mfma_f32_16x16x32_bf16 v[52:55], v[172:175], v[188:191], v[52:55]
	v_mfma_f32_16x16x32_bf16 v[48:51], v[180:183], v[188:191], v[48:51]
	v_mfma_f32_16x16x32_bf16 v[36:39], v[172:175], v[196:199], v[36:39]
	v_mfma_f32_16x16x32_bf16 v[32:35], v[180:183], v[196:199], v[32:35]
	v_mfma_f32_16x16x32_bf16 v[20:23], v[172:175], v[204:207], v[20:23]
	v_mfma_f32_16x16x32_bf16 v[16:19], v[180:183], v[204:207], v[16:19]
	v_mfma_f32_16x16x32_bf16 v[4:7], v[172:175], v[212:215], v[4:7]
	v_mfma_f32_16x16x32_bf16 v[0:3], v[180:183], v[212:215], v[0:3]
	s_nop 0
	s_barrier
	s_add_i32 s62, s62, 2
	s_add_u32 s18, s18, 0x100
	s_addc_u32 s19, s19, 0
	s_add_u32 s42, s42, 0x100
	s_addc_u32 s43, s43, 0
	s_cmp_gt_u32 s62, 5
	s_cbranch_scc0 .LBB0_917
	s_and_b64 vcc, exec, s[22:23]
	s_cbranch_vccz .LBB0_920
	s_barrier

.LBB0_1428:
	ds_read_b128 v[144:147], v155
	ds_read_b128 v[148:151], v155 offset:1024
	ds_read_b128 v[158:161], v155 offset:2048
	ds_read_b128 v[162:165], v155 offset:3072
	ds_read_b128 v[166:169], v156
	ds_read_b128 v[170:173], v156 offset:1024
	ds_read_b128 v[174:177], v156 offset:2048
	ds_read_b128 v[178:181], v156 offset:3072
	s_add_u32 s8, s6, 0xfffe0080
	s_addc_u32 s9, s7, -1
	s_cmp_eq_u32 s42, 4
	s_cselect_b32 s11, s24, s9
	s_cselect_b32 s10, s25, s8
	s_cselect_b32 s9, s21, s35
	s_cselect_b32 s8, s33, s34
	v_lshl_add_u64 v[214:215], s[6:7], 0, v[136:137]
	s_add_i32 m0, s72, 0xc000
	ds_read_b128 v[182:185], v157
	ds_read_b128 v[186:189], v157 offset:1024
	ds_read_b128 v[190:193], v157 offset:2048
	ds_read_b128 v[194:197], v157 offset:3072
	ds_read_b128 v[198:201], v157 offset:4096
	ds_read_b128 v[202:205], v157 offset:5120
	ds_read_b128 v[206:209], v157 offset:6144
	ds_read_b128 v[210:213], v157 offset:7168
	global_load_lds_dwordx4 v[214:215], off
	v_lshl_add_u64 v[214:215], s[6:7], 0, v[138:139]
	s_add_i32 m0, s72, 0xe000
	s_nop 0
	global_load_lds_dwordx4 v[214:215], off
	s_waitcnt vmcnt(8)
	s_waitcnt lgkmcnt(0)
	s_barrier
	s_nop 0
	s_waitcnt lgkmcnt(0)
	v_mfma_f32_16x16x32_bf16 v[124:127], v[144:147], v[182:185], v[124:127]
	v_mfma_f32_16x16x32_bf16 v[120:123], v[158:161], v[182:185], v[120:123]
	v_mfma_f32_16x16x32_bf16 v[108:111], v[144:147], v[190:193], v[108:111]
	v_mfma_f32_16x16x32_bf16 v[104:107], v[158:161], v[190:193], v[104:107]
	v_mfma_f32_16x16x32_bf16 v[92:95], v[144:147], v[198:201], v[92:95]
	v_mfma_f32_16x16x32_bf16 v[88:91], v[158:161], v[198:201], v[88:91]
	v_mfma_f32_16x16x32_bf16 v[76:79], v[144:147], v[206:209], v[76:79]
	v_mfma_f32_16x16x32_bf16 v[72:75], v[158:161], v[206:209], v[72:75]
	v_mfma_f32_16x16x32_bf16 v[124:127], v[148:151], v[186:189], v[124:127]
	v_mfma_f32_16x16x32_bf16 v[120:123], v[162:165], v[186:189], v[120:123]
	v_mfma_f32_16x16x32_bf16 v[108:111], v[148:151], v[194:197], v[108:111]
	v_mfma_f32_16x16x32_bf16 v[104:107], v[162:165], v[194:197], v[104:107]
	v_mfma_f32_16x16x32_bf16 v[92:95], v[148:151], v[202:205], v[92:95]
	v_mfma_f32_16x16x32_bf16 v[88:91], v[162:165], v[202:205], v[88:91]
	v_mfma_f32_16x16x32_bf16 v[76:79], v[148:151], v[210:213], v[76:79]
	v_mfma_f32_16x16x32_bf16 v[72:75], v[162:165], v[210:213], v[72:75]
	s_nop 0
	s_nop 0
	v_mfma_f32_16x16x32_bf16 v[116:119], v[166:169], v[182:185], v[116:119]
	v_mfma_f32_16x16x32_bf16 v[112:115], v[174:177], v[182:185], v[112:115]
	v_mfma_f32_16x16x32_bf16 v[100:103], v[166:169], v[190:193], v[100:103]
	v_mfma_f32_16x16x32_bf16 v[96:99], v[174:177], v[190:193], v[96:99]
	v_mfma_f32_16x16x32_bf16 v[84:87], v[166:169], v[198:201], v[84:87]
	v_mfma_f32_16x16x32_bf16 v[80:83], v[174:177], v[198:201], v[80:83]
	v_mfma_f32_16x16x32_bf16 v[68:71], v[166:169], v[206:209], v[68:71]
	v_mfma_f32_16x16x32_bf16 v[64:67], v[174:177], v[206:209], v[64:67]
	v_mfma_f32_16x16x32_bf16 v[116:119], v[170:173], v[186:189], v[116:119]
	v_mfma_f32_16x16x32_bf16 v[112:115], v[178:181], v[186:189], v[112:115]
	v_mfma_f32_16x16x32_bf16 v[100:103], v[170:173], v[194:197], v[100:103]
	v_mfma_f32_16x16x32_bf16 v[96:99], v[178:181], v[194:197], v[96:99]
	v_mfma_f32_16x16x32_bf16 v[84:87], v[170:173], v[202:205], v[84:87]
	v_mfma_f32_16x16x32_bf16 v[80:83], v[178:181], v[202:205], v[80:83]
	v_mfma_f32_16x16x32_bf16 v[68:71], v[170:173], v[210:213], v[68:71]
	v_mfma_f32_16x16x32_bf16 v[64:67], v[178:181], v[210:213], v[64:67]
	s_nop 0
	s_barrier
	s_add_i32 s43, s81, s3
	v_lshl_add_u64 v[214:215], s[8:9], 0, v[128:129]
	s_mov_b32 m0, s43
	ds_read_b128 v[182:185], v157 offset:16384
	ds_read_b128 v[186:189], v157 offset:17408
	ds_read_b128 v[190:193], v157 offset:18432
	ds_read_b128 v[194:197], v157 offset:19456
	ds_read_b128 v[198:201], v157 offset:20480
	ds_read_b128 v[202:205], v157 offset:21504
	ds_read_b128 v[206:209], v157 offset:22528
	ds_read_b128 v[210:213], v157 offset:23552
	global_load_lds_dwordx4 v[214:215], off
	s_add_i32 m0, s43, 0x2000
	s_add_u32 s58, s8, 0x20000
	v_lshl_add_u64 v[216:217], s[8:9], 0, v[130:131]
	s_addc_u32 s59, s9, 0
	s_add_i32 s43, s82, s3
	global_load_lds_dwordx4 v[216:217], off
	v_lshl_add_u64 v[218:219], s[58:59], 0, v[128:129]
	s_mov_b32 m0, s43
	v_lshl_add_u64 v[220:221], s[10:11], 0, v[132:133]
	global_load_lds_dwordx4 v[218:219], off
	v_lshl_add_u64 v[218:219], s[58:59], 0, v[130:131]
	s_add_i32 m0, s43, 0x2000
	s_nop 0
	global_load_lds_dwordx4 v[218:219], off
	v_lshl_add_u64 v[218:219], s[10:11], 0, v[134:135]
	s_mov_b32 m0, s72
	s_nop 0
	global_load_lds_dwordx4 v[218:219], off
	s_mov_b32 m0, s73
	s_nop 0
	global_load_lds_dwordx4 v[220:221], off
	s_waitcnt vmcnt(8)
	s_waitcnt lgkmcnt(0)
	s_barrier
	s_nop 0
	s_waitcnt lgkmcnt(0)
	v_mfma_f32_16x16x32_bf16 v[60:63], v[144:147], v[182:185], v[60:63]
	v_mfma_f32_16x16x32_bf16 v[56:59], v[158:161], v[182:185], v[56:59]
	v_mfma_f32_16x16x32_bf16 v[44:47], v[144:147], v[190:193], v[44:47]
	v_mfma_f32_16x16x32_bf16 v[40:43], v[158:161], v[190:193], v[40:43]
	v_mfma_f32_16x16x32_bf16 v[28:31], v[144:147], v[198:201], v[28:31]
	v_mfma_f32_16x16x32_bf16 v[24:27], v[158:161], v[198:201], v[24:27]
	v_mfma_f32_16x16x32_bf16 v[12:15], v[144:147], v[206:209], v[12:15]
	v_mfma_f32_16x16x32_bf16 v[8:11], v[158:161], v[206:209], v[8:11]
	v_mfma_f32_16x16x32_bf16 v[60:63], v[148:151], v[186:189], v[60:63]
	v_mfma_f32_16x16x32_bf16 v[56:59], v[162:165], v[186:189], v[56:59]
	v_mfma_f32_16x16x32_bf16 v[44:47], v[148:151], v[194:197], v[44:47]
	v_mfma_f32_16x16x32_bf16 v[40:43], v[162:165], v[194:197], v[40:43]
	v_mfma_f32_16x16x32_bf16 v[28:31], v[148:151], v[202:205], v[28:31]
	v_mfma_f32_16x16x32_bf16 v[24:27], v[162:165], v[202:205], v[24:27]
	v_mfma_f32_16x16x32_bf16 v[12:15], v[148:151], v[210:213], v[12:15]
	v_mfma_f32_16x16x32_bf16 v[8:11], v[162:165], v[210:213], v[8:11]
	s_nop 0
	s_nop 0
	v_mfma_f32_16x16x32_bf16 v[52:55], v[166:169], v[182:185], v[52:55]
	v_mfma_f32_16x16x32_bf16 v[48:51], v[174:177], v[182:185], v[48:51]
	v_mfma_f32_16x16x32_bf16 v[36:39], v[166:169], v[190:193], v[36:39]
	v_mfma_f32_16x16x32_bf16 v[32:35], v[174:177], v[190:193], v[32:35]
	v_mfma_f32_16x16x32_bf16 v[20:23], v[166:169], v[198:201], v[20:23]
	v_mfma_f32_16x16x32_bf16 v[16:19], v[174:177], v[198:201], v[16:19]
	v_mfma_f32_16x16x32_bf16 v[4:7], v[166:169], v[206:209], v[4:7]
	v_mfma_f32_16x16x32_bf16 v[0:3], v[174:177], v[206:209], v[0:3]
	v_mfma_f32_16x16x32_bf16 v[52:55], v[170:173], v[186:189], v[52:55]
	v_mfma_f32_16x16x32_bf16 v[48:51], v[178:181], v[186:189], v[48:51]
	v_mfma_f32_16x16x32_bf16 v[36:39], v[170:173], v[194:197], v[36:39]
	v_mfma_f32_16x16x32_bf16 v[32:35], v[178:181], v[194:197], v[32:35]
	v_mfma_f32_16x16x32_bf16 v[20:23], v[170:173], v[202:205], v[20:23]
	v_mfma_f32_16x16x32_bf16 v[16:19], v[178:181], v[202:205], v[16:19]
	v_mfma_f32_16x16x32_bf16 v[4:7], v[170:173], v[210:213], v[4:7]
	v_mfma_f32_16x16x32_bf16 v[0:3], v[178:181], v[210:213], v[0:3]
	s_nop 0
	s_barrier
	s_add_i32 s43, 0, 0x18000
	s_add_i32 s58, 0, 0x1c000
	v_add_u32_e32 v162, s43, v153
	v_add_u32_e32 v178, s58, v153
	ds_read_b128 v[144:147], v162
	ds_read_b128 v[148:151], v162 offset:1024
	ds_read_b128 v[158:161], v162 offset:2048
	ds_read_b128 v[162:165], v162 offset:3072
	ds_read_b128 v[166:169], v178
	ds_read_b128 v[170:173], v178 offset:1024
	ds_read_b128 v[174:177], v178 offset:2048
	ds_read_b128 v[178:181], v178 offset:3072
	s_add_u32 s10, s10, 0x20000
	s_addc_u32 s11, s11, 0
	s_mov_b32 m0, s74
	v_lshl_add_u64 v[222:223], s[10:11], 0, v[134:135]
	ds_read_b128 v[182:185], v157 offset:32768
	ds_read_b128 v[186:189], v157 offset:33792
	ds_read_b128 v[190:193], v157 offset:34816
	ds_read_b128 v[194:197], v157 offset:35840
	ds_read_b128 v[198:201], v157 offset:36864
	ds_read_b128 v[202:205], v157 offset:37888
	ds_read_b128 v[206:209], v157 offset:38912
	ds_read_b128 v[210:213], v157 offset:39936
	global_load_lds_dwordx4 v[222:223], off
	v_lshl_add_u64 v[222:223], s[10:11], 0, v[132:133]
	s_mov_b32 m0, s75
	s_nop 0
	global_load_lds_dwordx4 v[222:223], off
	s_waitcnt vmcnt(8)
	s_waitcnt lgkmcnt(0)
	s_barrier
	s_nop 0
	s_waitcnt lgkmcnt(0)
	v_mfma_f32_16x16x32_bf16 v[124:127], v[144:147], v[182:185], v[124:127]
	v_mfma_f32_16x16x32_bf16 v[120:123], v[158:161], v[182:185], v[120:123]
	v_mfma_f32_16x16x32_bf16 v[108:111], v[144:147], v[190:193], v[108:111]
	v_mfma_f32_16x16x32_bf16 v[104:107], v[158:161], v[190:193], v[104:107]
	v_mfma_f32_16x16x32_bf16 v[92:95], v[144:147], v[198:201], v[92:95]
	v_mfma_f32_16x16x32_bf16 v[88:91], v[158:161], v[198:201], v[88:91]
	v_mfma_f32_16x16x32_bf16 v[76:79], v[144:147], v[206:209], v[76:79]
	v_mfma_f32_16x16x32_bf16 v[72:75], v[158:161], v[206:209], v[72:75]
	v_mfma_f32_16x16x32_bf16 v[124:127], v[148:151], v[186:189], v[124:127]
	v_mfma_f32_16x16x32_bf16 v[120:123], v[162:165], v[186:189], v[120:123]
	v_mfma_f32_16x16x32_bf16 v[108:111], v[148:151], v[194:197], v[108:111]
	v_mfma_f32_16x16x32_bf16 v[104:107], v[162:165], v[194:197], v[104:107]
	v_mfma_f32_16x16x32_bf16 v[92:95], v[148:151], v[202:205], v[92:95]
	v_mfma_f32_16x16x32_bf16 v[88:91], v[162:165], v[202:205], v[88:91]
	v_mfma_f32_16x16x32_bf16 v[76:79], v[148:151], v[210:213], v[76:79]
	v_mfma_f32_16x16x32_bf16 v[72:75], v[162:165], v[210:213], v[72:75]
	s_nop 0
	s_nop 0
	v_mfma_f32_16x16x32_bf16 v[116:119], v[166:169], v[182:185], v[116:119]
	v_mfma_f32_16x16x32_bf16 v[112:115], v[174:177], v[182:185], v[112:115]
	v_mfma_f32_16x16x32_bf16 v[100:103], v[166:169], v[190:193], v[100:103]
	v_mfma_f32_16x16x32_bf16 v[96:99], v[174:177], v[190:193], v[96:99]
	v_mfma_f32_16x16x32_bf16 v[84:87], v[166:169], v[198:201], v[84:87]
	v_mfma_f32_16x16x32_bf16 v[80:83], v[174:177], v[198:201], v[80:83]
	v_mfma_f32_16x16x32_bf16 v[68:71], v[166:169], v[206:209], v[68:71]
	v_mfma_f32_16x16x32_bf16 v[64:67], v[174:177], v[206:209], v[64:67]
	v_mfma_f32_16x16x32_bf16 v[116:119], v[170:173], v[186:189], v[116:119]
	v_mfma_f32_16x16x32_bf16 v[112:115], v[178:181], v[186:189], v[112:115]
	v_mfma_f32_16x16x32_bf16 v[100:103], v[170:173], v[194:197], v[100:103]
	v_mfma_f32_16x16x32_bf16 v[96:99], v[178:181], v[194:197], v[96:99]
	v_mfma_f32_16x16x32_bf16 v[84:87], v[170:173], v[202:205], v[84:87]
	v_mfma_f32_16x16x32_bf16 v[80:83], v[178:181], v[202:205], v[80:83]
	v_mfma_f32_16x16x32_bf16 v[68:71], v[170:173], v[210:213], v[68:71]
	v_mfma_f32_16x16x32_bf16 v[64:67], v[178:181], v[210:213], v[64:67]
	s_nop 0
	s_barrier
	s_add_i32 s10, s43, s3
	v_lshl_add_u64 v[214:215], v[214:215], 0, s[18:19]
	s_mov_b32 m0, s10
	ds_read_b128 v[182:185], v157 offset:49152
	ds_read_b128 v[186:189], v157 offset:50176
	ds_read_b128 v[190:193], v157 offset:51200
	ds_read_b128 v[194:197], v157 offset:52224
	ds_read_b128 v[198:201], v157 offset:53248
	ds_read_b128 v[202:205], v157 offset:54272
	ds_read_b128 v[206:209], v157 offset:55296
	ds_read_b128 v[210:213], v157 offset:56320
	global_load_lds_dwordx4 v[214:215], off
	s_add_i32 m0, s10, 0x2000
	s_add_u32 s8, s8, 0x20080
	v_lshl_add_u64 v[214:215], v[216:217], 0, s[18:19]
	s_addc_u32 s9, s9, 0
	s_add_i32 s10, s58, s3
	global_load_lds_dwordx4 v[214:215], off
	v_lshl_add_u64 v[214:215], s[8:9], 0, v[128:129]
	s_mov_b32 m0, s10
	s_nop 0
	global_load_lds_dwordx4 v[214:215], off
	v_lshl_add_u64 v[214:215], s[8:9], 0, v[130:131]
	s_add_i32 m0, s10, 0x2000
	s_nop 0
	global_load_lds_dwordx4 v[214:215], off
	v_lshl_add_u64 v[214:215], v[218:219], 0, s[18:19]
	s_mov_b32 m0, s78
	s_nop 0
	global_load_lds_dwordx4 v[214:215], off
	v_lshl_add_u64 v[214:215], v[220:221], 0, s[18:19]
	s_mov_b32 m0, s79
	s_nop 0
	global_load_lds_dwordx4 v[214:215], off
	s_waitcnt vmcnt(8)
	s_waitcnt lgkmcnt(0)
	s_barrier
	s_nop 0
	s_waitcnt lgkmcnt(0)
	v_mfma_f32_16x16x32_bf16 v[60:63], v[144:147], v[182:185], v[60:63]
	v_mfma_f32_16x16x32_bf16 v[56:59], v[158:161], v[182:185], v[56:59]
	v_mfma_f32_16x16x32_bf16 v[44:47], v[144:147], v[190:193], v[44:47]
	v_mfma_f32_16x16x32_bf16 v[40:43], v[158:161], v[190:193], v[40:43]
	v_mfma_f32_16x16x32_bf16 v[28:31], v[144:147], v[198:201], v[28:31]
	v_mfma_f32_16x16x32_bf16 v[24:27], v[158:161], v[198:201], v[24:27]
	v_mfma_f32_16x16x32_bf16 v[12:15], v[144:147], v[206:209], v[12:15]
	v_mfma_f32_16x16x32_bf16 v[8:11], v[158:161], v[206:209], v[8:11]
	v_mfma_f32_16x16x32_bf16 v[60:63], v[148:151], v[186:189], v[60:63]
	v_mfma_f32_16x16x32_bf16 v[56:59], v[162:165], v[186:189], v[56:59]
	v_mfma_f32_16x16x32_bf16 v[44:47], v[148:151], v[194:197], v[44:47]
	v_mfma_f32_16x16x32_bf16 v[40:43], v[162:165], v[194:197], v[40:43]
	v_mfma_f32_16x16x32_bf16 v[28:31], v[148:151], v[202:205], v[28:31]
	v_mfma_f32_16x16x32_bf16 v[24:27], v[162:165], v[202:205], v[24:27]
	v_mfma_f32_16x16x32_bf16 v[12:15], v[148:151], v[210:213], v[12:15]
	v_mfma_f32_16x16x32_bf16 v[8:11], v[162:165], v[210:213], v[8:11]
	s_nop 0
	s_nop 0
	v_mfma_f32_16x16x32_bf16 v[52:55], v[166:169], v[182:185], v[52:55]
	v_mfma_f32_16x16x32_bf16 v[48:51], v[174:177], v[182:185], v[48:51]
	v_mfma_f32_16x16x32_bf16 v[36:39], v[166:169], v[190:193], v[36:39]
	v_mfma_f32_16x16x32_bf16 v[32:35], v[174:177], v[190:193], v[32:35]
	v_mfma_f32_16x16x32_bf16 v[20:23], v[166:169], v[198:201], v[20:23]
	v_mfma_f32_16x16x32_bf16 v[16:19], v[174:177], v[198:201], v[16:19]
	v_mfma_f32_16x16x32_bf16 v[4:7], v[166:169], v[206:209], v[4:7]
	v_mfma_f32_16x16x32_bf16 v[0:3], v[174:177], v[206:209], v[0:3]
	v_mfma_f32_16x16x32_bf16 v[52:55], v[170:173], v[186:189], v[52:55]
	v_mfma_f32_16x16x32_bf16 v[48:51], v[178:181], v[186:189], v[48:51]
	v_mfma_f32_16x16x32_bf16 v[36:39], v[170:173], v[194:197], v[36:39]
	v_mfma_f32_16x16x32_bf16 v[32:35], v[178:181], v[194:197], v[32:35]
	v_mfma_f32_16x16x32_bf16 v[20:23], v[170:173], v[202:205], v[20:23]
	v_mfma_f32_16x16x32_bf16 v[16:19], v[178:181], v[202:205], v[16:19]
	v_mfma_f32_16x16x32_bf16 v[4:7], v[170:173], v[210:213], v[4:7]
	v_mfma_f32_16x16x32_bf16 v[0:3], v[178:181], v[210:213], v[0:3]
	s_nop 0
	s_barrier
	s_add_i32 s42, s42, 2
	s_add_u32 s6, s6, 0x100
	s_addc_u32 s7, s7, 0
	s_add_u32 s34, s34, 0x100
	s_addc_u32 s35, s35, 0
	s_cmp_gt_u32 s42, 5
	s_cbranch_scc0 .LBB0_1428
	s_and_b64 vcc, exec, s[16:17]
	s_cbranch_vccz .LBB0_1431
	s_barrier

.LBB0_1786:
	ds_read_b128 v[112:115], v208
	ds_read_b128 v[120:123], v208 offset:1024
	ds_read_b128 v[128:131], v208 offset:2048
	ds_read_b128 v[132:135], v208 offset:3072
	ds_read_b128 v[144:147], v209
	ds_read_b128 v[148:151], v209 offset:1024
	ds_read_b128 v[168:171], v209 offset:2048
	ds_read_b128 v[172:175], v209 offset:3072
	s_add_u32 s58, s70, 0xfffc0080
	s_addc_u32 s59, s71, -1
	s_cmp_eq_u32 s90, 12
	s_cselect_b32 s75, s1, s59
	s_cselect_b32 s74, s16, s58
	s_cselect_b32 s73, s61, s89
	s_cselect_b32 s72, s63, s69
	v_lshl_add_u64 v[236:237], s[70:71], 0, v[160:161]
	s_add_i32 m0, s24, 0xc000
	ds_read_b128 v[176:179], v210
	ds_read_b128 v[180:183], v210 offset:1024
	ds_read_b128 v[184:187], v210 offset:2048
	ds_read_b128 v[216:219], v210 offset:3072
	ds_read_b128 v[220:223], v210 offset:4096
	ds_read_b128 v[224:227], v210 offset:5120
	ds_read_b128 v[228:231], v210 offset:6144
	ds_read_b128 v[232:235], v210 offset:7168
	global_load_lds_dwordx4 v[236:237], off
	v_lshl_add_u64 v[236:237], s[70:71], 0, v[162:163]
	s_add_i32 m0, s24, 0xe000
	s_nop 0
	global_load_lds_dwordx4 v[236:237], off
	s_waitcnt vmcnt(8)
	s_waitcnt lgkmcnt(0)
	s_barrier
	s_nop 0
	s_waitcnt lgkmcnt(0)
	v_mfma_f32_16x16x32_bf16 v[140:143], v[112:115], v[176:179], v[140:143]
	v_mfma_f32_16x16x32_bf16 v[136:139], v[128:131], v[176:179], v[136:139]
	v_mfma_f32_16x16x32_bf16 v[108:111], v[112:115], v[184:187], v[108:111]
	v_mfma_f32_16x16x32_bf16 v[104:107], v[128:131], v[184:187], v[104:107]
	v_mfma_f32_16x16x32_bf16 v[92:95], v[112:115], v[220:223], v[92:95]
	v_mfma_f32_16x16x32_bf16 v[88:91], v[128:131], v[220:223], v[88:91]
	v_mfma_f32_16x16x32_bf16 v[76:79], v[112:115], v[228:231], v[76:79]
	v_mfma_f32_16x16x32_bf16 v[72:75], v[128:131], v[228:231], v[72:75]
	v_mfma_f32_16x16x32_bf16 v[140:143], v[120:123], v[180:183], v[140:143]
	v_mfma_f32_16x16x32_bf16 v[136:139], v[132:135], v[180:183], v[136:139]
	v_mfma_f32_16x16x32_bf16 v[108:111], v[120:123], v[216:219], v[108:111]
	v_mfma_f32_16x16x32_bf16 v[104:107], v[132:135], v[216:219], v[104:107]
	v_mfma_f32_16x16x32_bf16 v[92:95], v[120:123], v[224:227], v[92:95]
	v_mfma_f32_16x16x32_bf16 v[88:91], v[132:135], v[224:227], v[88:91]
	v_mfma_f32_16x16x32_bf16 v[76:79], v[120:123], v[232:235], v[76:79]
	v_mfma_f32_16x16x32_bf16 v[72:75], v[132:135], v[232:235], v[72:75]
	s_nop 0
	s_nop 0
	v_mfma_f32_16x16x32_bf16 v[124:127], v[144:147], v[176:179], v[124:127]
	v_mfma_f32_16x16x32_bf16 v[116:119], v[168:171], v[176:179], v[116:119]
	v_mfma_f32_16x16x32_bf16 v[100:103], v[144:147], v[184:187], v[100:103]
	v_mfma_f32_16x16x32_bf16 v[96:99], v[168:171], v[184:187], v[96:99]
	v_mfma_f32_16x16x32_bf16 v[84:87], v[144:147], v[220:223], v[84:87]
	v_mfma_f32_16x16x32_bf16 v[80:83], v[168:171], v[220:223], v[80:83]
	v_mfma_f32_16x16x32_bf16 v[68:71], v[144:147], v[228:231], v[68:71]
	v_mfma_f32_16x16x32_bf16 v[64:67], v[168:171], v[228:231], v[64:67]
	v_mfma_f32_16x16x32_bf16 v[124:127], v[148:151], v[180:183], v[124:127]
	v_mfma_f32_16x16x32_bf16 v[116:119], v[172:175], v[180:183], v[116:119]
	v_mfma_f32_16x16x32_bf16 v[100:103], v[148:151], v[216:219], v[100:103]
	v_mfma_f32_16x16x32_bf16 v[96:99], v[172:175], v[216:219], v[96:99]
	v_mfma_f32_16x16x32_bf16 v[84:87], v[148:151], v[224:227], v[84:87]
	v_mfma_f32_16x16x32_bf16 v[80:83], v[172:175], v[224:227], v[80:83]
	v_mfma_f32_16x16x32_bf16 v[68:71], v[148:151], v[232:235], v[68:71]
	v_mfma_f32_16x16x32_bf16 v[64:67], v[172:175], v[232:235], v[64:67]
	s_nop 0
	s_barrier
	s_add_i32 s58, s84, s3
	v_lshl_add_u64 v[236:237], s[72:73], 0, v[152:153]
	s_mov_b32 m0, s58
	ds_read_b128 v[176:179], v210 offset:16384
	ds_read_b128 v[180:183], v210 offset:17408
	ds_read_b128 v[184:187], v210 offset:18432
	ds_read_b128 v[216:219], v210 offset:19456
	ds_read_b128 v[220:223], v210 offset:20480
	ds_read_b128 v[224:227], v210 offset:21504
	ds_read_b128 v[228:231], v210 offset:22528
	ds_read_b128 v[232:235], v210 offset:23552
	global_load_lds_dwordx4 v[236:237], off
	s_add_i32 m0, s58, 0x2000
	s_add_u32 s58, s72, 0x40000
	v_lshl_add_u64 v[238:239], s[72:73], 0, v[154:155]
	s_addc_u32 s59, s73, 0
	s_add_i32 s91, s85, s3
	global_load_lds_dwordx4 v[238:239], off
	v_lshl_add_u64 v[240:241], s[58:59], 0, v[152:153]
	s_mov_b32 m0, s91
	v_lshl_add_u64 v[242:243], s[74:75], 0, v[156:157]
	global_load_lds_dwordx4 v[240:241], off
	v_lshl_add_u64 v[240:241], s[58:59], 0, v[154:155]
	s_add_i32 m0, s91, 0x2000
	s_nop 0
	global_load_lds_dwordx4 v[240:241], off
	v_lshl_add_u64 v[240:241], s[74:75], 0, v[158:159]
	s_mov_b32 m0, s24
	s_nop 0
	global_load_lds_dwordx4 v[240:241], off
	s_mov_b32 m0, s25
	s_nop 0
	global_load_lds_dwordx4 v[242:243], off
	s_waitcnt vmcnt(8)
	s_waitcnt lgkmcnt(0)
	s_barrier
	s_nop 0
	s_waitcnt lgkmcnt(0)
	v_mfma_f32_16x16x32_bf16 v[60:63], v[112:115], v[176:179], v[60:63]
	v_mfma_f32_16x16x32_bf16 v[56:59], v[128:131], v[176:179], v[56:59]
	v_mfma_f32_16x16x32_bf16 v[44:47], v[112:115], v[184:187], v[44:47]
	v_mfma_f32_16x16x32_bf16 v[40:43], v[128:131], v[184:187], v[40:43]
	v_mfma_f32_16x16x32_bf16 v[28:31], v[112:115], v[220:223], v[28:31]
	v_mfma_f32_16x16x32_bf16 v[24:27], v[128:131], v[220:223], v[24:27]
	v_mfma_f32_16x16x32_bf16 v[12:15], v[112:115], v[228:231], v[12:15]
	v_mfma_f32_16x16x32_bf16 v[8:11], v[128:131], v[228:231], v[8:11]
	v_mfma_f32_16x16x32_bf16 v[60:63], v[120:123], v[180:183], v[60:63]
	v_mfma_f32_16x16x32_bf16 v[56:59], v[132:135], v[180:183], v[56:59]
	v_mfma_f32_16x16x32_bf16 v[44:47], v[120:123], v[216:219], v[44:47]
	v_mfma_f32_16x16x32_bf16 v[40:43], v[132:135], v[216:219], v[40:43]
	v_mfma_f32_16x16x32_bf16 v[28:31], v[120:123], v[224:227], v[28:31]
	v_mfma_f32_16x16x32_bf16 v[24:27], v[132:135], v[224:227], v[24:27]
	v_mfma_f32_16x16x32_bf16 v[12:15], v[120:123], v[232:235], v[12:15]
	v_mfma_f32_16x16x32_bf16 v[8:11], v[132:135], v[232:235], v[8:11]
	s_nop 0
	s_nop 0
	v_mfma_f32_16x16x32_bf16 v[52:55], v[144:147], v[176:179], v[52:55]
	v_mfma_f32_16x16x32_bf16 v[48:51], v[168:171], v[176:179], v[48:51]
	v_mfma_f32_16x16x32_bf16 v[36:39], v[144:147], v[184:187], v[36:39]
	v_mfma_f32_16x16x32_bf16 v[32:35], v[168:171], v[184:187], v[32:35]
	v_mfma_f32_16x16x32_bf16 v[20:23], v[144:147], v[220:223], v[20:23]
	v_mfma_f32_16x16x32_bf16 v[16:19], v[168:171], v[220:223], v[16:19]
	v_mfma_f32_16x16x32_bf16 v[4:7], v[144:147], v[228:231], v[4:7]
	v_mfma_f32_16x16x32_bf16 v[0:3], v[168:171], v[228:231], v[0:3]
	v_mfma_f32_16x16x32_bf16 v[52:55], v[148:151], v[180:183], v[52:55]
	v_mfma_f32_16x16x32_bf16 v[48:51], v[172:175], v[180:183], v[48:51]
	v_mfma_f32_16x16x32_bf16 v[36:39], v[148:151], v[216:219], v[36:39]
	v_mfma_f32_16x16x32_bf16 v[32:35], v[172:175], v[216:219], v[32:35]
	v_mfma_f32_16x16x32_bf16 v[20:23], v[148:151], v[224:227], v[20:23]
	v_mfma_f32_16x16x32_bf16 v[16:19], v[172:175], v[224:227], v[16:19]
	v_mfma_f32_16x16x32_bf16 v[4:7], v[148:151], v[232:235], v[4:7]
	v_mfma_f32_16x16x32_bf16 v[0:3], v[172:175], v[232:235], v[0:3]
	s_nop 0
	s_barrier
	s_add_i32 s91, 0, 0x18000
	s_add_i32 s92, 0, 0x1c000
	v_add_u32_e32 v132, s91, v189
	v_add_u32_e32 v172, s92, v189
	ds_read_b128 v[112:115], v132
	ds_read_b128 v[120:123], v132 offset:1024
	ds_read_b128 v[128:131], v132 offset:2048
	ds_read_b128 v[132:135], v132 offset:3072
	ds_read_b128 v[144:147], v172
	ds_read_b128 v[148:151], v172 offset:1024
	ds_read_b128 v[168:171], v172 offset:2048
	ds_read_b128 v[172:175], v172 offset:3072
	s_add_u32 s58, s74, 0x40000
	s_addc_u32 s59, s75, 0
	s_mov_b32 m0, s33
	v_lshl_add_u64 v[244:245], s[58:59], 0, v[158:159]
	ds_read_b128 v[176:179], v210 offset:32768
	ds_read_b128 v[180:183], v210 offset:33792
	ds_read_b128 v[184:187], v210 offset:34816
	ds_read_b128 v[216:219], v210 offset:35840
	ds_read_b128 v[220:223], v210 offset:36864
	ds_read_b128 v[224:227], v210 offset:37888
	ds_read_b128 v[228:231], v210 offset:38912
	ds_read_b128 v[232:235], v210 offset:39936
	global_load_lds_dwordx4 v[244:245], off
	v_lshl_add_u64 v[244:245], s[58:59], 0, v[156:157]
	s_mov_b32 m0, s42
	s_nop 0
	global_load_lds_dwordx4 v[244:245], off
	s_waitcnt vmcnt(8)
	s_waitcnt lgkmcnt(0)
	s_barrier
	s_nop 0
	s_waitcnt lgkmcnt(0)
	v_mfma_f32_16x16x32_bf16 v[140:143], v[112:115], v[176:179], v[140:143]
	v_mfma_f32_16x16x32_bf16 v[136:139], v[128:131], v[176:179], v[136:139]
	v_mfma_f32_16x16x32_bf16 v[108:111], v[112:115], v[184:187], v[108:111]
	v_mfma_f32_16x16x32_bf16 v[104:107], v[128:131], v[184:187], v[104:107]
	v_mfma_f32_16x16x32_bf16 v[92:95], v[112:115], v[220:223], v[92:95]
	v_mfma_f32_16x16x32_bf16 v[88:91], v[128:131], v[220:223], v[88:91]
	v_mfma_f32_16x16x32_bf16 v[76:79], v[112:115], v[228:231], v[76:79]
	v_mfma_f32_16x16x32_bf16 v[72:75], v[128:131], v[228:231], v[72:75]
	v_mfma_f32_16x16x32_bf16 v[140:143], v[120:123], v[180:183], v[140:143]
	v_mfma_f32_16x16x32_bf16 v[136:139], v[132:135], v[180:183], v[136:139]
	v_mfma_f32_16x16x32_bf16 v[108:111], v[120:123], v[216:219], v[108:111]
	v_mfma_f32_16x16x32_bf16 v[104:107], v[132:135], v[216:219], v[104:107]
	v_mfma_f32_16x16x32_bf16 v[92:95], v[120:123], v[224:227], v[92:95]
	v_mfma_f32_16x16x32_bf16 v[88:91], v[132:135], v[224:227], v[88:91]
	v_mfma_f32_16x16x32_bf16 v[76:79], v[120:123], v[232:235], v[76:79]
	v_mfma_f32_16x16x32_bf16 v[72:75], v[132:135], v[232:235], v[72:75]
	s_nop 0
	s_nop 0
	v_mfma_f32_16x16x32_bf16 v[124:127], v[144:147], v[176:179], v[124:127]
	v_mfma_f32_16x16x32_bf16 v[116:119], v[168:171], v[176:179], v[116:119]
	v_mfma_f32_16x16x32_bf16 v[100:103], v[144:147], v[184:187], v[100:103]
	v_mfma_f32_16x16x32_bf16 v[96:99], v[168:171], v[184:187], v[96:99]
	v_mfma_f32_16x16x32_bf16 v[84:87], v[144:147], v[220:223], v[84:87]
	v_mfma_f32_16x16x32_bf16 v[80:83], v[168:171], v[220:223], v[80:83]
	v_mfma_f32_16x16x32_bf16 v[68:71], v[144:147], v[228:231], v[68:71]
	v_mfma_f32_16x16x32_bf16 v[64:67], v[168:171], v[228:231], v[64:67]
	v_mfma_f32_16x16x32_bf16 v[124:127], v[148:151], v[180:183], v[124:127]
	v_mfma_f32_16x16x32_bf16 v[116:119], v[172:175], v[180:183], v[116:119]
	v_mfma_f32_16x16x32_bf16 v[100:103], v[148:151], v[216:219], v[100:103]
	v_mfma_f32_16x16x32_bf16 v[96:99], v[172:175], v[216:219], v[96:99]
	v_mfma_f32_16x16x32_bf16 v[84:87], v[148:151], v[224:227], v[84:87]
	v_mfma_f32_16x16x32_bf16 v[80:83], v[172:175], v[224:227], v[80:83]
	v_mfma_f32_16x16x32_bf16 v[68:71], v[148:151], v[232:235], v[68:71]
	v_mfma_f32_16x16x32_bf16 v[64:67], v[172:175], v[232:235], v[64:67]
	s_nop 0
	s_barrier
	s_add_i32 s58, s91, s3
	v_lshl_add_u64 v[236:237], v[236:237], 0, s[38:39]
	s_mov_b32 m0, s58
	ds_read_b128 v[176:179], v210 offset:49152
	ds_read_b128 v[180:183], v210 offset:50176
	ds_read_b128 v[184:187], v210 offset:51200
	ds_read_b128 v[216:219], v210 offset:52224
	ds_read_b128 v[220:223], v210 offset:53248
	ds_read_b128 v[224:227], v210 offset:54272
	ds_read_b128 v[228:231], v210 offset:55296
	ds_read_b128 v[232:235], v210 offset:56320
	global_load_lds_dwordx4 v[236:237], off
	s_add_i32 m0, s58, 0x2000
	s_add_u32 s58, s72, 0x40080
	v_lshl_add_u64 v[236:237], v[238:239], 0, s[38:39]
	s_addc_u32 s59, s73, 0
	s_add_i32 s72, s92, s3
	global_load_lds_dwordx4 v[236:237], off
	v_lshl_add_u64 v[236:237], s[58:59], 0, v[152:153]
	s_mov_b32 m0, s72
	s_nop 0
	global_load_lds_dwordx4 v[236:237], off
	v_lshl_add_u64 v[236:237], s[58:59], 0, v[154:155]
	s_add_i32 m0, s72, 0x2000
	s_nop 0
	global_load_lds_dwordx4 v[236:237], off
	v_lshl_add_u64 v[236:237], v[240:241], 0, s[38:39]
	s_mov_b32 m0, s81
	s_nop 0
	global_load_lds_dwordx4 v[236:237], off
	v_lshl_add_u64 v[236:237], v[242:243], 0, s[38:39]
	s_mov_b32 m0, s82
	s_nop 0
	global_load_lds_dwordx4 v[236:237], off
	s_waitcnt vmcnt(8)
	s_waitcnt lgkmcnt(0)
	s_barrier
	s_nop 0
	s_waitcnt lgkmcnt(0)
	v_mfma_f32_16x16x32_bf16 v[60:63], v[112:115], v[176:179], v[60:63]
	v_mfma_f32_16x16x32_bf16 v[56:59], v[128:131], v[176:179], v[56:59]
	v_mfma_f32_16x16x32_bf16 v[44:47], v[112:115], v[184:187], v[44:47]
	v_mfma_f32_16x16x32_bf16 v[40:43], v[128:131], v[184:187], v[40:43]
	v_mfma_f32_16x16x32_bf16 v[28:31], v[112:115], v[220:223], v[28:31]
	v_mfma_f32_16x16x32_bf16 v[24:27], v[128:131], v[220:223], v[24:27]
	v_mfma_f32_16x16x32_bf16 v[12:15], v[112:115], v[228:231], v[12:15]
	v_mfma_f32_16x16x32_bf16 v[8:11], v[128:131], v[228:231], v[8:11]
	v_mfma_f32_16x16x32_bf16 v[60:63], v[120:123], v[180:183], v[60:63]
	v_mfma_f32_16x16x32_bf16 v[56:59], v[132:135], v[180:183], v[56:59]
	v_mfma_f32_16x16x32_bf16 v[44:47], v[120:123], v[216:219], v[44:47]
	v_mfma_f32_16x16x32_bf16 v[40:43], v[132:135], v[216:219], v[40:43]
	v_mfma_f32_16x16x32_bf16 v[28:31], v[120:123], v[224:227], v[28:31]
	v_mfma_f32_16x16x32_bf16 v[24:27], v[132:135], v[224:227], v[24:27]
	v_mfma_f32_16x16x32_bf16 v[12:15], v[120:123], v[232:235], v[12:15]
	v_mfma_f32_16x16x32_bf16 v[8:11], v[132:135], v[232:235], v[8:11]
	s_nop 0
	s_nop 0
	v_mfma_f32_16x16x32_bf16 v[52:55], v[144:147], v[176:179], v[52:55]
	v_mfma_f32_16x16x32_bf16 v[48:51], v[168:171], v[176:179], v[48:51]
	v_mfma_f32_16x16x32_bf16 v[36:39], v[144:147], v[184:187], v[36:39]
	v_mfma_f32_16x16x32_bf16 v[32:35], v[168:171], v[184:187], v[32:35]
	v_mfma_f32_16x16x32_bf16 v[20:23], v[144:147], v[220:223], v[20:23]
	v_mfma_f32_16x16x32_bf16 v[16:19], v[168:171], v[220:223], v[16:19]
	v_mfma_f32_16x16x32_bf16 v[4:7], v[144:147], v[228:231], v[4:7]
	v_mfma_f32_16x16x32_bf16 v[0:3], v[168:171], v[228:231], v[0:3]
	v_mfma_f32_16x16x32_bf16 v[52:55], v[148:151], v[180:183], v[52:55]
	v_mfma_f32_16x16x32_bf16 v[48:51], v[172:175], v[180:183], v[48:51]
	v_mfma_f32_16x16x32_bf16 v[36:39], v[148:151], v[216:219], v[36:39]
	v_mfma_f32_16x16x32_bf16 v[32:35], v[172:175], v[216:219], v[32:35]
	v_mfma_f32_16x16x32_bf16 v[20:23], v[148:151], v[224:227], v[20:23]
	v_mfma_f32_16x16x32_bf16 v[16:19], v[172:175], v[224:227], v[16:19]
	v_mfma_f32_16x16x32_bf16 v[4:7], v[148:151], v[232:235], v[4:7]
	v_mfma_f32_16x16x32_bf16 v[0:3], v[172:175], v[232:235], v[0:3]
	s_nop 0
	s_barrier
	s_add_i32 s90, s90, 2
	s_add_u32 s70, s70, 0x100
	s_addc_u32 s71, s71, 0
	s_add_u32 s69, s69, 0x100
	s_addc_u32 s89, s89, 0
	s_cmp_gt_u32 s90, 13
	s_cbranch_scc0 .LBB0_1786
	s_and_b64 vcc, exec, s[22:23]
	s_cbranch_vccz .LBB0_1789
	s_barrier

.LBB0_1882:
	ds_read_b128 v[152:155], v149
	ds_read_b128 v[156:159], v149 offset:1024
	ds_read_b128 v[160:163], v149 offset:2048
	ds_read_b128 v[164:167], v149 offset:3072
	ds_read_b128 v[168:171], v150
	ds_read_b128 v[172:175], v150 offset:1024
	ds_read_b128 v[176:179], v150 offset:2048
	ds_read_b128 v[180:183], v150 offset:3072
	s_add_u32 s48, s38, 0xfffc0080
	s_addc_u32 s49, s39, -1
	s_cmp_eq_u32 s76, 12
	s_cselect_b32 s51, s23, s49
	s_cselect_b32 s50, s72, s48
	s_cselect_b32 s49, s21, s75
	s_cselect_b32 s48, s73, s74
	v_lshl_add_u64 v[144:145], s[38:39], 0, v[136:137]
	s_add_i32 m0, s33, 0xc000
	ds_read_b128 v[184:187], v151
	ds_read_b128 v[188:191], v151 offset:1024
	ds_read_b128 v[192:195], v151 offset:2048
	ds_read_b128 v[196:199], v151 offset:3072
	ds_read_b128 v[200:203], v151 offset:4096
	ds_read_b128 v[204:207], v151 offset:5120
	ds_read_b128 v[208:211], v151 offset:6144
	ds_read_b128 v[212:215], v151 offset:7168
	global_load_lds_dwordx4 v[144:145], off
	v_lshl_add_u64 v[144:145], s[38:39], 0, v[138:139]
	s_add_i32 m0, s33, 0xe000
	s_nop 0
	global_load_lds_dwordx4 v[144:145], off
	s_waitcnt vmcnt(8)
	s_waitcnt lgkmcnt(0)
	s_barrier
	s_nop 0
	s_waitcnt lgkmcnt(0)
	v_mfma_f32_16x16x32_bf16 v[124:127], v[152:155], v[184:187], v[124:127]
	v_mfma_f32_16x16x32_bf16 v[120:123], v[160:163], v[184:187], v[120:123]
	v_mfma_f32_16x16x32_bf16 v[108:111], v[152:155], v[192:195], v[108:111]
	v_mfma_f32_16x16x32_bf16 v[104:107], v[160:163], v[192:195], v[104:107]
	v_mfma_f32_16x16x32_bf16 v[92:95], v[152:155], v[200:203], v[92:95]
	v_mfma_f32_16x16x32_bf16 v[88:91], v[160:163], v[200:203], v[88:91]
	v_mfma_f32_16x16x32_bf16 v[76:79], v[152:155], v[208:211], v[76:79]
	v_mfma_f32_16x16x32_bf16 v[72:75], v[160:163], v[208:211], v[72:75]
	v_mfma_f32_16x16x32_bf16 v[124:127], v[156:159], v[188:191], v[124:127]
	v_mfma_f32_16x16x32_bf16 v[120:123], v[164:167], v[188:191], v[120:123]
	v_mfma_f32_16x16x32_bf16 v[108:111], v[156:159], v[196:199], v[108:111]
	v_mfma_f32_16x16x32_bf16 v[104:107], v[164:167], v[196:199], v[104:107]
	v_mfma_f32_16x16x32_bf16 v[92:95], v[156:159], v[204:207], v[92:95]
	v_mfma_f32_16x16x32_bf16 v[88:91], v[164:167], v[204:207], v[88:91]
	v_mfma_f32_16x16x32_bf16 v[76:79], v[156:159], v[212:215], v[76:79]
	v_mfma_f32_16x16x32_bf16 v[72:75], v[164:167], v[212:215], v[72:75]
	s_nop 0
	s_nop 0
	v_mfma_f32_16x16x32_bf16 v[116:119], v[168:171], v[184:187], v[116:119]
	v_mfma_f32_16x16x32_bf16 v[112:115], v[176:179], v[184:187], v[112:115]
	v_mfma_f32_16x16x32_bf16 v[100:103], v[168:171], v[192:195], v[100:103]
	v_mfma_f32_16x16x32_bf16 v[96:99], v[176:179], v[192:195], v[96:99]
	v_mfma_f32_16x16x32_bf16 v[84:87], v[168:171], v[200:203], v[84:87]
	v_mfma_f32_16x16x32_bf16 v[80:83], v[176:179], v[200:203], v[80:83]
	v_mfma_f32_16x16x32_bf16 v[68:71], v[168:171], v[208:211], v[68:71]
	v_mfma_f32_16x16x32_bf16 v[64:67], v[176:179], v[208:211], v[64:67]
	v_mfma_f32_16x16x32_bf16 v[116:119], v[172:175], v[188:191], v[116:119]
	v_mfma_f32_16x16x32_bf16 v[112:115], v[180:183], v[188:191], v[112:115]
	v_mfma_f32_16x16x32_bf16 v[100:103], v[172:175], v[196:199], v[100:103]
	v_mfma_f32_16x16x32_bf16 v[96:99], v[180:183], v[196:199], v[96:99]
	v_mfma_f32_16x16x32_bf16 v[84:87], v[172:175], v[204:207], v[84:87]
	v_mfma_f32_16x16x32_bf16 v[80:83], v[180:183], v[204:207], v[80:83]
	v_mfma_f32_16x16x32_bf16 v[68:71], v[172:175], v[212:215], v[68:71]
	v_mfma_f32_16x16x32_bf16 v[64:67], v[180:183], v[212:215], v[64:67]
	s_nop 0
	s_barrier
	s_add_i32 s58, s65, s3
	v_lshl_add_u64 v[144:145], s[48:49], 0, v[132:133]
	s_mov_b32 m0, s58
	ds_read_b128 v[184:187], v151 offset:16384
	ds_read_b128 v[188:191], v151 offset:17408
	ds_read_b128 v[192:195], v151 offset:18432
	ds_read_b128 v[196:199], v151 offset:19456
	ds_read_b128 v[200:203], v151 offset:20480
	ds_read_b128 v[204:207], v151 offset:21504
	ds_read_b128 v[208:211], v151 offset:22528
	ds_read_b128 v[212:215], v151 offset:23552
	global_load_lds_dwordx4 v[144:145], off
	s_add_i32 m0, s58, 0x2000
	s_add_u32 s58, s48, 0x40000
	v_lshl_add_u64 v[216:217], s[48:49], 0, v[128:129]
	s_addc_u32 s59, s49, 0
	s_add_i32 s77, s66, s3
	global_load_lds_dwordx4 v[216:217], off
	v_lshl_add_u64 v[218:219], s[58:59], 0, v[132:133]
	s_mov_b32 m0, s77
	v_lshl_add_u64 v[220:221], s[50:51], 0, v[130:131]
	global_load_lds_dwordx4 v[218:219], off
	v_lshl_add_u64 v[218:219], s[58:59], 0, v[128:129]
	s_add_i32 m0, s77, 0x2000
	s_nop 0
	global_load_lds_dwordx4 v[218:219], off
	v_lshl_add_u64 v[218:219], s[50:51], 0, v[134:135]
	s_mov_b32 m0, s33
	s_nop 0
	global_load_lds_dwordx4 v[218:219], off
	s_mov_b32 m0, s37
	s_nop 0
	global_load_lds_dwordx4 v[220:221], off
	s_waitcnt vmcnt(8)
	s_waitcnt lgkmcnt(0)
	s_barrier
	s_nop 0
	s_waitcnt lgkmcnt(0)
	v_mfma_f32_16x16x32_bf16 v[60:63], v[152:155], v[184:187], v[60:63]
	v_mfma_f32_16x16x32_bf16 v[56:59], v[160:163], v[184:187], v[56:59]
	v_mfma_f32_16x16x32_bf16 v[44:47], v[152:155], v[192:195], v[44:47]
	v_mfma_f32_16x16x32_bf16 v[40:43], v[160:163], v[192:195], v[40:43]
	v_mfma_f32_16x16x32_bf16 v[28:31], v[152:155], v[200:203], v[28:31]
	v_mfma_f32_16x16x32_bf16 v[24:27], v[160:163], v[200:203], v[24:27]
	v_mfma_f32_16x16x32_bf16 v[12:15], v[152:155], v[208:211], v[12:15]
	v_mfma_f32_16x16x32_bf16 v[8:11], v[160:163], v[208:211], v[8:11]
	v_mfma_f32_16x16x32_bf16 v[60:63], v[156:159], v[188:191], v[60:63]
	v_mfma_f32_16x16x32_bf16 v[56:59], v[164:167], v[188:191], v[56:59]
	v_mfma_f32_16x16x32_bf16 v[44:47], v[156:159], v[196:199], v[44:47]
	v_mfma_f32_16x16x32_bf16 v[40:43], v[164:167], v[196:199], v[40:43]
	v_mfma_f32_16x16x32_bf16 v[28:31], v[156:159], v[204:207], v[28:31]
	v_mfma_f32_16x16x32_bf16 v[24:27], v[164:167], v[204:207], v[24:27]
	v_mfma_f32_16x16x32_bf16 v[12:15], v[156:159], v[212:215], v[12:15]
	v_mfma_f32_16x16x32_bf16 v[8:11], v[164:167], v[212:215], v[8:11]
	s_nop 0
	s_nop 0
	v_mfma_f32_16x16x32_bf16 v[52:55], v[168:171], v[184:187], v[52:55]
	v_mfma_f32_16x16x32_bf16 v[48:51], v[176:179], v[184:187], v[48:51]
	v_mfma_f32_16x16x32_bf16 v[36:39], v[168:171], v[192:195], v[36:39]
	v_mfma_f32_16x16x32_bf16 v[32:35], v[176:179], v[192:195], v[32:35]
	v_mfma_f32_16x16x32_bf16 v[20:23], v[168:171], v[200:203], v[20:23]
	v_mfma_f32_16x16x32_bf16 v[16:19], v[176:179], v[200:203], v[16:19]
	v_mfma_f32_16x16x32_bf16 v[4:7], v[168:171], v[208:211], v[4:7]
	v_mfma_f32_16x16x32_bf16 v[0:3], v[176:179], v[208:211], v[0:3]
	v_mfma_f32_16x16x32_bf16 v[52:55], v[172:175], v[188:191], v[52:55]
	v_mfma_f32_16x16x32_bf16 v[48:51], v[180:183], v[188:191], v[48:51]
	v_mfma_f32_16x16x32_bf16 v[36:39], v[172:175], v[196:199], v[36:39]
	v_mfma_f32_16x16x32_bf16 v[32:35], v[180:183], v[196:199], v[32:35]
	v_mfma_f32_16x16x32_bf16 v[20:23], v[172:175], v[204:207], v[20:23]
	v_mfma_f32_16x16x32_bf16 v[16:19], v[180:183], v[204:207], v[16:19]
	v_mfma_f32_16x16x32_bf16 v[4:7], v[172:175], v[212:215], v[4:7]
	v_mfma_f32_16x16x32_bf16 v[0:3], v[180:183], v[212:215], v[0:3]
	s_nop 0
	s_barrier
	s_add_i32 s58, 0, 0x18000
	s_add_i32 s59, 0, 0x1c000
	v_add_u32_e32 v164, s58, v147
	v_add_u32_e32 v180, s59, v147
	ds_read_b128 v[152:155], v164
	ds_read_b128 v[156:159], v164 offset:1024
	ds_read_b128 v[160:163], v164 offset:2048
	ds_read_b128 v[164:167], v164 offset:3072
	ds_read_b128 v[168:171], v180
	ds_read_b128 v[172:175], v180 offset:1024
	ds_read_b128 v[176:179], v180 offset:2048
	ds_read_b128 v[180:183], v180 offset:3072
	s_add_u32 s50, s50, 0x40000
	s_addc_u32 s51, s51, 0
	s_mov_b32 m0, s42
	v_lshl_add_u64 v[222:223], s[50:51], 0, v[134:135]
	ds_read_b128 v[184:187], v151 offset:32768
	ds_read_b128 v[188:191], v151 offset:33792
	ds_read_b128 v[192:195], v151 offset:34816
	ds_read_b128 v[196:199], v151 offset:35840
	ds_read_b128 v[200:203], v151 offset:36864
	ds_read_b128 v[204:207], v151 offset:37888
	ds_read_b128 v[208:211], v151 offset:38912
	ds_read_b128 v[212:215], v151 offset:39936
	global_load_lds_dwordx4 v[222:223], off
	v_lshl_add_u64 v[222:223], s[50:51], 0, v[130:131]
	s_mov_b32 m0, s43
	s_nop 0
	global_load_lds_dwordx4 v[222:223], off
	s_waitcnt vmcnt(8)
	s_waitcnt lgkmcnt(0)
	s_barrier
	s_nop 0
	s_waitcnt lgkmcnt(0)
	v_mfma_f32_16x16x32_bf16 v[124:127], v[152:155], v[184:187], v[124:127]
	v_mfma_f32_16x16x32_bf16 v[120:123], v[160:163], v[184:187], v[120:123]
	v_mfma_f32_16x16x32_bf16 v[108:111], v[152:155], v[192:195], v[108:111]
	v_mfma_f32_16x16x32_bf16 v[104:107], v[160:163], v[192:195], v[104:107]
	v_mfma_f32_16x16x32_bf16 v[92:95], v[152:155], v[200:203], v[92:95]
	v_mfma_f32_16x16x32_bf16 v[88:91], v[160:163], v[200:203], v[88:91]
	v_mfma_f32_16x16x32_bf16 v[76:79], v[152:155], v[208:211], v[76:79]
	v_mfma_f32_16x16x32_bf16 v[72:75], v[160:163], v[208:211], v[72:75]
	v_mfma_f32_16x16x32_bf16 v[124:127], v[156:159], v[188:191], v[124:127]
	v_mfma_f32_16x16x32_bf16 v[120:123], v[164:167], v[188:191], v[120:123]
	v_mfma_f32_16x16x32_bf16 v[108:111], v[156:159], v[196:199], v[108:111]
	v_mfma_f32_16x16x32_bf16 v[104:107], v[164:167], v[196:199], v[104:107]
	v_mfma_f32_16x16x32_bf16 v[92:95], v[156:159], v[204:207], v[92:95]
	v_mfma_f32_16x16x32_bf16 v[88:91], v[164:167], v[204:207], v[88:91]
	v_mfma_f32_16x16x32_bf16 v[76:79], v[156:159], v[212:215], v[76:79]
	v_mfma_f32_16x16x32_bf16 v[72:75], v[164:167], v[212:215], v[72:75]
	s_nop 0
	s_nop 0
	v_mfma_f32_16x16x32_bf16 v[116:119], v[168:171], v[184:187], v[116:119]
	v_mfma_f32_16x16x32_bf16 v[112:115], v[176:179], v[184:187], v[112:115]
	v_mfma_f32_16x16x32_bf16 v[100:103], v[168:171], v[192:195], v[100:103]
	v_mfma_f32_16x16x32_bf16 v[96:99], v[176:179], v[192:195], v[96:99]
	v_mfma_f32_16x16x32_bf16 v[84:87], v[168:171], v[200:203], v[84:87]
	v_mfma_f32_16x16x32_bf16 v[80:83], v[176:179], v[200:203], v[80:83]
	v_mfma_f32_16x16x32_bf16 v[68:71], v[168:171], v[208:211], v[68:71]
	v_mfma_f32_16x16x32_bf16 v[64:67], v[176:179], v[208:211], v[64:67]
	v_mfma_f32_16x16x32_bf16 v[116:119], v[172:175], v[188:191], v[116:119]
	v_mfma_f32_16x16x32_bf16 v[112:115], v[180:183], v[188:191], v[112:115]
	v_mfma_f32_16x16x32_bf16 v[100:103], v[172:175], v[196:199], v[100:103]
	v_mfma_f32_16x16x32_bf16 v[96:99], v[180:183], v[196:199], v[96:99]
	v_mfma_f32_16x16x32_bf16 v[84:87], v[172:175], v[204:207], v[84:87]
	v_mfma_f32_16x16x32_bf16 v[80:83], v[180:183], v[204:207], v[80:83]
	v_mfma_f32_16x16x32_bf16 v[68:71], v[172:175], v[212:215], v[68:71]
	v_mfma_f32_16x16x32_bf16 v[64:67], v[180:183], v[212:215], v[64:67]
	s_nop 0
	s_barrier
	s_add_i32 s50, s58, s3
	v_lshl_add_u64 v[144:145], v[144:145], 0, s[10:11]
	s_mov_b32 m0, s50
	ds_read_b128 v[184:187], v151 offset:49152
	ds_read_b128 v[188:191], v151 offset:50176
	ds_read_b128 v[192:195], v151 offset:51200
	ds_read_b128 v[196:199], v151 offset:52224
	ds_read_b128 v[200:203], v151 offset:53248
	ds_read_b128 v[204:207], v151 offset:54272
	ds_read_b128 v[208:211], v151 offset:55296
	ds_read_b128 v[212:215], v151 offset:56320
	global_load_lds_dwordx4 v[144:145], off
	s_add_i32 m0, s50, 0x2000
	s_add_u32 s48, s48, 0x40080
	v_lshl_add_u64 v[144:145], v[216:217], 0, s[10:11]
	s_addc_u32 s49, s49, 0
	s_add_i32 s50, s59, s3
	global_load_lds_dwordx4 v[144:145], off
	v_lshl_add_u64 v[144:145], s[48:49], 0, v[132:133]
	s_mov_b32 m0, s50
	s_nop 0
	global_load_lds_dwordx4 v[144:145], off
	v_lshl_add_u64 v[144:145], s[48:49], 0, v[128:129]
	s_add_i32 m0, s50, 0x2000
	s_nop 0
	global_load_lds_dwordx4 v[144:145], off
	v_lshl_add_u64 v[144:145], v[218:219], 0, s[10:11]
	s_mov_b32 m0, s62
	s_nop 0
	global_load_lds_dwordx4 v[144:145], off
	v_lshl_add_u64 v[144:145], v[220:221], 0, s[10:11]
	s_mov_b32 m0, s63
	s_nop 0
	global_load_lds_dwordx4 v[144:145], off
	s_waitcnt vmcnt(8)
	s_waitcnt lgkmcnt(0)
	s_barrier
	s_nop 0
	s_waitcnt lgkmcnt(0)
	v_mfma_f32_16x16x32_bf16 v[60:63], v[152:155], v[184:187], v[60:63]
	v_mfma_f32_16x16x32_bf16 v[56:59], v[160:163], v[184:187], v[56:59]
	v_mfma_f32_16x16x32_bf16 v[44:47], v[152:155], v[192:195], v[44:47]
	v_mfma_f32_16x16x32_bf16 v[40:43], v[160:163], v[192:195], v[40:43]
	v_mfma_f32_16x16x32_bf16 v[28:31], v[152:155], v[200:203], v[28:31]
	v_mfma_f32_16x16x32_bf16 v[24:27], v[160:163], v[200:203], v[24:27]
	v_mfma_f32_16x16x32_bf16 v[12:15], v[152:155], v[208:211], v[12:15]
	v_mfma_f32_16x16x32_bf16 v[8:11], v[160:163], v[208:211], v[8:11]
	v_mfma_f32_16x16x32_bf16 v[60:63], v[156:159], v[188:191], v[60:63]
	v_mfma_f32_16x16x32_bf16 v[56:59], v[164:167], v[188:191], v[56:59]
	v_mfma_f32_16x16x32_bf16 v[44:47], v[156:159], v[196:199], v[44:47]
	v_mfma_f32_16x16x32_bf16 v[40:43], v[164:167], v[196:199], v[40:43]
	v_mfma_f32_16x16x32_bf16 v[28:31], v[156:159], v[204:207], v[28:31]
	v_mfma_f32_16x16x32_bf16 v[24:27], v[164:167], v[204:207], v[24:27]
	v_mfma_f32_16x16x32_bf16 v[12:15], v[156:159], v[212:215], v[12:15]
	v_mfma_f32_16x16x32_bf16 v[8:11], v[164:167], v[212:215], v[8:11]
	s_nop 0
	s_nop 0
	v_mfma_f32_16x16x32_bf16 v[52:55], v[168:171], v[184:187], v[52:55]
	v_mfma_f32_16x16x32_bf16 v[48:51], v[176:179], v[184:187], v[48:51]
	v_mfma_f32_16x16x32_bf16 v[36:39], v[168:171], v[192:195], v[36:39]
	v_mfma_f32_16x16x32_bf16 v[32:35], v[176:179], v[192:195], v[32:35]
	v_mfma_f32_16x16x32_bf16 v[20:23], v[168:171], v[200:203], v[20:23]
	v_mfma_f32_16x16x32_bf16 v[16:19], v[176:179], v[200:203], v[16:19]
	v_mfma_f32_16x16x32_bf16 v[4:7], v[168:171], v[208:211], v[4:7]
	v_mfma_f32_16x16x32_bf16 v[0:3], v[176:179], v[208:211], v[0:3]
	v_mfma_f32_16x16x32_bf16 v[52:55], v[172:175], v[188:191], v[52:55]
	v_mfma_f32_16x16x32_bf16 v[48:51], v[180:183], v[188:191], v[48:51]
	v_mfma_f32_16x16x32_bf16 v[36:39], v[172:175], v[196:199], v[36:39]
	v_mfma_f32_16x16x32_bf16 v[32:35], v[180:183], v[196:199], v[32:35]
	v_mfma_f32_16x16x32_bf16 v[20:23], v[172:175], v[204:207], v[20:23]
	v_mfma_f32_16x16x32_bf16 v[16:19], v[180:183], v[204:207], v[16:19]
	v_mfma_f32_16x16x32_bf16 v[4:7], v[172:175], v[212:215], v[4:7]
	v_mfma_f32_16x16x32_bf16 v[0:3], v[180:183], v[212:215], v[0:3]
	s_nop 0
	s_barrier
	s_add_i32 s76, s76, 2
	s_add_u32 s38, s38, 0x100
	s_addc_u32 s39, s39, 0
	s_add_u32 s74, s74, 0x100
	s_addc_u32 s75, s75, 0
	s_cmp_gt_u32 s76, 13
	s_cbranch_scc0 .LBB0_1882
	s_and_b64 vcc, exec, s[8:9]
	s_cbranch_vccz .LBB0_1885
	s_barrier

.LBB0_1949:
	ds_read_b128 v[112:115], v194
	ds_read_b128 v[116:119], v194 offset:1024
	ds_read_b128 v[124:127], v194 offset:2048
	ds_read_b128 v[132:135], v194 offset:3072
	ds_read_b128 v[144:147], v195
	ds_read_b128 v[148:151], v195 offset:1024
	ds_read_b128 v[168:171], v195 offset:2048
	ds_read_b128 v[202:205], v195 offset:3072
	s_add_u32 s58, s54, 0xfff00080
	s_addc_u32 s59, s55, -1
	s_cmp_eq_u32 s77, 60
	s_cselect_b32 s61, s11, s59
	s_cselect_b32 s60, s16, s58
	s_cselect_b32 s59, s41, s76
	s_cselect_b32 s58, s43, s51
	v_lshl_add_u64 v[172:173], s[54:55], 0, v[160:161]
	s_add_i32 m0, s33, 0xc000
	ds_read_b128 v[206:209], v196
	ds_read_b128 v[210:213], v196 offset:1024
	ds_read_b128 v[214:217], v196 offset:2048
	ds_read_b128 v[218:221], v196 offset:3072
	ds_read_b128 v[222:225], v196 offset:4096
	ds_read_b128 v[226:229], v196 offset:5120
	ds_read_b128 v[230:233], v196 offset:6144
	ds_read_b128 v[234:237], v196 offset:7168
	global_load_lds_dwordx4 v[172:173], off
	v_lshl_add_u64 v[172:173], s[54:55], 0, v[162:163]
	s_add_i32 m0, s33, 0xe000
	s_nop 0
	global_load_lds_dwordx4 v[172:173], off
	s_waitcnt vmcnt(8)
	s_waitcnt lgkmcnt(0)
	s_barrier
	s_nop 0
	s_waitcnt lgkmcnt(0)
	v_mfma_f32_16x16x32_bf16 v[140:143], v[112:115], v[206:209], v[140:143]
	v_mfma_f32_16x16x32_bf16 v[136:139], v[124:127], v[206:209], v[136:139]
	v_mfma_f32_16x16x32_bf16 v[108:111], v[112:115], v[214:217], v[108:111]
	v_mfma_f32_16x16x32_bf16 v[104:107], v[124:127], v[214:217], v[104:107]
	v_mfma_f32_16x16x32_bf16 v[92:95], v[112:115], v[222:225], v[92:95]
	v_mfma_f32_16x16x32_bf16 v[88:91], v[124:127], v[222:225], v[88:91]
	v_mfma_f32_16x16x32_bf16 v[76:79], v[112:115], v[230:233], v[76:79]
	v_mfma_f32_16x16x32_bf16 v[72:75], v[124:127], v[230:233], v[72:75]
	v_mfma_f32_16x16x32_bf16 v[140:143], v[116:119], v[210:213], v[140:143]
	v_mfma_f32_16x16x32_bf16 v[136:139], v[132:135], v[210:213], v[136:139]
	v_mfma_f32_16x16x32_bf16 v[108:111], v[116:119], v[218:221], v[108:111]
	v_mfma_f32_16x16x32_bf16 v[104:107], v[132:135], v[218:221], v[104:107]
	v_mfma_f32_16x16x32_bf16 v[92:95], v[116:119], v[226:229], v[92:95]
	v_mfma_f32_16x16x32_bf16 v[88:91], v[132:135], v[226:229], v[88:91]
	v_mfma_f32_16x16x32_bf16 v[76:79], v[116:119], v[234:237], v[76:79]
	v_mfma_f32_16x16x32_bf16 v[72:75], v[132:135], v[234:237], v[72:75]
	s_nop 0
	s_nop 0
	v_mfma_f32_16x16x32_bf16 v[128:131], v[144:147], v[206:209], v[128:131]
	v_mfma_f32_16x16x32_bf16 v[120:123], v[168:171], v[206:209], v[120:123]
	v_mfma_f32_16x16x32_bf16 v[100:103], v[144:147], v[214:217], v[100:103]
	v_mfma_f32_16x16x32_bf16 v[96:99], v[168:171], v[214:217], v[96:99]
	v_mfma_f32_16x16x32_bf16 v[84:87], v[144:147], v[222:225], v[84:87]
	v_mfma_f32_16x16x32_bf16 v[80:83], v[168:171], v[222:225], v[80:83]
	v_mfma_f32_16x16x32_bf16 v[68:71], v[144:147], v[230:233], v[68:71]
	v_mfma_f32_16x16x32_bf16 v[64:67], v[168:171], v[230:233], v[64:67]
	v_mfma_f32_16x16x32_bf16 v[128:131], v[148:151], v[210:213], v[128:131]
	v_mfma_f32_16x16x32_bf16 v[120:123], v[202:205], v[210:213], v[120:123]
	v_mfma_f32_16x16x32_bf16 v[100:103], v[148:151], v[218:221], v[100:103]
	v_mfma_f32_16x16x32_bf16 v[96:99], v[202:205], v[218:221], v[96:99]
	v_mfma_f32_16x16x32_bf16 v[84:87], v[148:151], v[226:229], v[84:87]
	v_mfma_f32_16x16x32_bf16 v[80:83], v[202:205], v[226:229], v[80:83]
	v_mfma_f32_16x16x32_bf16 v[68:71], v[148:151], v[234:237], v[68:71]
	v_mfma_f32_16x16x32_bf16 v[64:67], v[202:205], v[234:237], v[64:67]
	s_nop 0
	s_barrier
	s_add_i32 s78, s72, s3
	v_lshl_add_u64 v[172:173], s[58:59], 0, v[152:153]
	s_mov_b32 m0, s78
	ds_read_b128 v[206:209], v196 offset:16384
	ds_read_b128 v[210:213], v196 offset:17408
	ds_read_b128 v[214:217], v196 offset:18432
	ds_read_b128 v[218:221], v196 offset:19456
	ds_read_b128 v[222:225], v196 offset:20480
	ds_read_b128 v[226:229], v196 offset:21504
	ds_read_b128 v[230:233], v196 offset:22528
	ds_read_b128 v[234:237], v196 offset:23552
	global_load_lds_dwordx4 v[172:173], off
	s_add_i32 m0, s78, 0x2000
	s_add_u32 s78, s58, 0x100000
	v_lshl_add_u64 v[238:239], s[58:59], 0, v[154:155]
	s_addc_u32 s79, s59, 0
	s_add_i32 s80, s73, s3
	global_load_lds_dwordx4 v[238:239], off
	v_lshl_add_u64 v[240:241], s[78:79], 0, v[152:153]
	s_mov_b32 m0, s80
	v_lshl_add_u64 v[242:243], s[60:61], 0, v[156:157]
	global_load_lds_dwordx4 v[240:241], off
	v_lshl_add_u64 v[240:241], s[78:79], 0, v[154:155]
	s_add_i32 m0, s80, 0x2000
	s_nop 0
	global_load_lds_dwordx4 v[240:241], off
	v_lshl_add_u64 v[240:241], s[60:61], 0, v[158:159]
	s_mov_b32 m0, s33
	s_nop 0
	global_load_lds_dwordx4 v[240:241], off
	s_mov_b32 m0, s57
	s_nop 0
	global_load_lds_dwordx4 v[242:243], off
	s_waitcnt vmcnt(8)
	s_waitcnt lgkmcnt(0)
	s_barrier
	s_nop 0
	s_waitcnt lgkmcnt(0)
	v_mfma_f32_16x16x32_bf16 v[60:63], v[112:115], v[206:209], v[60:63]
	v_mfma_f32_16x16x32_bf16 v[56:59], v[124:127], v[206:209], v[56:59]
	v_mfma_f32_16x16x32_bf16 v[44:47], v[112:115], v[214:217], v[44:47]
	v_mfma_f32_16x16x32_bf16 v[40:43], v[124:127], v[214:217], v[40:43]
	v_mfma_f32_16x16x32_bf16 v[28:31], v[112:115], v[222:225], v[28:31]
	v_mfma_f32_16x16x32_bf16 v[24:27], v[124:127], v[222:225], v[24:27]
	v_mfma_f32_16x16x32_bf16 v[12:15], v[112:115], v[230:233], v[12:15]
	v_mfma_f32_16x16x32_bf16 v[8:11], v[124:127], v[230:233], v[8:11]
	v_mfma_f32_16x16x32_bf16 v[60:63], v[116:119], v[210:213], v[60:63]
	v_mfma_f32_16x16x32_bf16 v[56:59], v[132:135], v[210:213], v[56:59]
	v_mfma_f32_16x16x32_bf16 v[44:47], v[116:119], v[218:221], v[44:47]
	v_mfma_f32_16x16x32_bf16 v[40:43], v[132:135], v[218:221], v[40:43]
	v_mfma_f32_16x16x32_bf16 v[28:31], v[116:119], v[226:229], v[28:31]
	v_mfma_f32_16x16x32_bf16 v[24:27], v[132:135], v[226:229], v[24:27]
	v_mfma_f32_16x16x32_bf16 v[12:15], v[116:119], v[234:237], v[12:15]
	v_mfma_f32_16x16x32_bf16 v[8:11], v[132:135], v[234:237], v[8:11]
	s_nop 0
	s_nop 0
	v_mfma_f32_16x16x32_bf16 v[52:55], v[144:147], v[206:209], v[52:55]
	v_mfma_f32_16x16x32_bf16 v[48:51], v[168:171], v[206:209], v[48:51]
	v_mfma_f32_16x16x32_bf16 v[36:39], v[144:147], v[214:217], v[36:39]
	v_mfma_f32_16x16x32_bf16 v[32:35], v[168:171], v[214:217], v[32:35]
	v_mfma_f32_16x16x32_bf16 v[20:23], v[144:147], v[222:225], v[20:23]
	v_mfma_f32_16x16x32_bf16 v[16:19], v[168:171], v[222:225], v[16:19]
	v_mfma_f32_16x16x32_bf16 v[4:7], v[144:147], v[230:233], v[4:7]
	v_mfma_f32_16x16x32_bf16 v[0:3], v[168:171], v[230:233], v[0:3]
	v_mfma_f32_16x16x32_bf16 v[52:55], v[148:151], v[210:213], v[52:55]
	v_mfma_f32_16x16x32_bf16 v[48:51], v[202:205], v[210:213], v[48:51]
	v_mfma_f32_16x16x32_bf16 v[36:39], v[148:151], v[218:221], v[36:39]
	v_mfma_f32_16x16x32_bf16 v[32:35], v[202:205], v[218:221], v[32:35]
	v_mfma_f32_16x16x32_bf16 v[20:23], v[148:151], v[226:229], v[20:23]
	v_mfma_f32_16x16x32_bf16 v[16:19], v[202:205], v[226:229], v[16:19]
	v_mfma_f32_16x16x32_bf16 v[4:7], v[148:151], v[234:237], v[4:7]
	v_mfma_f32_16x16x32_bf16 v[0:3], v[202:205], v[234:237], v[0:3]
	s_nop 0
	s_barrier
	s_add_i32 s78, 0, 0x18000
	s_add_i32 s79, 0, 0x1c000
	v_add_u32_e32 v132, s78, v175
	v_add_u32_e32 v202, s79, v175
	ds_read_b128 v[112:115], v132
	ds_read_b128 v[116:119], v132 offset:1024
	ds_read_b128 v[124:127], v132 offset:2048
	ds_read_b128 v[132:135], v132 offset:3072
	ds_read_b128 v[144:147], v202
	ds_read_b128 v[148:151], v202 offset:1024
	ds_read_b128 v[168:171], v202 offset:2048
	ds_read_b128 v[202:205], v202 offset:3072
	s_add_u32 s60, s60, 0x100000
	s_addc_u32 s61, s61, 0
	s_mov_b32 m0, s62
	v_lshl_add_u64 v[244:245], s[60:61], 0, v[158:159]
	ds_read_b128 v[206:209], v196 offset:32768
	ds_read_b128 v[210:213], v196 offset:33792
	ds_read_b128 v[214:217], v196 offset:34816
	ds_read_b128 v[218:221], v196 offset:35840
	ds_read_b128 v[222:225], v196 offset:36864
	ds_read_b128 v[226:229], v196 offset:37888
	ds_read_b128 v[230:233], v196 offset:38912
	ds_read_b128 v[234:237], v196 offset:39936
	global_load_lds_dwordx4 v[244:245], off
	v_lshl_add_u64 v[244:245], s[60:61], 0, v[156:157]
	s_mov_b32 m0, s63
	s_nop 0
	global_load_lds_dwordx4 v[244:245], off
	s_waitcnt vmcnt(8)
	s_waitcnt lgkmcnt(0)
	s_barrier
	s_nop 0
	s_waitcnt lgkmcnt(0)
	v_mfma_f32_16x16x32_bf16 v[140:143], v[112:115], v[206:209], v[140:143]
	v_mfma_f32_16x16x32_bf16 v[136:139], v[124:127], v[206:209], v[136:139]
	v_mfma_f32_16x16x32_bf16 v[108:111], v[112:115], v[214:217], v[108:111]
	v_mfma_f32_16x16x32_bf16 v[104:107], v[124:127], v[214:217], v[104:107]
	v_mfma_f32_16x16x32_bf16 v[92:95], v[112:115], v[222:225], v[92:95]
	v_mfma_f32_16x16x32_bf16 v[88:91], v[124:127], v[222:225], v[88:91]
	v_mfma_f32_16x16x32_bf16 v[76:79], v[112:115], v[230:233], v[76:79]
	v_mfma_f32_16x16x32_bf16 v[72:75], v[124:127], v[230:233], v[72:75]
	v_mfma_f32_16x16x32_bf16 v[140:143], v[116:119], v[210:213], v[140:143]
	v_mfma_f32_16x16x32_bf16 v[136:139], v[132:135], v[210:213], v[136:139]
	v_mfma_f32_16x16x32_bf16 v[108:111], v[116:119], v[218:221], v[108:111]
	v_mfma_f32_16x16x32_bf16 v[104:107], v[132:135], v[218:221], v[104:107]
	v_mfma_f32_16x16x32_bf16 v[92:95], v[116:119], v[226:229], v[92:95]
	v_mfma_f32_16x16x32_bf16 v[88:91], v[132:135], v[226:229], v[88:91]
	v_mfma_f32_16x16x32_bf16 v[76:79], v[116:119], v[234:237], v[76:79]
	v_mfma_f32_16x16x32_bf16 v[72:75], v[132:135], v[234:237], v[72:75]
	s_nop 0
	s_nop 0
	v_mfma_f32_16x16x32_bf16 v[128:131], v[144:147], v[206:209], v[128:131]
	v_mfma_f32_16x16x32_bf16 v[120:123], v[168:171], v[206:209], v[120:123]
	v_mfma_f32_16x16x32_bf16 v[100:103], v[144:147], v[214:217], v[100:103]
	v_mfma_f32_16x16x32_bf16 v[96:99], v[168:171], v[214:217], v[96:99]
	v_mfma_f32_16x16x32_bf16 v[84:87], v[144:147], v[222:225], v[84:87]
	v_mfma_f32_16x16x32_bf16 v[80:83], v[168:171], v[222:225], v[80:83]
	v_mfma_f32_16x16x32_bf16 v[68:71], v[144:147], v[230:233], v[68:71]
	v_mfma_f32_16x16x32_bf16 v[64:67], v[168:171], v[230:233], v[64:67]
	v_mfma_f32_16x16x32_bf16 v[128:131], v[148:151], v[210:213], v[128:131]
	v_mfma_f32_16x16x32_bf16 v[120:123], v[202:205], v[210:213], v[120:123]
	v_mfma_f32_16x16x32_bf16 v[100:103], v[148:151], v[218:221], v[100:103]
	v_mfma_f32_16x16x32_bf16 v[96:99], v[202:205], v[218:221], v[96:99]
	v_mfma_f32_16x16x32_bf16 v[84:87], v[148:151], v[226:229], v[84:87]
	v_mfma_f32_16x16x32_bf16 v[80:83], v[202:205], v[226:229], v[80:83]
	v_mfma_f32_16x16x32_bf16 v[68:71], v[148:151], v[234:237], v[68:71]
	v_mfma_f32_16x16x32_bf16 v[64:67], v[202:205], v[234:237], v[64:67]
	s_nop 0
	s_barrier
	s_add_i32 s60, s78, s3
	v_lshl_add_u64 v[172:173], v[172:173], 0, s[26:27]
	s_mov_b32 m0, s60
	ds_read_b128 v[206:209], v196 offset:49152
	ds_read_b128 v[210:213], v196 offset:50176
	ds_read_b128 v[214:217], v196 offset:51200
	ds_read_b128 v[218:221], v196 offset:52224
	ds_read_b128 v[222:225], v196 offset:53248
	ds_read_b128 v[226:229], v196 offset:54272
	ds_read_b128 v[230:233], v196 offset:55296
	ds_read_b128 v[234:237], v196 offset:56320
	global_load_lds_dwordx4 v[172:173], off
	s_add_i32 m0, s60, 0x2000
	s_add_u32 s58, s58, 0x100080
	v_lshl_add_u64 v[172:173], v[238:239], 0, s[26:27]
	s_addc_u32 s59, s59, 0
	s_add_i32 s60, s79, s3
	global_load_lds_dwordx4 v[172:173], off
	v_lshl_add_u64 v[172:173], s[58:59], 0, v[152:153]
	s_mov_b32 m0, s60
	s_nop 0
	global_load_lds_dwordx4 v[172:173], off
	v_lshl_add_u64 v[172:173], s[58:59], 0, v[154:155]
	s_add_i32 m0, s60, 0x2000
	s_nop 0
	global_load_lds_dwordx4 v[172:173], off
	v_lshl_add_u64 v[172:173], v[240:241], 0, s[26:27]
	s_mov_b32 m0, s70
	s_nop 0
	global_load_lds_dwordx4 v[172:173], off
	v_lshl_add_u64 v[172:173], v[242:243], 0, s[26:27]
	s_mov_b32 m0, s71
	s_nop 0
	global_load_lds_dwordx4 v[172:173], off
	s_waitcnt vmcnt(8)
	s_waitcnt lgkmcnt(0)
	s_barrier
	s_nop 0
	s_waitcnt lgkmcnt(0)
	v_mfma_f32_16x16x32_bf16 v[60:63], v[112:115], v[206:209], v[60:63]
	v_mfma_f32_16x16x32_bf16 v[56:59], v[124:127], v[206:209], v[56:59]
	v_mfma_f32_16x16x32_bf16 v[44:47], v[112:115], v[214:217], v[44:47]
	v_mfma_f32_16x16x32_bf16 v[40:43], v[124:127], v[214:217], v[40:43]
	v_mfma_f32_16x16x32_bf16 v[28:31], v[112:115], v[222:225], v[28:31]
	v_mfma_f32_16x16x32_bf16 v[24:27], v[124:127], v[222:225], v[24:27]
	v_mfma_f32_16x16x32_bf16 v[12:15], v[112:115], v[230:233], v[12:15]
	v_mfma_f32_16x16x32_bf16 v[8:11], v[124:127], v[230:233], v[8:11]
	v_mfma_f32_16x16x32_bf16 v[60:63], v[116:119], v[210:213], v[60:63]
	v_mfma_f32_16x16x32_bf16 v[56:59], v[132:135], v[210:213], v[56:59]
	v_mfma_f32_16x16x32_bf16 v[44:47], v[116:119], v[218:221], v[44:47]
	v_mfma_f32_16x16x32_bf16 v[40:43], v[132:135], v[218:221], v[40:43]
	v_mfma_f32_16x16x32_bf16 v[28:31], v[116:119], v[226:229], v[28:31]
	v_mfma_f32_16x16x32_bf16 v[24:27], v[132:135], v[226:229], v[24:27]
	v_mfma_f32_16x16x32_bf16 v[12:15], v[116:119], v[234:237], v[12:15]
	v_mfma_f32_16x16x32_bf16 v[8:11], v[132:135], v[234:237], v[8:11]
	s_nop 0
	s_nop 0
	v_mfma_f32_16x16x32_bf16 v[52:55], v[144:147], v[206:209], v[52:55]
	v_mfma_f32_16x16x32_bf16 v[48:51], v[168:171], v[206:209], v[48:51]
	v_mfma_f32_16x16x32_bf16 v[36:39], v[144:147], v[214:217], v[36:39]
	v_mfma_f32_16x16x32_bf16 v[32:35], v[168:171], v[214:217], v[32:35]
	v_mfma_f32_16x16x32_bf16 v[20:23], v[144:147], v[222:225], v[20:23]
	v_mfma_f32_16x16x32_bf16 v[16:19], v[168:171], v[222:225], v[16:19]
	v_mfma_f32_16x16x32_bf16 v[4:7], v[144:147], v[230:233], v[4:7]
	v_mfma_f32_16x16x32_bf16 v[0:3], v[168:171], v[230:233], v[0:3]
	v_mfma_f32_16x16x32_bf16 v[52:55], v[148:151], v[210:213], v[52:55]
	v_mfma_f32_16x16x32_bf16 v[48:51], v[202:205], v[210:213], v[48:51]
	v_mfma_f32_16x16x32_bf16 v[36:39], v[148:151], v[218:221], v[36:39]
	v_mfma_f32_16x16x32_bf16 v[32:35], v[202:205], v[218:221], v[32:35]
	v_mfma_f32_16x16x32_bf16 v[20:23], v[148:151], v[226:229], v[20:23]
	v_mfma_f32_16x16x32_bf16 v[16:19], v[202:205], v[226:229], v[16:19]
	v_mfma_f32_16x16x32_bf16 v[4:7], v[148:151], v[234:237], v[4:7]
	v_mfma_f32_16x16x32_bf16 v[0:3], v[202:205], v[234:237], v[0:3]
	s_nop 0
	s_barrier
	s_add_i32 s77, s77, 2
	s_add_u32 s54, s54, 0x100
	s_addc_u32 s55, s55, 0
	s_add_u32 s51, s51, 0x100
	s_addc_u32 s76, s76, 0
	s_cmp_gt_u32 s77, 61
	s_cbranch_scc0 .LBB0_1949
	s_and_b64 vcc, exec, s[22:23]
	s_cbranch_vccz .LBB0_1952
	s_barrier
